# rsqrt: dropped unreachable denormal-range rescale around v_rsq_f32 (argument >= eps)
# speedup vs baseline: 1.0090x; 1.0037x over previous
; DI unsigned pk2(float lo, float hi) { const f32x2 v = {lo, hi}; return __builtin_bit_cast(unsigned, __builtin_convertvector(v, bf16v2_t)); }
; DI float wave_sum(float v) { for (int o = 32; o; o >>= 1) v += __shfl_xor(v, o); return v; }
; DI void rmsnorm_phase(const float* x, const float* g, bf16_t* h, int ntok, const int tid) {
;     ...
;     for (int t0 = (blockIdx.x * 8 + wv) * 2; t0 < ntok; t0 += gridDim.x * 16) {
;         f32x4 v[2][4];
; #pragma unroll
;         for (int u = 0; u < 2; ++u)
; #pragma unroll
;             for (int c = 0; c < 4; ++c) v[u][c] = ((const f32x4*)(x + (size_t)(t0 + u) * 1024))[lane + 64 * c];
; #pragma unroll
;         for (int u = 0; u < 2; ++u) { float ss = 0.f;
; #pragma unroll
;             for (int c = 0; c < 4; ++c) ss += v[u][c][0] * v[u][c][0] + v[u][c][1] * v[u][c][1] + v[u][c][2] * v[u][c][2] + v[u][c][3] * v[u][c][3];
;             ss = wave_sum(ss);
;             const float rs = rsqrtf(ss * (1.f / 1024.f) + NEPS);
; #pragma unroll
;             for (int c = 0; c < 4; ++c) { u32x2 o; o[0] = pk2(v[u][c][0] * rs * gg[c][0], v[u][c][1] * rs * gg[c][1]); o[1] = pk2(v[u][c][2] * rs * gg[c][2], v[u][c][3] * rs * gg[c][3]);
;                 *(u32x2*)(h + (size_t)(t0 + u) * 1024 + (lane + 64 * c) * 4) = o; } }
;     }
.LBB0_127:
	v_ashrrev_i32_e32 v51, 31, v50
	v_lshlrev_b64 v[18:19], 12, v[50:51]
	v_add_u32_e32 v56, 1, v50
	v_lshl_add_u64 v[18:19], v[52:53], 0, v[18:19]
	v_ashrrev_i32_e32 v57, 31, v56
	global_load_dwordx4 v[46:49], v[18:19], off
	global_load_dwordx4 v[42:45], v[18:19], off offset:1024
	global_load_dwordx4 v[38:41], v[18:19], off offset:2048
	global_load_dwordx4 v[34:37], v[18:19], off offset:3072
	v_lshlrev_b64 v[18:19], 12, v[56:57]
	v_lshl_add_u64 v[18:19], v[52:53], 0, v[18:19]
	global_load_dwordx4 v[30:33], v[18:19], off
	global_load_dwordx4 v[26:29], v[18:19], off offset:1024
	global_load_dwordx4 v[22:25], v[18:19], off offset:2048
	s_nop 0
	global_load_dwordx4 v[18:21], v[18:19], off offset:3072
	s_waitcnt vmcnt(0)
	v_mov_b32_e32 v66, v47
	v_mov_b32_e32 v67, v43
	v_mov_b32_e32 v58, v46
	v_mov_b32_e32 v72, v31
	v_mov_b32_e32 v73, v27
	v_mov_b32_e32 v59, v42
	v_pk_mul_f32 v[66:67], v[66:67], v[66:67]
	v_mov_b32_e32 v70, v30
	v_mov_b32_e32 v71, v26
	v_pk_mul_f32 v[72:73], v[72:73], v[72:73]
	v_pk_fma_f32 v[58:59], v[58:59], v[58:59], v[66:67]
	v_mov_b32_e32 v66, v48
	v_mov_b32_e32 v67, v44
	v_pk_fma_f32 v[70:71], v[70:71], v[70:71], v[72:73]
	v_mov_b32_e32 v72, v32
	v_mov_b32_e32 v73, v28
	v_pk_fma_f32 v[58:59], v[66:67], v[66:67], v[58:59]
	v_mov_b32_e32 v66, v49
	v_mov_b32_e32 v67, v45
	v_mov_b32_e32 v68, v39
	v_mov_b32_e32 v69, v35
	v_pk_fma_f32 v[70:71], v[72:73], v[72:73], v[70:71]
	v_mov_b32_e32 v72, v33
	v_mov_b32_e32 v73, v29
	v_mov_b32_e32 v74, v23
	v_mov_b32_e32 v75, v19
	v_pk_fma_f32 v[66:67], v[66:67], v[66:67], v[58:59]
	v_mov_b32_e32 v58, v38
	v_mov_b32_e32 v59, v34
	v_pk_mul_f32 v[68:69], v[68:69], v[68:69]
	v_pk_fma_f32 v[70:71], v[72:73], v[72:73], v[70:71]
	v_mov_b32_e32 v72, v22
	v_mov_b32_e32 v73, v18
	v_pk_mul_f32 v[74:75], v[74:75], v[74:75]
	v_pk_fma_f32 v[58:59], v[58:59], v[58:59], v[68:69]
	v_mov_b32_e32 v68, v40
	v_mov_b32_e32 v69, v36
	v_pk_fma_f32 v[72:73], v[72:73], v[72:73], v[74:75]
	v_mov_b32_e32 v74, v24
	v_mov_b32_e32 v75, v20
	v_pk_fma_f32 v[58:59], v[68:69], v[68:69], v[58:59]
	v_mov_b32_e32 v68, v41
	v_mov_b32_e32 v69, v37
	v_pk_fma_f32 v[72:73], v[74:75], v[74:75], v[72:73]
	v_mov_b32_e32 v74, v25
	v_mov_b32_e32 v75, v21
	v_pk_fma_f32 v[68:69], v[68:69], v[68:69], v[58:59]
	v_pk_fma_f32 v[72:73], v[74:75], v[74:75], v[72:73]
	v_mov_b32_e32 v74, v70
	v_mov_b32_e32 v75, v66
	v_mov_b32_e32 v66, v71
	v_pk_add_f32 v[66:67], v[74:75], v[66:67]
	v_mov_b32_e32 v70, v72
	v_mov_b32_e32 v71, v68
	v_pk_add_f32 v[66:67], v[66:67], v[70:71]
	v_mov_b32_e32 v68, v73
	v_pk_add_f32 v[66:67], v[66:67], v[68:69]
	v_mov_b32_e32 v69, v67
	v_mov_b32_e32 v68, v66
	s_nop 0
	v_permlane32_swap_b32_e32 v69, v67
	v_permlane32_swap_b32_e32 v68, v66
	v_lshlrev_b64 v[58:59], 11, v[50:51]
	v_lshl_add_u64 v[58:59], v[54:55], 0, v[58:59]
	v_add_u32_e32 v50, s17, v50
	s_waitcnt lgkmcnt(0)
	v_pk_add_f32 v[66:67], v[66:67], v[68:69]
	v_mov_b32_e32 v69, v67
	v_mov_b32_e32 v68, v66
	s_nop 0
	v_permlane16_swap_b32_e32 v69, v67
	v_permlane16_swap_b32_e32 v68, v66
	s_waitcnt lgkmcnt(0)
	v_pk_add_f32 v[66:67], v[66:67], v[68:69]
	s_nop 1
	v_add_f32_dpp v67, v67, v67 row_ror:8 row_mask:0xf bank_mask:0xf
	v_add_f32_dpp v66, v66, v66 row_ror:8 row_mask:0xf bank_mask:0xf
	s_waitcnt lgkmcnt(0)
	s_nop 1
	v_add_f32_dpp v67, v67, v67 row_ror:4 row_mask:0xf bank_mask:0xf
	v_add_f32_dpp v66, v66, v66 row_ror:4 row_mask:0xf bank_mask:0xf
	s_waitcnt lgkmcnt(0)
	s_nop 1
	v_add_f32_dpp v67, v67, v67 quad_perm:[2,3,0,1] row_mask:0xf bank_mask:0xf
	v_add_f32_dpp v66, v66, v66 quad_perm:[2,3,0,1] row_mask:0xf bank_mask:0xf
	s_waitcnt lgkmcnt(0)
	s_nop 1
	v_add_f32_dpp v67, v67, v67 quad_perm:[1,0,3,2] row_mask:0xf bank_mask:0xf
	v_add_f32_dpp v66, v66, v66 quad_perm:[1,0,3,2] row_mask:0xf bank_mask:0xf
	s_waitcnt lgkmcnt(0)
	s_nop 0
	v_pk_fma_f32 v[66:67], v[66:67], s[12:13], v[190:191] op_sel_hi:[1,0,0]
	s_nop 0
	v_cmp_gt_f32_e64 s[0:1], s77, v67
	v_cmp_gt_f32_e32 vcc, s77, v66
	s_nop 0
	v_rsq_f32_e32 v0, v67
	s_nop 0
	v_pk_mul_f32 v[46:47], v[46:47], v[0:1] op_sel_hi:[1,0]
	v_pk_mul_f32 v[48:49], v[48:49], v[0:1] op_sel_hi:[1,0]
	v_pk_mul_f32 v[42:43], v[42:43], v[0:1] op_sel_hi:[1,0]
	v_pk_mul_f32 v[44:45], v[44:45], v[0:1] op_sel_hi:[1,0]
	v_pk_mul_f32 v[38:39], v[38:39], v[0:1] op_sel_hi:[1,0]
	v_pk_mul_f32 v[40:41], v[40:41], v[0:1] op_sel_hi:[1,0]
	v_pk_mul_f32 v[34:35], v[34:35], v[0:1] op_sel_hi:[1,0]
	v_pk_mul_f32 v[36:37], v[36:37], v[0:1] op_sel_hi:[1,0]
	v_rsq_f32_e32 v0, v66
	v_pk_mul_f32 v[34:35], v[2:3], v[34:35]
	v_pk_mul_f32 v[36:37], v[4:5], v[36:37]
	v_cvt_pk_bf16_f32 v34, v34, v35
	v_cvt_pk_bf16_f32 v35, v36, v37
	global_store_dwordx2 v[58:59], v[34:35], off offset:1536
	v_pk_mul_f32 v[30:31], v[30:31], v[0:1] op_sel_hi:[1,0]
	v_pk_mul_f32 v[32:33], v[32:33], v[0:1] op_sel_hi:[1,0]
	v_pk_mul_f32 v[26:27], v[26:27], v[0:1] op_sel_hi:[1,0]
	v_pk_mul_f32 v[28:29], v[28:29], v[0:1] op_sel_hi:[1,0]
	v_pk_mul_f32 v[22:23], v[22:23], v[0:1] op_sel_hi:[1,0]
	v_pk_mul_f32 v[24:25], v[24:25], v[0:1] op_sel_hi:[1,0]
	v_pk_mul_f32 v[18:19], v[18:19], v[0:1] op_sel_hi:[1,0]
	v_pk_mul_f32 v[20:21], v[20:21], v[0:1] op_sel_hi:[1,0]
	v_pk_mul_f32 v[46:47], v[14:15], v[46:47]
	v_pk_mul_f32 v[48:49], v[16:17], v[48:49]
	v_pk_mul_f32 v[42:43], v[10:11], v[42:43]
	v_pk_mul_f32 v[44:45], v[12:13], v[44:45]
	v_pk_mul_f32 v[38:39], v[6:7], v[38:39]
	v_pk_mul_f32 v[40:41], v[8:9], v[40:41]
	v_lshlrev_b64 v[34:35], 11, v[56:57]
	v_pk_mul_f32 v[30:31], v[14:15], v[30:31]
	v_pk_mul_f32 v[32:33], v[16:17], v[32:33]
	v_pk_mul_f32 v[26:27], v[10:11], v[26:27]
	v_pk_mul_f32 v[28:29], v[12:13], v[28:29]
	v_pk_mul_f32 v[22:23], v[6:7], v[22:23]
	v_pk_mul_f32 v[24:25], v[8:9], v[24:25]
	v_pk_mul_f32 v[18:19], v[2:3], v[18:19]
	v_pk_mul_f32 v[20:21], v[4:5], v[20:21]
	v_cmp_lt_i32_e32 vcc, s16, v50
	v_cvt_pk_bf16_f32 v46, v46, v47
	v_cvt_pk_bf16_f32 v47, v48, v49
	v_cvt_pk_bf16_f32 v42, v42, v43
	v_cvt_pk_bf16_f32 v43, v44, v45
	v_cvt_pk_bf16_f32 v38, v38, v39
	v_cvt_pk_bf16_f32 v39, v40, v41
	v_cvt_pk_bf16_f32 v30, v30, v31
	v_cvt_pk_bf16_f32 v31, v32, v33
	v_lshl_add_u64 v[32:33], v[54:55], 0, v[34:35]
	v_cvt_pk_bf16_f32 v26, v26, v27
	v_cvt_pk_bf16_f32 v27, v28, v29
	v_cvt_pk_bf16_f32 v22, v22, v23
	v_cvt_pk_bf16_f32 v23, v24, v25
	v_cvt_pk_bf16_f32 v18, v18, v19
	v_cvt_pk_bf16_f32 v19, v20, v21
	s_or_b64 s[34:35], vcc, s[34:35]
	global_store_dwordx2 v[58:59], v[46:47], off
	global_store_dwordx2 v[58:59], v[42:43], off offset:512
	global_store_dwordx2 v[58:59], v[38:39], off offset:1024
	global_store_dwordx2 v[32:33], v[30:31], off
	global_store_dwordx2 v[32:33], v[26:27], off offset:512
	global_store_dwordx2 v[32:33], v[22:23], off offset:1024
	global_store_dwordx2 v[32:33], v[18:19], off offset:1536
	s_andn2_b64 exec, exec, s[34:35]
	s_cbranch_execnz .LBB0_127

.LBB0_207:
	v_add_u32_e32 v0, 0xfc0, v8
	v_mov_b64_e32 v[10:11], s[30:31]
	v_mad_u64_u32 v[10:11], s[0:1], v0, s3, v[10:11]
	s_lshl_b32 s4, s34, 1
	v_lshlrev_b64 v[38:39], 12, v[0:1]
	v_lshl_add_u64 v[10:11], v[10:11], 0, s[4:5]
	v_lshlrev_b32_e32 v0, 1, v6
	v_lshl_add_u64 v[6:7], v[10:11], 0, v[0:1]
	v_or_b32_e32 v10, 0x1000, v38
	v_mov_b32_e32 v11, v39
	v_lshl_add_u64 v[8:9], v[4:5], 0, v[38:39]
	v_lshl_add_u64 v[10:11], v[4:5], 0, v[10:11]
	global_load_dword v37, v[8:9], off
	global_load_dword v43, v[10:11], off
	global_load_dword v42, v[6:7], off offset:3072
	s_movk_i32 s0, 0x3000
	v_add_co_u32_e32 v10, vcc, s0, v6
	s_movk_i32 s0, 0x5000
	s_nop 0
	v_addc_co_u32_e32 v11, vcc, 0, v7, vcc
	global_load_dword v45, v[10:11], off offset:896
	v_or_b32_e32 v10, 0x2000, v38
	v_mov_b32_e32 v11, v39
	v_lshl_add_u64 v[10:11], v[4:5], 0, v[10:11]
	global_load_dword v35, v[10:11], off
	v_add_co_u32_e32 v10, vcc, s0, v6
	s_mov_b32 s4, 0x8000
	s_nop 0
	v_addc_co_u32_e32 v11, vcc, 0, v7, vcc
	global_load_dword v36, v[10:11], off offset:2816
	v_or_b32_e32 v10, 0x3000, v38
	v_mov_b32_e32 v11, v39
	v_lshl_add_u64 v[10:11], v[4:5], 0, v[10:11]
	global_load_dword v33, v[10:11], off
	v_add_co_u32_e32 v10, vcc, s4, v6
	s_mov_b32 s12, 0xa000
	s_nop 0
	v_addc_co_u32_e32 v11, vcc, 0, v7, vcc
	global_load_dword v34, v[10:11], off offset:640
	v_or_b32_e32 v10, 0x4000, v38
	v_mov_b32_e32 v11, v39
	v_lshl_add_u64 v[10:11], v[4:5], 0, v[10:11]
	global_load_dword v31, v[10:11], off
	v_add_co_u32_e32 v10, vcc, s12, v6
	s_mov_b32 s0, 0xd000
	s_nop 0
	v_addc_co_u32_e32 v11, vcc, 0, v7, vcc
	global_load_dword v32, v[10:11], off offset:2560
	v_or_b32_e32 v10, 0x5000, v38
	v_mov_b32_e32 v11, v39
	v_lshl_add_u64 v[10:11], v[4:5], 0, v[10:11]
	global_load_dword v29, v[10:11], off
	v_add_co_u32_e32 v10, vcc, s0, v6
	s_mov_b32 s0, 0xf000
	s_nop 0
	v_addc_co_u32_e32 v11, vcc, 0, v7, vcc
	global_load_dword v30, v[10:11], off offset:384
	v_or_b32_e32 v10, 0x6000, v38
	v_mov_b32_e32 v11, v39
	v_lshl_add_u64 v[10:11], v[4:5], 0, v[10:11]
	global_load_dword v27, v[10:11], off
	v_add_co_u32_e32 v10, vcc, s0, v6
	s_mov_b32 s0, 0x12000
	s_nop 0
	v_addc_co_u32_e32 v11, vcc, 0, v7, vcc
	global_load_dword v28, v[10:11], off offset:2304
	v_or_b32_e32 v10, 0x7000, v38
	v_mov_b32_e32 v11, v39
	v_lshl_add_u64 v[10:11], v[4:5], 0, v[10:11]
	global_load_dword v25, v[10:11], off
	v_add_co_u32_e32 v10, vcc, s0, v6
	s_mov_b32 s0, 0x14000
	s_nop 0
	v_addc_co_u32_e32 v11, vcc, 0, v7, vcc
	global_load_dword v26, v[10:11], off offset:128
	v_or_b32_e32 v10, 0x8000, v38
	v_mov_b32_e32 v11, v39
	v_lshl_add_u64 v[10:11], v[4:5], 0, v[10:11]
	global_load_dword v23, v[10:11], off
	v_add_co_u32_e32 v10, vcc, s0, v6
	s_mov_b32 s0, 0x16000
	s_nop 0
	v_addc_co_u32_e32 v11, vcc, 0, v7, vcc
	global_load_dword v24, v[10:11], off offset:2048
	v_or_b32_e32 v10, 0x9000, v38
	v_mov_b32_e32 v11, v39
	v_lshl_add_u64 v[10:11], v[4:5], 0, v[10:11]
	global_load_dword v21, v[10:11], off
	v_add_co_u32_e32 v10, vcc, s0, v6
	s_mov_b32 s0, 0x19000
	s_nop 0
	v_addc_co_u32_e32 v11, vcc, 0, v7, vcc
	global_load_dword v22, v[10:11], off offset:3968
	v_or_b32_e32 v10, 0xa000, v38
	v_mov_b32_e32 v11, v39
	v_lshl_add_u64 v[10:11], v[4:5], 0, v[10:11]
	global_load_dword v19, v[10:11], off
	v_add_co_u32_e32 v10, vcc, s0, v6
	s_mov_b32 s0, 0x1b000
	s_nop 0
	v_addc_co_u32_e32 v11, vcc, 0, v7, vcc
	global_load_dword v20, v[10:11], off offset:1792
	v_or_b32_e32 v10, 0xb000, v38
	v_mov_b32_e32 v11, v39
	v_lshl_add_u64 v[10:11], v[4:5], 0, v[10:11]
	global_load_dword v17, v[10:11], off
	v_add_co_u32_e32 v10, vcc, s0, v6
	s_mov_b32 s0, 0x1e000
	s_nop 0
	v_addc_co_u32_e32 v11, vcc, 0, v7, vcc
	global_load_dword v18, v[10:11], off offset:3712
	v_or_b32_e32 v10, 0xc000, v38
	v_mov_b32_e32 v11, v39
	v_lshl_add_u64 v[10:11], v[4:5], 0, v[10:11]
	global_load_dword v15, v[10:11], off
	v_add_co_u32_e32 v10, vcc, s0, v6
	s_mov_b32 s0, 0x20000
	s_nop 0
	v_addc_co_u32_e32 v11, vcc, 0, v7, vcc
	global_load_dword v16, v[10:11], off offset:1536
	v_or_b32_e32 v10, 0xd000, v38
	v_mov_b32_e32 v11, v39
	v_lshl_add_u64 v[10:11], v[4:5], 0, v[10:11]
	global_load_dword v13, v[10:11], off
	v_add_co_u32_e32 v10, vcc, s0, v6
	s_mov_b32 s0, 0x23000
	s_nop 0
	v_addc_co_u32_e32 v11, vcc, 0, v7, vcc
	global_load_dword v14, v[10:11], off offset:3456
	v_or_b32_e32 v10, 0xe000, v38
	v_mov_b32_e32 v11, v39
	v_add_co_u32_e32 v40, vcc, s0, v6
	v_or_b32_e32 v38, 0xf000, v38
	v_lshl_add_u64 v[10:11], v[4:5], 0, v[10:11]
	v_addc_co_u32_e32 v41, vcc, 0, v7, vcc
	v_lshl_add_u64 v[4:5], v[4:5], 0, v[38:39]
	s_mov_b32 s0, 0x25000
	global_load_dword v0, v[4:5], off
	v_add_co_u32_e32 v4, vcc, s0, v6
	global_load_dword v11, v[10:11], off
	s_nop 0
	v_addc_co_u32_e32 v5, vcc, 0, v7, vcc
	global_load_dword v10, v[4:5], off offset:3200
	s_waitcnt vmcnt(28)
	v_lshlrev_b32_e32 v4, 16, v42
	v_lshlrev_b32_e32 v6, 16, v37
	v_and_b32_e32 v7, 0xffff0000, v37
	v_mul_f32_e32 v37, 0xbfb8aa3b, v4
	v_exp_f32_e32 v37, v37
	v_and_b32_e32 v5, 0xffff0000, v42
	global_load_dword v12, v[40:41], off offset:1280
	v_lshlrev_b32_e32 v42, 16, v43
	v_add_f32_e32 v37, 1.0, v37
	v_rcp_f32_e32 v40, v37
	v_mul_f32_e32 v37, 0xbfb8aa3b, v5
	v_exp_f32_e32 v37, v37
	v_and_b32_e32 v43, 0xffff0000, v43
	v_pk_mul_f32 v[38:39], v[6:7], v[6:7]
	s_waitcnt vmcnt(28)
	v_lshlrev_b32_e32 v44, 16, v45
	v_add_f32_e32 v37, 1.0, v37
	v_rcp_f32_e32 v41, v37
	v_mov_b32_e32 v47, v38
	v_and_b32_e32 v45, 0xffff0000, v45
	v_pk_mul_f32 v[40:41], v[40:41], v[4:5]
	v_pk_mul_f32 v[4:5], v[42:43], v[42:43]
	s_nop 0
	v_mov_b32_e32 v46, v4
	v_mov_b32_e32 v38, v5
	v_pk_add_f32 v[4:5], v[46:47], v[38:39]
	v_mov_b32_e32 v39, v5
	v_mov_b32_e32 v38, v4
	s_nop 0
	v_permlane32_swap_b32_e32 v39, v5
	v_permlane32_swap_b32_e32 v38, v4
	s_waitcnt lgkmcnt(0)
	v_pk_add_f32 v[4:5], v[4:5], v[38:39]
	v_mov_b32_e32 v39, v5
	v_mov_b32_e32 v38, v4
	s_nop 0
	v_permlane16_swap_b32_e32 v39, v5
	v_permlane16_swap_b32_e32 v38, v4
	s_waitcnt lgkmcnt(0)
	v_pk_add_f32 v[4:5], v[4:5], v[38:39]
	s_nop 1
	v_add_f32_dpp v5, v5, v5 row_ror:8 row_mask:0xf bank_mask:0xf
	v_add_f32_dpp v4, v4, v4 row_ror:8 row_mask:0xf bank_mask:0xf
	s_waitcnt lgkmcnt(0)
	s_nop 1
	v_add_f32_dpp v5, v5, v5 row_ror:4 row_mask:0xf bank_mask:0xf
	v_add_f32_dpp v4, v4, v4 row_ror:4 row_mask:0xf bank_mask:0xf
	s_waitcnt lgkmcnt(0)
	s_nop 1
	v_add_f32_dpp v5, v5, v5 quad_perm:[2,3,0,1] row_mask:0xf bank_mask:0xf
	v_add_f32_dpp v4, v4, v4 quad_perm:[2,3,0,1] row_mask:0xf bank_mask:0xf
	s_waitcnt lgkmcnt(0)
	s_nop 1
	v_add_f32_dpp v39, v5, v5 quad_perm:[1,0,3,2] row_mask:0xf bank_mask:0xf
	v_add_f32_dpp v38, v4, v4 quad_perm:[1,0,3,2] row_mask:0xf bank_mask:0xf
	s_waitcnt lgkmcnt(0)
	v_mov_b64_e32 v[4:5], s[72:73]
	v_pk_fma_f32 v[38:39], v[38:39], s[96:97], v[4:5] op_sel_hi:[1,0,0]
	s_nop 0
	v_cmp_gt_f32_e64 s[0:1], s77, v39
	v_cmp_gt_f32_e32 vcc, s77, v38
	s_nop 0
	v_rsq_f32_e32 v37, v39
	s_nop 0
	v_mov_b32_e32 v46, v37
	v_pk_mul_f32 v[6:7], v[46:47], v[6:7] op_sel_hi:[0,1]
	v_pk_mul_f32 v[6:7], v[2:3], v[6:7]
	v_mul_f32_e32 v37, 0xbfb8aa3b, v45
	v_pk_mul_f32 v[6:7], v[40:41], v[6:7]
	v_exp_f32_e32 v37, v37
	v_cvt_pk_bf16_f32 v6, v6, v7
	global_store_dword v[8:9], v6, off
	v_rsq_f32_e32 v6, v38
	v_add_f32_e32 v37, 1.0, v37
	v_rcp_f32_e32 v39, v37
	s_waitcnt vmcnt(27)
	v_lshlrev_b32_e32 v40, 16, v36
	v_mul_f32_e32 v7, 0xbfb8aa3b, v44
	v_exp_f32_e32 v7, v7
	v_and_b32_e32 v41, 0xffff0000, v36
	s_movk_i32 s0, 0x2000
	v_add_f32_e32 v7, 1.0, v7
	v_rcp_f32_e32 v38, v7
	v_pk_mul_f32 v[6:7], v[6:7], v[42:43] op_sel_hi:[0,1]
	v_pk_mul_f32 v[6:7], v[2:3], v[6:7]
	v_pk_mul_f32 v[38:39], v[38:39], v[44:45]
	s_nop 0
	v_pk_mul_f32 v[6:7], v[38:39], v[6:7]
	v_lshlrev_b32_e32 v38, 16, v35
	v_and_b32_e32 v39, 0xffff0000, v35
	v_mul_f32_e32 v35, 0xbfb8aa3b, v40
	v_exp_f32_e32 v35, v35
	v_cvt_pk_bf16_f32 v37, v6, v7
	v_add_co_u32_e32 v6, vcc, s0, v8
	v_add_f32_e32 v35, 1.0, v35
	v_rcp_f32_e32 v42, v35
	v_mul_f32_e32 v35, 0xbfb8aa3b, v41
	v_exp_f32_e32 v35, v35
	v_addc_co_u32_e32 v7, vcc, 0, v9, vcc
	global_store_dword v[6:7], v37, off offset:-4096
	v_add_f32_e32 v35, 1.0, v35
	v_rcp_f32_e32 v43, v35
	v_pk_mul_f32 v[36:37], v[38:39], v[38:39]
	s_waitcnt vmcnt(26)
	v_lshlrev_b32_e32 v44, 16, v34
	v_and_b32_e32 v45, 0xffff0000, v34
	v_pk_mul_f32 v[40:41], v[42:43], v[40:41]
	v_lshlrev_b32_e32 v42, 16, v33
	v_and_b32_e32 v43, 0xffff0000, v33
	v_pk_mul_f32 v[34:35], v[42:43], v[42:43]
	v_mov_b32_e32 v47, v36
	v_mov_b32_e32 v46, v34
	v_mov_b32_e32 v36, v35
	v_pk_add_f32 v[34:35], v[46:47], v[36:37]
	v_mov_b32_e32 v37, v35
	v_mov_b32_e32 v36, v34
	s_nop 0
	v_permlane32_swap_b32_e32 v37, v35
	v_permlane32_swap_b32_e32 v36, v34
	s_waitcnt lgkmcnt(0)
	v_pk_add_f32 v[34:35], v[34:35], v[36:37]
	v_mov_b32_e32 v37, v35
	v_mov_b32_e32 v36, v34
	s_nop 0
	v_permlane16_swap_b32_e32 v37, v35
	v_permlane16_swap_b32_e32 v36, v34
	s_waitcnt lgkmcnt(0)
	v_pk_add_f32 v[34:35], v[34:35], v[36:37]
	s_nop 1
	v_add_f32_dpp v35, v35, v35 row_ror:8 row_mask:0xf bank_mask:0xf
	v_add_f32_dpp v34, v34, v34 row_ror:8 row_mask:0xf bank_mask:0xf
	s_waitcnt lgkmcnt(0)
	s_nop 1
	v_add_f32_dpp v35, v35, v35 row_ror:4 row_mask:0xf bank_mask:0xf
	v_add_f32_dpp v34, v34, v34 row_ror:4 row_mask:0xf bank_mask:0xf
	s_waitcnt lgkmcnt(0)
	s_nop 1
	v_add_f32_dpp v35, v35, v35 quad_perm:[2,3,0,1] row_mask:0xf bank_mask:0xf
	v_add_f32_dpp v34, v34, v34 quad_perm:[2,3,0,1] row_mask:0xf bank_mask:0xf
	s_waitcnt lgkmcnt(0)
	s_nop 1
	v_add_f32_dpp v35, v35, v35 quad_perm:[1,0,3,2] row_mask:0xf bank_mask:0xf
	v_add_f32_dpp v34, v34, v34 quad_perm:[1,0,3,2] row_mask:0xf bank_mask:0xf
	s_waitcnt lgkmcnt(0)
	s_nop 0
	v_pk_fma_f32 v[34:35], v[34:35], s[96:97], v[4:5] op_sel_hi:[1,0,0]
	s_nop 0
	v_cmp_gt_f32_e64 s[0:1], s77, v35
	v_cmp_gt_f32_e32 vcc, s77, v34
	s_nop 0
	v_rsq_f32_e32 v33, v35
	s_nop 0
	v_mov_b32_e32 v36, v33
	v_pk_mul_f32 v[36:37], v[36:37], v[38:39] op_sel_hi:[0,1]
	v_pk_mul_f32 v[36:37], v[2:3], v[36:37]
	s_nop 0
	v_pk_mul_f32 v[36:37], v[40:41], v[36:37]
	s_waitcnt vmcnt(22)
	v_lshlrev_b32_e32 v40, 16, v30
	v_cvt_pk_bf16_f32 v33, v36, v37
	global_store_dword v[6:7], v33, off
	v_rsq_f32_e32 v6, v34
	v_mul_f32_e32 v33, 0xbfb8aa3b, v45
	v_exp_f32_e32 v33, v33
	v_lshlrev_b32_e32 v36, 16, v32
	v_mul_f32_e32 v7, 0xbfb8aa3b, v44
	v_exp_f32_e32 v7, v7
	v_add_f32_e32 v33, 1.0, v33
	v_rcp_f32_e32 v35, v33
	v_and_b32_e32 v37, 0xffff0000, v32
	v_add_f32_e32 v7, 1.0, v7
	v_rcp_f32_e32 v34, v7
	v_pk_mul_f32 v[6:7], v[6:7], v[42:43] op_sel_hi:[0,1]
	v_pk_mul_f32 v[6:7], v[2:3], v[6:7]
	v_and_b32_e32 v41, 0xffff0000, v30
	v_pk_mul_f32 v[34:35], v[34:35], v[44:45]
	s_nop 0
	v_pk_mul_f32 v[6:7], v[34:35], v[6:7]
	v_lshlrev_b32_e32 v34, 16, v31
	v_and_b32_e32 v35, 0xffff0000, v31
	v_mul_f32_e32 v31, 0xbfb8aa3b, v36
	v_exp_f32_e32 v31, v31
	v_cvt_pk_bf16_f32 v33, v6, v7
	v_add_co_u32_e32 v6, vcc, s76, v8
	v_add_f32_e32 v31, 1.0, v31
	v_rcp_f32_e32 v38, v31
	v_mul_f32_e32 v31, 0xbfb8aa3b, v37
	v_exp_f32_e32 v31, v31
	v_addc_co_u32_e32 v7, vcc, 0, v9, vcc
	global_store_dword v[6:7], v33, off offset:-4096
	v_add_f32_e32 v31, 1.0, v31
	v_rcp_f32_e32 v39, v31
	v_pk_mul_f32 v[32:33], v[34:35], v[34:35]
	v_pk_mul_f32 v[36:37], v[38:39], v[36:37]
	v_lshlrev_b32_e32 v38, 16, v29
	v_and_b32_e32 v39, 0xffff0000, v29
	v_pk_mul_f32 v[30:31], v[38:39], v[38:39]
	v_mov_b32_e32 v43, v32
	v_mov_b32_e32 v42, v30
	v_mov_b32_e32 v32, v31
	v_pk_add_f32 v[30:31], v[42:43], v[32:33]
	v_mov_b32_e32 v33, v31
	v_mov_b32_e32 v32, v30
	s_nop 0
	v_permlane32_swap_b32_e32 v33, v31
	v_permlane32_swap_b32_e32 v32, v30
	s_waitcnt lgkmcnt(0)
	v_pk_add_f32 v[30:31], v[30:31], v[32:33]
	v_mov_b32_e32 v33, v31
	v_mov_b32_e32 v32, v30
	s_nop 0
	v_permlane16_swap_b32_e32 v33, v31
	v_permlane16_swap_b32_e32 v32, v30
	s_waitcnt lgkmcnt(0)
	v_pk_add_f32 v[30:31], v[30:31], v[32:33]
	s_nop 1
	v_add_f32_dpp v31, v31, v31 row_ror:8 row_mask:0xf bank_mask:0xf
	v_add_f32_dpp v30, v30, v30 row_ror:8 row_mask:0xf bank_mask:0xf
	s_waitcnt lgkmcnt(0)
	s_nop 1
	v_add_f32_dpp v31, v31, v31 row_ror:4 row_mask:0xf bank_mask:0xf
	v_add_f32_dpp v30, v30, v30 row_ror:4 row_mask:0xf bank_mask:0xf
	s_waitcnt lgkmcnt(0)
	s_nop 1
	v_add_f32_dpp v31, v31, v31 quad_perm:[2,3,0,1] row_mask:0xf bank_mask:0xf
	v_add_f32_dpp v30, v30, v30 quad_perm:[2,3,0,1] row_mask:0xf bank_mask:0xf
	s_waitcnt lgkmcnt(0)
	s_nop 1
	v_add_f32_dpp v31, v31, v31 quad_perm:[1,0,3,2] row_mask:0xf bank_mask:0xf
	v_add_f32_dpp v30, v30, v30 quad_perm:[1,0,3,2] row_mask:0xf bank_mask:0xf
	s_waitcnt lgkmcnt(0)
	s_nop 0
	v_pk_fma_f32 v[30:31], v[30:31], s[96:97], v[4:5] op_sel_hi:[1,0,0]
	s_nop 0
	v_cmp_gt_f32_e64 s[0:1], s77, v31
	v_cmp_gt_f32_e32 vcc, s77, v30
	s_nop 0
	v_rsq_f32_e32 v29, v31
	s_nop 0
	v_mov_b32_e32 v32, v29
	v_pk_mul_f32 v[32:33], v[32:33], v[34:35] op_sel_hi:[0,1]
	v_pk_mul_f32 v[32:33], v[2:3], v[32:33]
	s_movk_i32 s0, 0x6000
	v_pk_mul_f32 v[32:33], v[36:37], v[32:33]
	s_waitcnt vmcnt(20)
	v_lshlrev_b32_e32 v36, 16, v26
	v_cvt_pk_bf16_f32 v29, v32, v33
	global_store_dword v[6:7], v29, off
	v_rsq_f32_e32 v6, v30
	v_mul_f32_e32 v29, 0xbfb8aa3b, v41
	v_exp_f32_e32 v29, v29
	v_lshlrev_b32_e32 v32, 16, v28
	v_mul_f32_e32 v7, 0xbfb8aa3b, v40
	v_exp_f32_e32 v7, v7
	v_add_f32_e32 v29, 1.0, v29
	v_rcp_f32_e32 v31, v29
	v_and_b32_e32 v33, 0xffff0000, v28
	v_add_f32_e32 v7, 1.0, v7
	v_rcp_f32_e32 v30, v7
	v_pk_mul_f32 v[6:7], v[6:7], v[38:39] op_sel_hi:[0,1]
	v_pk_mul_f32 v[6:7], v[2:3], v[6:7]
	v_and_b32_e32 v37, 0xffff0000, v26
	v_pk_mul_f32 v[30:31], v[30:31], v[40:41]
	s_nop 0
	v_pk_mul_f32 v[6:7], v[30:31], v[6:7]
	v_lshlrev_b32_e32 v30, 16, v27
	v_and_b32_e32 v31, 0xffff0000, v27
	v_mul_f32_e32 v27, 0xbfb8aa3b, v32
	v_exp_f32_e32 v27, v27
	v_cvt_pk_bf16_f32 v29, v6, v7
	v_add_co_u32_e32 v6, vcc, s0, v8
	v_add_f32_e32 v27, 1.0, v27
	v_rcp_f32_e32 v34, v27
	v_mul_f32_e32 v27, 0xbfb8aa3b, v33
	v_exp_f32_e32 v27, v27
	v_addc_co_u32_e32 v7, vcc, 0, v9, vcc
	global_store_dword v[6:7], v29, off offset:-4096
	v_add_f32_e32 v27, 1.0, v27
	v_rcp_f32_e32 v35, v27
	v_pk_mul_f32 v[28:29], v[30:31], v[30:31]
	v_pk_mul_f32 v[32:33], v[34:35], v[32:33]
	v_lshlrev_b32_e32 v34, 16, v25
	v_and_b32_e32 v35, 0xffff0000, v25
	v_pk_mul_f32 v[26:27], v[34:35], v[34:35]
	v_mov_b32_e32 v39, v28
	v_mov_b32_e32 v38, v26
	v_mov_b32_e32 v28, v27
	v_pk_add_f32 v[26:27], v[38:39], v[28:29]
	v_mov_b32_e32 v29, v27
	v_mov_b32_e32 v28, v26
	s_nop 0
	v_permlane32_swap_b32_e32 v29, v27
	v_permlane32_swap_b32_e32 v28, v26
	s_waitcnt lgkmcnt(0)
	v_pk_add_f32 v[26:27], v[26:27], v[28:29]
	v_mov_b32_e32 v29, v27
	v_mov_b32_e32 v28, v26
	s_nop 0
	v_permlane16_swap_b32_e32 v29, v27
	v_permlane16_swap_b32_e32 v28, v26
	s_waitcnt lgkmcnt(0)
	v_pk_add_f32 v[26:27], v[26:27], v[28:29]
	s_nop 1
	v_add_f32_dpp v27, v27, v27 row_ror:8 row_mask:0xf bank_mask:0xf
	v_add_f32_dpp v26, v26, v26 row_ror:8 row_mask:0xf bank_mask:0xf
	s_waitcnt lgkmcnt(0)
	s_nop 1
	v_add_f32_dpp v27, v27, v27 row_ror:4 row_mask:0xf bank_mask:0xf
	v_add_f32_dpp v26, v26, v26 row_ror:4 row_mask:0xf bank_mask:0xf
	s_waitcnt lgkmcnt(0)
	s_nop 1
	v_add_f32_dpp v27, v27, v27 quad_perm:[2,3,0,1] row_mask:0xf bank_mask:0xf
	v_add_f32_dpp v26, v26, v26 quad_perm:[2,3,0,1] row_mask:0xf bank_mask:0xf
	s_waitcnt lgkmcnt(0)
	s_nop 1
	v_add_f32_dpp v27, v27, v27 quad_perm:[1,0,3,2] row_mask:0xf bank_mask:0xf
	v_add_f32_dpp v26, v26, v26 quad_perm:[1,0,3,2] row_mask:0xf bank_mask:0xf
	s_waitcnt lgkmcnt(0)
	s_nop 0
	v_pk_fma_f32 v[26:27], v[26:27], s[96:97], v[4:5] op_sel_hi:[1,0,0]
	s_nop 0
	v_cmp_gt_f32_e64 s[0:1], s77, v27
	v_cmp_gt_f32_e32 vcc, s77, v26
	s_nop 0
	v_rsq_f32_e32 v25, v27
	s_nop 0
	v_mov_b32_e32 v28, v25
	v_pk_mul_f32 v[28:29], v[28:29], v[30:31] op_sel_hi:[0,1]
	v_pk_mul_f32 v[28:29], v[2:3], v[28:29]
	s_nop 0
	v_pk_mul_f32 v[28:29], v[32:33], v[28:29]
	s_waitcnt vmcnt(18)
	v_lshlrev_b32_e32 v32, 16, v22
	v_cvt_pk_bf16_f32 v25, v28, v29
	global_store_dword v[6:7], v25, off
	v_rsq_f32_e32 v6, v26
	v_mul_f32_e32 v25, 0xbfb8aa3b, v37
	v_exp_f32_e32 v25, v25
	v_lshlrev_b32_e32 v28, 16, v24
	v_mul_f32_e32 v7, 0xbfb8aa3b, v36
	v_exp_f32_e32 v7, v7
	v_add_f32_e32 v25, 1.0, v25
	v_rcp_f32_e32 v27, v25
	v_and_b32_e32 v29, 0xffff0000, v24
	v_add_f32_e32 v7, 1.0, v7
	v_rcp_f32_e32 v26, v7
	v_pk_mul_f32 v[6:7], v[6:7], v[34:35] op_sel_hi:[0,1]
	v_pk_mul_f32 v[6:7], v[2:3], v[6:7]
	v_and_b32_e32 v33, 0xffff0000, v22
	v_pk_mul_f32 v[26:27], v[26:27], v[36:37]
	s_nop 0
	v_pk_mul_f32 v[6:7], v[26:27], v[6:7]
	v_lshlrev_b32_e32 v26, 16, v23
	v_and_b32_e32 v27, 0xffff0000, v23
	v_mul_f32_e32 v23, 0xbfb8aa3b, v28
	v_exp_f32_e32 v23, v23
	v_cvt_pk_bf16_f32 v25, v6, v7
	v_add_co_u32_e32 v6, vcc, s4, v8
	v_add_f32_e32 v23, 1.0, v23
	v_rcp_f32_e32 v30, v23
	v_mul_f32_e32 v23, 0xbfb8aa3b, v29
	v_exp_f32_e32 v23, v23
	v_addc_co_u32_e32 v7, vcc, 0, v9, vcc
	global_store_dword v[6:7], v25, off offset:-4096
	v_add_f32_e32 v23, 1.0, v23
	v_rcp_f32_e32 v31, v23
	v_pk_mul_f32 v[24:25], v[26:27], v[26:27]
	v_pk_mul_f32 v[28:29], v[30:31], v[28:29]
	v_lshlrev_b32_e32 v30, 16, v21
	v_and_b32_e32 v31, 0xffff0000, v21
	v_pk_mul_f32 v[22:23], v[30:31], v[30:31]
	v_mov_b32_e32 v35, v24
	v_mov_b32_e32 v34, v22
	v_mov_b32_e32 v24, v23
	v_pk_add_f32 v[22:23], v[34:35], v[24:25]
	v_mov_b32_e32 v25, v23
	v_mov_b32_e32 v24, v22
	s_nop 0
	v_permlane32_swap_b32_e32 v25, v23
	v_permlane32_swap_b32_e32 v24, v22
	s_waitcnt lgkmcnt(0)
	v_pk_add_f32 v[22:23], v[22:23], v[24:25]
	v_mov_b32_e32 v25, v23
	v_mov_b32_e32 v24, v22
	s_nop 0
	v_permlane16_swap_b32_e32 v25, v23
	v_permlane16_swap_b32_e32 v24, v22
	s_waitcnt lgkmcnt(0)
	v_pk_add_f32 v[22:23], v[22:23], v[24:25]
	s_nop 1
	v_add_f32_dpp v23, v23, v23 row_ror:8 row_mask:0xf bank_mask:0xf
	v_add_f32_dpp v22, v22, v22 row_ror:8 row_mask:0xf bank_mask:0xf
	s_waitcnt lgkmcnt(0)
	s_nop 1
	v_add_f32_dpp v23, v23, v23 row_ror:4 row_mask:0xf bank_mask:0xf
	v_add_f32_dpp v22, v22, v22 row_ror:4 row_mask:0xf bank_mask:0xf
	s_waitcnt lgkmcnt(0)
	s_nop 1
	v_add_f32_dpp v23, v23, v23 quad_perm:[2,3,0,1] row_mask:0xf bank_mask:0xf
	v_add_f32_dpp v22, v22, v22 quad_perm:[2,3,0,1] row_mask:0xf bank_mask:0xf
	s_waitcnt lgkmcnt(0)
	s_nop 1
	v_add_f32_dpp v23, v23, v23 quad_perm:[1,0,3,2] row_mask:0xf bank_mask:0xf
	v_add_f32_dpp v22, v22, v22 quad_perm:[1,0,3,2] row_mask:0xf bank_mask:0xf
	s_waitcnt lgkmcnt(0)
	s_nop 0
	v_pk_fma_f32 v[22:23], v[22:23], s[96:97], v[4:5] op_sel_hi:[1,0,0]
	s_nop 0
	v_cmp_gt_f32_e64 s[0:1], s77, v23
	v_cmp_gt_f32_e32 vcc, s77, v22
	s_nop 0
	v_rsq_f32_e32 v21, v23
	s_nop 0
	v_mov_b32_e32 v24, v21
	v_pk_mul_f32 v[24:25], v[24:25], v[26:27] op_sel_hi:[0,1]
	v_pk_mul_f32 v[24:25], v[2:3], v[24:25]
	s_nop 0
	v_pk_mul_f32 v[24:25], v[28:29], v[24:25]
	s_waitcnt vmcnt(16)
	v_lshlrev_b32_e32 v28, 16, v18
	v_cvt_pk_bf16_f32 v21, v24, v25
	global_store_dword v[6:7], v21, off
	v_rsq_f32_e32 v6, v22
	v_mul_f32_e32 v21, 0xbfb8aa3b, v33
	v_exp_f32_e32 v21, v21
	v_lshlrev_b32_e32 v24, 16, v20
	v_mul_f32_e32 v7, 0xbfb8aa3b, v32
	v_exp_f32_e32 v7, v7
	v_add_f32_e32 v21, 1.0, v21
	v_rcp_f32_e32 v23, v21
	v_and_b32_e32 v25, 0xffff0000, v20
	v_add_f32_e32 v7, 1.0, v7
	v_rcp_f32_e32 v22, v7
	v_pk_mul_f32 v[6:7], v[6:7], v[30:31] op_sel_hi:[0,1]
	v_pk_mul_f32 v[6:7], v[2:3], v[6:7]
	v_and_b32_e32 v29, 0xffff0000, v18
	v_pk_mul_f32 v[22:23], v[22:23], v[32:33]
	s_nop 0
	v_pk_mul_f32 v[6:7], v[22:23], v[6:7]
	v_lshlrev_b32_e32 v22, 16, v19
	v_and_b32_e32 v23, 0xffff0000, v19
	v_mul_f32_e32 v19, 0xbfb8aa3b, v24
	v_exp_f32_e32 v19, v19
	v_cvt_pk_bf16_f32 v21, v6, v7
	v_add_co_u32_e32 v6, vcc, s12, v8
	v_add_f32_e32 v19, 1.0, v19
	v_rcp_f32_e32 v26, v19
	v_mul_f32_e32 v19, 0xbfb8aa3b, v25
	v_exp_f32_e32 v19, v19
	v_addc_co_u32_e32 v7, vcc, 0, v9, vcc
	global_store_dword v[6:7], v21, off offset:-4096
	v_add_f32_e32 v19, 1.0, v19
	v_rcp_f32_e32 v27, v19
	v_pk_mul_f32 v[20:21], v[22:23], v[22:23]
	v_pk_mul_f32 v[24:25], v[26:27], v[24:25]
	v_lshlrev_b32_e32 v26, 16, v17
	v_and_b32_e32 v27, 0xffff0000, v17
	v_pk_mul_f32 v[18:19], v[26:27], v[26:27]
	v_mov_b32_e32 v31, v20
	v_mov_b32_e32 v30, v18
	v_mov_b32_e32 v20, v19
	v_pk_add_f32 v[18:19], v[30:31], v[20:21]
	v_mov_b32_e32 v21, v19
	v_mov_b32_e32 v20, v18
	s_nop 0
	v_permlane32_swap_b32_e32 v21, v19
	v_permlane32_swap_b32_e32 v20, v18
	s_waitcnt lgkmcnt(0)
	v_pk_add_f32 v[18:19], v[18:19], v[20:21]
	v_mov_b32_e32 v21, v19
	v_mov_b32_e32 v20, v18
	s_nop 0
	v_permlane16_swap_b32_e32 v21, v19
	v_permlane16_swap_b32_e32 v20, v18
	s_waitcnt lgkmcnt(0)
	v_pk_add_f32 v[18:19], v[18:19], v[20:21]
	s_nop 1
	v_add_f32_dpp v19, v19, v19 row_ror:8 row_mask:0xf bank_mask:0xf
	v_add_f32_dpp v18, v18, v18 row_ror:8 row_mask:0xf bank_mask:0xf
	s_waitcnt lgkmcnt(0)
	s_nop 1
	v_add_f32_dpp v19, v19, v19 row_ror:4 row_mask:0xf bank_mask:0xf
	v_add_f32_dpp v18, v18, v18 row_ror:4 row_mask:0xf bank_mask:0xf
	s_waitcnt lgkmcnt(0)
	s_nop 1
	v_add_f32_dpp v19, v19, v19 quad_perm:[2,3,0,1] row_mask:0xf bank_mask:0xf
	v_add_f32_dpp v18, v18, v18 quad_perm:[2,3,0,1] row_mask:0xf bank_mask:0xf
	s_waitcnt lgkmcnt(0)
	s_nop 1
	v_add_f32_dpp v19, v19, v19 quad_perm:[1,0,3,2] row_mask:0xf bank_mask:0xf
	v_add_f32_dpp v18, v18, v18 quad_perm:[1,0,3,2] row_mask:0xf bank_mask:0xf
	s_waitcnt lgkmcnt(0)
	s_nop 0
	v_pk_fma_f32 v[18:19], v[18:19], s[96:97], v[4:5] op_sel_hi:[1,0,0]
	s_nop 0
	v_cmp_gt_f32_e64 s[0:1], s77, v19
	v_cmp_gt_f32_e32 vcc, s77, v18
	s_nop 0
	v_rsq_f32_e32 v17, v19
	s_nop 0
	v_mov_b32_e32 v20, v17
	v_pk_mul_f32 v[20:21], v[20:21], v[22:23] op_sel_hi:[0,1]
	v_pk_mul_f32 v[20:21], v[2:3], v[20:21]
	s_mov_b32 s0, 0xc000
	v_pk_mul_f32 v[20:21], v[24:25], v[20:21]
	s_waitcnt vmcnt(14)
	v_lshlrev_b32_e32 v24, 16, v14
	v_cvt_pk_bf16_f32 v17, v20, v21
	global_store_dword v[6:7], v17, off
	v_rsq_f32_e32 v6, v18
	v_mul_f32_e32 v17, 0xbfb8aa3b, v29
	v_exp_f32_e32 v17, v17
	v_lshlrev_b32_e32 v20, 16, v16
	v_mul_f32_e32 v7, 0xbfb8aa3b, v28
	v_exp_f32_e32 v7, v7
	v_add_f32_e32 v17, 1.0, v17
	v_rcp_f32_e32 v19, v17
	v_and_b32_e32 v21, 0xffff0000, v16
	v_add_f32_e32 v7, 1.0, v7
	v_rcp_f32_e32 v18, v7
	v_pk_mul_f32 v[6:7], v[6:7], v[26:27] op_sel_hi:[0,1]
	v_pk_mul_f32 v[6:7], v[2:3], v[6:7]
	v_and_b32_e32 v25, 0xffff0000, v14
	v_pk_mul_f32 v[18:19], v[18:19], v[28:29]
	s_nop 0
	v_pk_mul_f32 v[6:7], v[18:19], v[6:7]
	v_lshlrev_b32_e32 v18, 16, v15
	v_and_b32_e32 v19, 0xffff0000, v15
	v_mul_f32_e32 v15, 0xbfb8aa3b, v20
	v_exp_f32_e32 v15, v15
	v_cvt_pk_bf16_f32 v17, v6, v7
	v_add_co_u32_e32 v6, vcc, s0, v8
	v_add_f32_e32 v15, 1.0, v15
	v_rcp_f32_e32 v22, v15
	v_mul_f32_e32 v15, 0xbfb8aa3b, v21
	v_exp_f32_e32 v15, v15
	v_addc_co_u32_e32 v7, vcc, 0, v9, vcc
	global_store_dword v[6:7], v17, off offset:-4096
	v_add_f32_e32 v15, 1.0, v15
	v_rcp_f32_e32 v23, v15
	v_pk_mul_f32 v[16:17], v[18:19], v[18:19]
	v_pk_mul_f32 v[20:21], v[22:23], v[20:21]
	v_lshlrev_b32_e32 v22, 16, v13
	v_and_b32_e32 v23, 0xffff0000, v13
	v_pk_mul_f32 v[14:15], v[22:23], v[22:23]
	v_mov_b32_e32 v27, v16
	v_mov_b32_e32 v26, v14
	v_mov_b32_e32 v16, v15
	v_pk_add_f32 v[14:15], v[26:27], v[16:17]
	v_mov_b32_e32 v17, v15
	v_mov_b32_e32 v16, v14
	s_nop 0
	v_permlane32_swap_b32_e32 v17, v15
	v_permlane32_swap_b32_e32 v16, v14
	s_waitcnt lgkmcnt(0)
	v_pk_add_f32 v[14:15], v[14:15], v[16:17]
	v_mov_b32_e32 v17, v15
	v_mov_b32_e32 v16, v14
	s_nop 0
	v_permlane16_swap_b32_e32 v17, v15
	v_permlane16_swap_b32_e32 v16, v14
	s_waitcnt lgkmcnt(0)
	v_pk_add_f32 v[14:15], v[14:15], v[16:17]
	s_nop 1
	v_add_f32_dpp v15, v15, v15 row_ror:8 row_mask:0xf bank_mask:0xf
	v_add_f32_dpp v14, v14, v14 row_ror:8 row_mask:0xf bank_mask:0xf
	s_waitcnt lgkmcnt(0)
	s_nop 1
	v_add_f32_dpp v15, v15, v15 row_ror:4 row_mask:0xf bank_mask:0xf
	v_add_f32_dpp v14, v14, v14 row_ror:4 row_mask:0xf bank_mask:0xf
	s_waitcnt lgkmcnt(0)
	s_nop 1
	v_add_f32_dpp v15, v15, v15 quad_perm:[2,3,0,1] row_mask:0xf bank_mask:0xf
	v_add_f32_dpp v14, v14, v14 quad_perm:[2,3,0,1] row_mask:0xf bank_mask:0xf
	s_waitcnt lgkmcnt(0)
	s_nop 1
	v_add_f32_dpp v15, v15, v15 quad_perm:[1,0,3,2] row_mask:0xf bank_mask:0xf
	v_add_f32_dpp v14, v14, v14 quad_perm:[1,0,3,2] row_mask:0xf bank_mask:0xf
	s_waitcnt lgkmcnt(0)
	s_nop 0
	v_pk_fma_f32 v[14:15], v[14:15], s[96:97], v[4:5] op_sel_hi:[1,0,0]
	s_nop 0
	v_cmp_gt_f32_e64 s[0:1], s77, v15
	v_cmp_gt_f32_e32 vcc, s77, v14
	s_nop 0
	v_rsq_f32_e32 v13, v15
	s_nop 0
	v_mov_b32_e32 v16, v13
	v_pk_mul_f32 v[16:17], v[16:17], v[18:19] op_sel_hi:[0,1]
	v_pk_mul_f32 v[16:17], v[2:3], v[16:17]
	s_mov_b32 s0, 0xe000
	v_pk_mul_f32 v[16:17], v[20:21], v[16:17]
	s_waitcnt vmcnt(13)
	v_lshlrev_b32_e32 v20, 16, v10
	v_cvt_pk_bf16_f32 v13, v16, v17
	global_store_dword v[6:7], v13, off
	v_rsq_f32_e32 v6, v14
	v_mul_f32_e32 v13, 0xbfb8aa3b, v25
	v_exp_f32_e32 v13, v13
	s_waitcnt vmcnt(13)
	v_lshlrev_b32_e32 v16, 16, v12
	v_mul_f32_e32 v7, 0xbfb8aa3b, v24
	v_exp_f32_e32 v7, v7
	v_add_f32_e32 v13, 1.0, v13
	v_rcp_f32_e32 v15, v13
	v_and_b32_e32 v17, 0xffff0000, v12
	v_add_f32_e32 v7, 1.0, v7
	v_rcp_f32_e32 v14, v7
	v_pk_mul_f32 v[6:7], v[6:7], v[22:23] op_sel_hi:[0,1]
	v_pk_mul_f32 v[6:7], v[2:3], v[6:7]
	v_and_b32_e32 v21, 0xffff0000, v10
	v_pk_mul_f32 v[14:15], v[14:15], v[24:25]
	s_nop 0
	v_pk_mul_f32 v[6:7], v[14:15], v[6:7]
	v_lshlrev_b32_e32 v14, 16, v11
	v_and_b32_e32 v15, 0xffff0000, v11
	v_mul_f32_e32 v11, 0xbfb8aa3b, v16
	v_exp_f32_e32 v11, v11
	v_cvt_pk_bf16_f32 v13, v6, v7
	v_add_co_u32_e32 v6, vcc, s0, v8
	v_add_f32_e32 v11, 1.0, v11
	v_rcp_f32_e32 v18, v11
	v_mul_f32_e32 v11, 0xbfb8aa3b, v17
	v_exp_f32_e32 v11, v11
	v_addc_co_u32_e32 v7, vcc, 0, v9, vcc
	global_store_dword v[6:7], v13, off offset:-4096
	v_add_f32_e32 v11, 1.0, v11
	v_rcp_f32_e32 v19, v11
	v_pk_mul_f32 v[12:13], v[14:15], v[14:15]
	v_pk_mul_f32 v[16:17], v[18:19], v[16:17]
	v_lshlrev_b32_e32 v18, 16, v0
	v_and_b32_e32 v19, 0xffff0000, v0
	v_pk_mul_f32 v[10:11], v[18:19], v[18:19]
	v_mov_b32_e32 v23, v12
	v_mov_b32_e32 v22, v10
	v_mov_b32_e32 v12, v11
	v_pk_add_f32 v[10:11], v[22:23], v[12:13]
	v_mov_b32_e32 v13, v11
	v_mov_b32_e32 v12, v10
	s_nop 0
	v_permlane32_swap_b32_e32 v13, v11
	v_permlane32_swap_b32_e32 v12, v10
	s_waitcnt lgkmcnt(0)
	v_pk_add_f32 v[10:11], v[10:11], v[12:13]
	v_mov_b32_e32 v13, v11
	v_mov_b32_e32 v12, v10
	s_nop 0
	v_permlane16_swap_b32_e32 v13, v11
	v_permlane16_swap_b32_e32 v12, v10
	s_waitcnt lgkmcnt(0)
	v_pk_add_f32 v[10:11], v[10:11], v[12:13]
	s_nop 1
	v_add_f32_dpp v11, v11, v11 row_ror:8 row_mask:0xf bank_mask:0xf
	v_add_f32_dpp v10, v10, v10 row_ror:8 row_mask:0xf bank_mask:0xf
	s_waitcnt lgkmcnt(0)
	s_nop 1
	v_add_f32_dpp v11, v11, v11 row_ror:4 row_mask:0xf bank_mask:0xf
	v_add_f32_dpp v10, v10, v10 row_ror:4 row_mask:0xf bank_mask:0xf
	s_waitcnt lgkmcnt(0)
	s_nop 1
	v_add_f32_dpp v11, v11, v11 quad_perm:[2,3,0,1] row_mask:0xf bank_mask:0xf
	v_add_f32_dpp v10, v10, v10 quad_perm:[2,3,0,1] row_mask:0xf bank_mask:0xf
	s_waitcnt lgkmcnt(0)
	s_nop 1
	v_add_f32_dpp v11, v11, v11 quad_perm:[1,0,3,2] row_mask:0xf bank_mask:0xf
	v_add_f32_dpp v10, v10, v10 quad_perm:[1,0,3,2] row_mask:0xf bank_mask:0xf
	s_waitcnt lgkmcnt(0)
	s_nop 0
	v_pk_fma_f32 v[4:5], v[10:11], s[96:97], v[4:5] op_sel_hi:[1,0,0]
	s_nop 0
	v_cmp_gt_f32_e64 s[0:1], s77, v5
	v_cmp_gt_f32_e32 vcc, s77, v4
	s_nop 0
	v_rsq_f32_e32 v0, v5
	s_nop 0
	v_pk_mul_f32 v[10:11], v[0:1], v[14:15] op_sel_hi:[0,1]
	v_pk_mul_f32 v[10:11], v[2:3], v[10:11]
	s_nop 0
	v_pk_mul_f32 v[10:11], v[16:17], v[10:11]
	s_nop 0
	v_cvt_pk_bf16_f32 v0, v10, v11
	global_store_dword v[6:7], v0, off
	v_rsq_f32_e32 v0, v4
	s_nop 0
	v_mul_f32_e32 v4, 0xbfb8aa3b, v20
	v_pk_mul_f32 v[6:7], v[0:1], v[18:19] op_sel_hi:[0,1]
	v_mul_f32_e32 v0, 0xbfb8aa3b, v21
	v_exp_f32_e32 v4, v4
	v_exp_f32_e32 v0, v0
	v_pk_mul_f32 v[2:3], v[2:3], v[6:7]
	v_add_f32_e32 v4, 1.0, v4
	v_add_f32_e32 v0, 1.0, v0
	v_rcp_f32_e32 v4, v4
	v_rcp_f32_e32 v5, v0
	s_nop 0
	v_pk_mul_f32 v[4:5], v[4:5], v[20:21]
	s_nop 0
	v_pk_mul_f32 v[2:3], v[4:5], v[2:3]
	s_nop 0
	v_cvt_pk_bf16_f32 v0, v2, v3
	v_add_co_u32_e32 v2, vcc, 0xf000, v8
	s_nop 1
	v_addc_co_u32_e32 v3, vcc, 0, v9, vcc
	global_store_dword v[2:3], v0, off

.LBB0_316:
	s_andn2_b64 vcc, exec, s[0:1]
	s_cbranch_vccnz .LBB0_313
	s_lshl_b64 s[0:1], s[4:5], 6
	v_lshl_add_u64 v[38:39], v[8:9], 0, s[0:1]
	v_mov_b64_e32 v[40:41], s[30:31]
	v_mad_u64_u32 v[40:41], s[0:1], v38, s3, v[40:41]
	v_mad_u32_u24 v41, v39, s3, v41
	s_lshl_b32 s0, s34, 1
	s_mov_b32 s1, s5
	v_lshlrev_b64 v[44:45], 12, v[38:39]
	v_lshl_add_u64 v[38:39], v[40:41], 0, s[0:1]
	v_lshlrev_b32_e32 v0, 1, v6
	v_lshl_add_u64 v[100:101], v[38:39], 0, v[0:1]
	v_lshl_add_u64 v[70:71], v[4:5], 0, v[44:45]
	global_load_dword v102, v[100:101], off offset:3072
	global_load_dword v99, v[70:71], off
	v_or_b32_e32 v38, 0x1000, v44
	v_mov_b32_e32 v39, v45
	v_lshl_add_u64 v[68:69], v[4:5], 0, v[38:39]
	global_load_dword v107, v[68:69], off
	s_movk_i32 s0, 0x3000
	v_add_co_u32_e32 v38, vcc, s0, v100
	s_movk_i32 s0, 0x5000
	s_nop 0
	v_addc_co_u32_e32 v39, vcc, 0, v101, vcc
	global_load_dword v109, v[38:39], off offset:896
	v_or_b32_e32 v38, 0x2000, v44
	v_mov_b32_e32 v39, v45
	v_lshl_add_u64 v[66:67], v[4:5], 0, v[38:39]
	v_add_co_u32_e32 v38, vcc, s0, v100
	global_load_dword v97, v[66:67], off
	s_nop 0
	v_addc_co_u32_e32 v39, vcc, 0, v101, vcc
	global_load_dword v98, v[38:39], off offset:2816
	v_or_b32_e32 v38, 0x3000, v44
	v_mov_b32_e32 v39, v45
	s_mov_b32 s0, 0x8000
	v_lshl_add_u64 v[64:65], v[4:5], 0, v[38:39]
	v_add_co_u32_e32 v38, vcc, s0, v100
	global_load_dword v95, v[64:65], off
	s_nop 0
	v_addc_co_u32_e32 v39, vcc, 0, v101, vcc
	global_load_dword v96, v[38:39], off offset:640
	v_or_b32_e32 v38, 0x4000, v44
	v_mov_b32_e32 v39, v45
	s_mov_b32 s0, 0xa000
	v_lshl_add_u64 v[62:63], v[4:5], 0, v[38:39]
	v_add_co_u32_e32 v38, vcc, s0, v100
	global_load_dword v93, v[62:63], off
	s_nop 0
	v_addc_co_u32_e32 v39, vcc, 0, v101, vcc
	global_load_dword v94, v[38:39], off offset:2560
	v_or_b32_e32 v38, 0x5000, v44
	v_mov_b32_e32 v39, v45
	s_mov_b32 s0, 0xd000
	v_lshl_add_u64 v[60:61], v[4:5], 0, v[38:39]
	v_add_co_u32_e32 v38, vcc, s0, v100
	s_mov_b32 s0, 0xf000
	s_nop 0
	v_addc_co_u32_e32 v39, vcc, 0, v101, vcc
	global_load_dword v92, v[38:39], off offset:384
	v_or_b32_e32 v38, 0x6000, v44
	v_mov_b32_e32 v39, v45
	v_lshl_add_u64 v[58:59], v[4:5], 0, v[38:39]
	v_add_co_u32_e32 v38, vcc, s0, v100
	s_mov_b32 s0, 0x12000
	s_nop 0
	v_addc_co_u32_e32 v39, vcc, 0, v101, vcc
	global_load_dword v90, v[38:39], off offset:2304
	v_or_b32_e32 v38, 0x7000, v44
	v_mov_b32_e32 v39, v45
	v_lshl_add_u64 v[56:57], v[4:5], 0, v[38:39]
	v_add_co_u32_e32 v38, vcc, s0, v100
	s_mov_b32 s0, 0x14000
	s_nop 0
	v_addc_co_u32_e32 v39, vcc, 0, v101, vcc
	global_load_dword v88, v[38:39], off offset:128
	v_or_b32_e32 v38, 0x8000, v44
	v_mov_b32_e32 v39, v45
	v_lshl_add_u64 v[54:55], v[4:5], 0, v[38:39]
	v_add_co_u32_e32 v38, vcc, s0, v100
	s_mov_b32 s0, 0x16000
	s_nop 0
	v_addc_co_u32_e32 v39, vcc, 0, v101, vcc
	global_load_dword v86, v[38:39], off offset:2048
	v_or_b32_e32 v38, 0x9000, v44
	v_mov_b32_e32 v39, v45
	v_lshl_add_u64 v[52:53], v[4:5], 0, v[38:39]
	v_add_co_u32_e32 v38, vcc, s0, v100
	s_mov_b32 s0, 0x19000
	s_nop 0
	v_addc_co_u32_e32 v39, vcc, 0, v101, vcc
	global_load_dword v84, v[38:39], off offset:3968
	v_or_b32_e32 v38, 0xa000, v44
	v_mov_b32_e32 v39, v45
	v_lshl_add_u64 v[50:51], v[4:5], 0, v[38:39]
	v_add_co_u32_e32 v38, vcc, s0, v100
	s_mov_b32 s0, 0x1b000
	s_nop 0
	v_addc_co_u32_e32 v39, vcc, 0, v101, vcc
	global_load_dword v82, v[38:39], off offset:1792
	v_or_b32_e32 v38, 0xb000, v44
	v_mov_b32_e32 v39, v45
	v_lshl_add_u64 v[48:49], v[4:5], 0, v[38:39]
	v_add_co_u32_e32 v38, vcc, s0, v100
	s_mov_b32 s0, 0x1e000
	s_nop 0
	v_addc_co_u32_e32 v39, vcc, 0, v101, vcc
	global_load_dword v80, v[38:39], off offset:3712
	v_or_b32_e32 v38, 0xc000, v44
	v_mov_b32_e32 v39, v45
	v_lshl_add_u64 v[46:47], v[4:5], 0, v[38:39]
	v_add_co_u32_e32 v38, vcc, s0, v100
	s_mov_b32 s0, 0x20000
	s_nop 0
	v_addc_co_u32_e32 v39, vcc, 0, v101, vcc
	global_load_dword v78, v[38:39], off offset:1536
	v_or_b32_e32 v38, 0xd000, v44
	v_mov_b32_e32 v39, v45
	v_lshl_add_u64 v[42:43], v[4:5], 0, v[38:39]
	v_add_co_u32_e32 v38, vcc, s0, v100
	s_mov_b32 s0, 0x23000
	s_nop 0
	v_addc_co_u32_e32 v39, vcc, 0, v101, vcc
	global_load_dword v76, v[38:39], off offset:3456
	v_or_b32_e32 v38, 0xe000, v44
	v_mov_b32_e32 v39, v45
	v_lshl_add_u64 v[40:41], v[4:5], 0, v[38:39]
	v_add_co_u32_e32 v38, vcc, s0, v100
	v_or_b32_e32 v44, 0xf000, v44
	s_nop 0
	v_addc_co_u32_e32 v39, vcc, 0, v101, vcc
	s_mov_b32 s0, 0x25000
	global_load_dword v74, v[38:39], off offset:1280
	v_lshl_add_u64 v[38:39], v[4:5], 0, v[44:45]
	v_add_co_u32_e32 v44, vcc, s0, v100
	s_waitcnt vmcnt(18)
	v_lshlrev_b32_e32 v100, 16, v99
	v_addc_co_u32_e32 v45, vcc, 0, v101, vcc
	global_load_dword v72, v[44:45], off offset:3200
	v_lshlrev_b32_e32 v44, 16, v102
	v_and_b32_e32 v101, 0xffff0000, v99
	v_mul_f32_e32 v99, 0xbfb8aa3b, v44
	v_exp_f32_e32 v99, v99
	v_and_b32_e32 v45, 0xffff0000, v102
	s_waitcnt vmcnt(18)
	v_lshlrev_b32_e32 v106, 16, v107
	v_and_b32_e32 v107, 0xffff0000, v107
	v_add_f32_e32 v99, 1.0, v99
	v_rcp_f32_e32 v104, v99
	v_mul_f32_e32 v99, 0xbfb8aa3b, v45
	v_exp_f32_e32 v99, v99
	v_pk_mul_f32 v[102:103], v[100:101], v[100:101]
	s_waitcnt vmcnt(17)
	v_lshlrev_b32_e32 v108, 16, v109
	v_mov_b32_e32 v111, v102
	v_add_f32_e32 v99, 1.0, v99
	v_rcp_f32_e32 v105, v99
	v_and_b32_e32 v109, 0xffff0000, v109
	global_load_dword v91, v[60:61], off
	global_load_dword v89, v[58:59], off
	global_load_dword v87, v[56:57], off
	global_load_dword v85, v[54:55], off
	global_load_dword v83, v[52:53], off
	global_load_dword v81, v[50:51], off
	global_load_dword v79, v[48:49], off
	global_load_dword v77, v[46:47], off
	v_pk_mul_f32 v[104:105], v[104:105], v[44:45]
	v_pk_mul_f32 v[44:45], v[106:107], v[106:107]
	global_load_dword v75, v[42:43], off
	global_load_dword v73, v[40:41], off
	global_load_dword v0, v[38:39], off
	v_mov_b32_e32 v110, v44
	v_mov_b32_e32 v102, v45
	v_pk_add_f32 v[44:45], v[110:111], v[102:103]
	v_mov_b32_e32 v103, v45
	v_mov_b32_e32 v102, v44
	s_nop 0
	v_permlane32_swap_b32_e32 v103, v45
	v_permlane32_swap_b32_e32 v102, v44
	s_waitcnt lgkmcnt(0)
	v_pk_add_f32 v[44:45], v[44:45], v[102:103]
	v_mov_b32_e32 v103, v45
	v_mov_b32_e32 v102, v44
	s_nop 0
	v_permlane16_swap_b32_e32 v103, v45
	v_permlane16_swap_b32_e32 v102, v44
	s_waitcnt lgkmcnt(0)
	v_pk_add_f32 v[44:45], v[44:45], v[102:103]
	s_nop 1
	v_add_f32_dpp v45, v45, v45 row_ror:8 row_mask:0xf bank_mask:0xf
	v_add_f32_dpp v44, v44, v44 row_ror:8 row_mask:0xf bank_mask:0xf
	s_waitcnt lgkmcnt(0)
	s_nop 1
	v_add_f32_dpp v45, v45, v45 row_ror:4 row_mask:0xf bank_mask:0xf
	v_add_f32_dpp v44, v44, v44 row_ror:4 row_mask:0xf bank_mask:0xf
	s_waitcnt lgkmcnt(0)
	s_nop 1
	v_add_f32_dpp v45, v45, v45 quad_perm:[2,3,0,1] row_mask:0xf bank_mask:0xf
	v_add_f32_dpp v44, v44, v44 quad_perm:[2,3,0,1] row_mask:0xf bank_mask:0xf
	s_waitcnt lgkmcnt(0)
	s_nop 1
	v_add_f32_dpp v103, v45, v45 quad_perm:[1,0,3,2] row_mask:0xf bank_mask:0xf
	v_add_f32_dpp v102, v44, v44 quad_perm:[1,0,3,2] row_mask:0xf bank_mask:0xf
	s_waitcnt lgkmcnt(0)
	v_mov_b64_e32 v[44:45], s[72:73]
	v_pk_fma_f32 v[102:103], v[102:103], s[96:97], v[44:45] op_sel_hi:[1,0,0]
	s_nop 0
	v_cmp_gt_f32_e64 s[0:1], s77, v103
	v_cmp_gt_f32_e32 vcc, s77, v102
	s_nop 0
	v_rsq_f32_e32 v99, v103
	s_nop 0
	v_mov_b32_e32 v110, v99
	v_pk_mul_f32 v[100:101], v[110:111], v[100:101] op_sel_hi:[0,1]
	v_pk_mul_f32 v[100:101], v[2:3], v[100:101]
	s_waitcnt vmcnt(24)
	v_and_b32_e32 v103, 0xffff0000, v96
	v_pk_mul_f32 v[100:101], v[104:105], v[100:101]
	s_nop 0
	v_cvt_pk_bf16_f32 v99, v100, v101
	global_store_dword v[70:71], v99, off
	v_rsq_f32_e32 v70, v102
	v_mul_f32_e32 v99, 0xbfb8aa3b, v109
	v_exp_f32_e32 v99, v99
	v_lshlrev_b32_e32 v102, 16, v96
	v_mul_f32_e32 v71, 0xbfb8aa3b, v108
	v_exp_f32_e32 v71, v71
	v_add_f32_e32 v99, 1.0, v99
	v_rcp_f32_e32 v101, v99
	v_add_f32_e32 v71, 1.0, v71
	v_rcp_f32_e32 v100, v71
	v_pk_mul_f32 v[70:71], v[70:71], v[106:107] op_sel_hi:[0,1]
	v_pk_mul_f32 v[70:71], v[2:3], v[70:71]
	v_pk_mul_f32 v[100:101], v[100:101], v[108:109]
	s_nop 0
	v_pk_mul_f32 v[70:71], v[100:101], v[70:71]
	s_nop 0
	v_cvt_pk_bf16_f32 v70, v70, v71
	global_store_dword v[68:69], v70, off
	v_lshlrev_b32_e32 v70, 16, v98
	v_lshlrev_b32_e32 v68, 16, v97
	v_and_b32_e32 v69, 0xffff0000, v97
	v_mul_f32_e32 v97, 0xbfb8aa3b, v70
	v_exp_f32_e32 v97, v97
	v_and_b32_e32 v71, 0xffff0000, v98
	v_pk_mul_f32 v[98:99], v[68:69], v[68:69]
	v_add_f32_e32 v97, 1.0, v97
	v_rcp_f32_e32 v100, v97
	v_mul_f32_e32 v97, 0xbfb8aa3b, v71
	v_exp_f32_e32 v97, v97
	v_mov_b32_e32 v105, v98
	v_add_f32_e32 v97, 1.0, v97
	v_rcp_f32_e32 v101, v97
	s_nop 0
	v_pk_mul_f32 v[70:71], v[100:101], v[70:71]
	v_lshlrev_b32_e32 v100, 16, v95
	v_and_b32_e32 v101, 0xffff0000, v95
	v_pk_mul_f32 v[96:97], v[100:101], v[100:101]
	s_nop 0
	v_mov_b32_e32 v104, v96
	v_mov_b32_e32 v98, v97
	v_pk_add_f32 v[96:97], v[104:105], v[98:99]
	v_mov_b32_e32 v99, v97
	v_mov_b32_e32 v98, v96
	s_nop 0
	v_permlane32_swap_b32_e32 v99, v97
	v_permlane32_swap_b32_e32 v98, v96
	s_waitcnt lgkmcnt(0)
	v_pk_add_f32 v[96:97], v[96:97], v[98:99]
	v_mov_b32_e32 v99, v97
	v_mov_b32_e32 v98, v96
	s_nop 0
	v_permlane16_swap_b32_e32 v99, v97
	v_permlane16_swap_b32_e32 v98, v96
	s_waitcnt lgkmcnt(0)
	v_pk_add_f32 v[96:97], v[96:97], v[98:99]
	s_nop 1
	v_add_f32_dpp v97, v97, v97 row_ror:8 row_mask:0xf bank_mask:0xf
	v_add_f32_dpp v96, v96, v96 row_ror:8 row_mask:0xf bank_mask:0xf
	s_waitcnt lgkmcnt(0)
	s_nop 1
	v_add_f32_dpp v97, v97, v97 row_ror:4 row_mask:0xf bank_mask:0xf
	v_add_f32_dpp v96, v96, v96 row_ror:4 row_mask:0xf bank_mask:0xf
	s_waitcnt lgkmcnt(0)
	s_nop 1
	v_add_f32_dpp v97, v97, v97 quad_perm:[2,3,0,1] row_mask:0xf bank_mask:0xf
	v_add_f32_dpp v96, v96, v96 quad_perm:[2,3,0,1] row_mask:0xf bank_mask:0xf
	s_waitcnt lgkmcnt(0)
	s_nop 1
	v_add_f32_dpp v97, v97, v97 quad_perm:[1,0,3,2] row_mask:0xf bank_mask:0xf
	v_add_f32_dpp v96, v96, v96 quad_perm:[1,0,3,2] row_mask:0xf bank_mask:0xf
	s_waitcnt lgkmcnt(0)
	s_nop 0
	v_pk_fma_f32 v[96:97], v[96:97], s[96:97], v[44:45] op_sel_hi:[1,0,0]
	s_nop 0
	v_cmp_gt_f32_e64 s[0:1], s77, v97
	v_cmp_gt_f32_e32 vcc, s77, v96
	s_nop 0
	v_rsq_f32_e32 v95, v97
	s_nop 0
	v_mov_b32_e32 v98, v95
	v_pk_mul_f32 v[68:69], v[98:99], v[68:69] op_sel_hi:[0,1]
	v_pk_mul_f32 v[68:69], v[2:3], v[68:69]
	s_waitcnt vmcnt(23)
	v_and_b32_e32 v95, 0xffff0000, v92
	v_pk_mul_f32 v[68:69], v[70:71], v[68:69]
	s_nop 0
	v_cvt_pk_bf16_f32 v68, v68, v69
	global_store_dword v[66:67], v68, off
	v_rsq_f32_e32 v66, v96
	v_mul_f32_e32 v69, 0xbfb8aa3b, v103
	v_exp_f32_e32 v69, v69
	v_mul_f32_e32 v67, 0xbfb8aa3b, v102
	v_exp_f32_e32 v67, v67
	v_add_f32_e32 v69, 1.0, v69
	v_rcp_f32_e32 v69, v69
	v_add_f32_e32 v67, 1.0, v67
	v_rcp_f32_e32 v68, v67
	v_pk_mul_f32 v[66:67], v[66:67], v[100:101] op_sel_hi:[0,1]
	v_pk_mul_f32 v[66:67], v[2:3], v[66:67]
	v_pk_mul_f32 v[68:69], v[68:69], v[102:103]
	s_nop 0
	v_pk_mul_f32 v[66:67], v[68:69], v[66:67]
	s_nop 0
	v_cvt_pk_bf16_f32 v66, v66, v67
	global_store_dword v[64:65], v66, off
	v_lshlrev_b32_e32 v66, 16, v94
	v_and_b32_e32 v67, 0xffff0000, v94
	v_mul_f32_e32 v70, 0xbfb8aa3b, v66
	v_mul_f32_e32 v71, 0xbfb8aa3b, v67
	v_exp_f32_e32 v70, v70
	v_exp_f32_e32 v71, v71
	v_lshlrev_b32_e32 v64, 16, v93
	v_and_b32_e32 v65, 0xffff0000, v93
	v_add_f32_e32 v70, 1.0, v70
	v_add_f32_e32 v71, 1.0, v71
	v_rcp_f32_e32 v70, v70
	v_rcp_f32_e32 v71, v71
	v_pk_mul_f32 v[68:69], v[64:65], v[64:65]
	v_lshlrev_b32_e32 v94, 16, v92
	v_mov_b32_e32 v97, v68
	v_pk_mul_f32 v[66:67], v[70:71], v[66:67]
	s_waitcnt vmcnt(14)
	v_lshlrev_b32_e32 v70, 16, v91
	v_and_b32_e32 v71, 0xffff0000, v91
	v_pk_mul_f32 v[92:93], v[70:71], v[70:71]
	s_nop 0
	v_mov_b32_e32 v96, v92
	v_mov_b32_e32 v68, v93
	v_pk_add_f32 v[68:69], v[96:97], v[68:69]
	v_mov_b32_e32 v93, v69
	v_mov_b32_e32 v92, v68
	s_nop 0
	v_permlane32_swap_b32_e32 v93, v69
	v_permlane32_swap_b32_e32 v92, v68
	s_waitcnt lgkmcnt(0)
	v_pk_add_f32 v[68:69], v[68:69], v[92:93]
	v_mov_b32_e32 v93, v69
	v_mov_b32_e32 v92, v68
	s_nop 0
	v_permlane16_swap_b32_e32 v93, v69
	v_permlane16_swap_b32_e32 v92, v68
	s_waitcnt lgkmcnt(0)
	v_pk_add_f32 v[68:69], v[68:69], v[92:93]
	s_nop 1
	v_add_f32_dpp v69, v69, v69 row_ror:8 row_mask:0xf bank_mask:0xf
	v_add_f32_dpp v68, v68, v68 row_ror:8 row_mask:0xf bank_mask:0xf
	s_waitcnt lgkmcnt(0)
	s_nop 1
	v_add_f32_dpp v69, v69, v69 row_ror:4 row_mask:0xf bank_mask:0xf
	v_add_f32_dpp v68, v68, v68 row_ror:4 row_mask:0xf bank_mask:0xf
	s_waitcnt lgkmcnt(0)
	s_nop 1
	v_add_f32_dpp v69, v69, v69 quad_perm:[2,3,0,1] row_mask:0xf bank_mask:0xf
	v_add_f32_dpp v68, v68, v68 quad_perm:[2,3,0,1] row_mask:0xf bank_mask:0xf
	s_waitcnt lgkmcnt(0)
	s_nop 1
	v_add_f32_dpp v69, v69, v69 quad_perm:[1,0,3,2] row_mask:0xf bank_mask:0xf
	v_add_f32_dpp v68, v68, v68 quad_perm:[1,0,3,2] row_mask:0xf bank_mask:0xf
	s_waitcnt lgkmcnt(0)
	s_nop 0
	v_pk_fma_f32 v[68:69], v[68:69], s[96:97], v[44:45] op_sel_hi:[1,0,0]
	s_nop 0
	v_mul_f32_e32 v91, 0x4b800000, v69
	v_cmp_gt_f32_e64 s[0:1], s77, v69
	v_cmp_gt_f32_e32 vcc, s77, v68
	s_nop 0
	v_cndmask_b32_e64 v69, v69, v91, s[0:1]
	v_rsq_f32_e32 v69, v69
	s_nop 0
	v_mul_f32_e32 v91, 0x45800000, v69
	v_cndmask_b32_e64 v92, v69, v91, s[0:1]
	v_pk_mul_f32 v[64:65], v[92:93], v[64:65] op_sel_hi:[0,1]
	v_pk_mul_f32 v[64:65], v[2:3], v[64:65]
	v_and_b32_e32 v69, 0xffff0000, v88
	v_pk_mul_f32 v[64:65], v[66:67], v[64:65]
	s_nop 0
	v_cvt_pk_bf16_f32 v64, v64, v65
	global_store_dword v[62:63], v64, off
	v_rsq_f32_e32 v62, v68
	v_mul_f32_e32 v65, 0xbfb8aa3b, v95
	v_exp_f32_e32 v65, v65
	v_lshlrev_b32_e32 v68, 16, v88
	v_mul_f32_e32 v63, 0xbfb8aa3b, v94
	v_exp_f32_e32 v63, v63
	v_add_f32_e32 v65, 1.0, v65
	v_rcp_f32_e32 v65, v65
	v_add_f32_e32 v63, 1.0, v63
	v_rcp_f32_e32 v64, v63
	v_pk_mul_f32 v[62:63], v[62:63], v[70:71] op_sel_hi:[0,1]
	v_pk_mul_f32 v[62:63], v[2:3], v[62:63]
	v_pk_mul_f32 v[64:65], v[64:65], v[94:95]
	s_nop 0
	v_pk_mul_f32 v[62:63], v[64:65], v[62:63]
	s_nop 0
	v_cvt_pk_bf16_f32 v62, v62, v63
	global_store_dword v[60:61], v62, off
	v_lshlrev_b32_e32 v62, 16, v90
	v_and_b32_e32 v63, 0xffff0000, v90
	v_mul_f32_e32 v66, 0xbfb8aa3b, v62
	v_mul_f32_e32 v67, 0xbfb8aa3b, v63
	v_exp_f32_e32 v66, v66
	v_exp_f32_e32 v67, v67
	s_waitcnt vmcnt(15)
	v_lshlrev_b32_e32 v60, 16, v89
	v_and_b32_e32 v61, 0xffff0000, v89
	v_add_f32_e32 v66, 1.0, v66
	v_add_f32_e32 v67, 1.0, v67
	v_rcp_f32_e32 v66, v66
	v_rcp_f32_e32 v67, v67
	v_pk_mul_f32 v[64:65], v[60:61], v[60:61]
	v_pk_mul_f32 v[62:63], v[66:67], v[62:63]
	s_waitcnt vmcnt(14)
	v_lshlrev_b32_e32 v66, 16, v87
	v_and_b32_e32 v67, 0xffff0000, v87
	v_pk_mul_f32 v[70:71], v[66:67], v[66:67]
	v_mov_b32_e32 v89, v64
	v_mov_b32_e32 v88, v70
	v_mov_b32_e32 v64, v71
	v_pk_add_f32 v[64:65], v[88:89], v[64:65]
	v_mov_b32_e32 v71, v65
	v_mov_b32_e32 v70, v64
	s_nop 0
	v_permlane32_swap_b32_e32 v71, v65
	v_permlane32_swap_b32_e32 v70, v64
	s_waitcnt lgkmcnt(0)
	v_pk_add_f32 v[64:65], v[64:65], v[70:71]
	v_mov_b32_e32 v71, v65
	v_mov_b32_e32 v70, v64
	s_nop 0
	v_permlane16_swap_b32_e32 v71, v65
	v_permlane16_swap_b32_e32 v70, v64
	s_waitcnt lgkmcnt(0)
	v_pk_add_f32 v[64:65], v[64:65], v[70:71]
	s_nop 1
	v_add_f32_dpp v65, v65, v65 row_ror:8 row_mask:0xf bank_mask:0xf
	v_add_f32_dpp v64, v64, v64 row_ror:8 row_mask:0xf bank_mask:0xf
	s_waitcnt lgkmcnt(0)
	s_nop 1
	v_add_f32_dpp v65, v65, v65 row_ror:4 row_mask:0xf bank_mask:0xf
	v_add_f32_dpp v64, v64, v64 row_ror:4 row_mask:0xf bank_mask:0xf
	s_waitcnt lgkmcnt(0)
	s_nop 1
	v_add_f32_dpp v65, v65, v65 quad_perm:[2,3,0,1] row_mask:0xf bank_mask:0xf
	v_add_f32_dpp v64, v64, v64 quad_perm:[2,3,0,1] row_mask:0xf bank_mask:0xf
	s_waitcnt lgkmcnt(0)
	s_nop 1
	v_add_f32_dpp v65, v65, v65 quad_perm:[1,0,3,2] row_mask:0xf bank_mask:0xf
	v_add_f32_dpp v64, v64, v64 quad_perm:[1,0,3,2] row_mask:0xf bank_mask:0xf
	s_waitcnt lgkmcnt(0)
	s_nop 0
	v_pk_fma_f32 v[64:65], v[64:65], s[96:97], v[44:45] op_sel_hi:[1,0,0]
	s_nop 0
	v_mul_f32_e32 v70, 0x4b800000, v65
	v_cmp_gt_f32_e64 s[0:1], s77, v65
	v_cmp_gt_f32_e32 vcc, s77, v64
	s_nop 0
	v_cndmask_b32_e64 v65, v65, v70, s[0:1]
	v_rsq_f32_e32 v65, v65
	s_nop 0
	v_mul_f32_e32 v70, 0x45800000, v65
	v_cndmask_b32_e64 v70, v65, v70, s[0:1]
	v_pk_mul_f32 v[60:61], v[70:71], v[60:61] op_sel_hi:[0,1]
	v_pk_mul_f32 v[60:61], v[2:3], v[60:61]
	v_and_b32_e32 v65, 0xffff0000, v84
	v_pk_mul_f32 v[60:61], v[62:63], v[60:61]
	s_nop 0
	v_cvt_pk_bf16_f32 v60, v60, v61
	global_store_dword v[58:59], v60, off
	v_rsq_f32_e32 v58, v64
	v_mul_f32_e32 v61, 0xbfb8aa3b, v69
	v_exp_f32_e32 v61, v61
	v_lshlrev_b32_e32 v64, 16, v84
	v_mul_f32_e32 v59, 0xbfb8aa3b, v68
	v_exp_f32_e32 v59, v59
	v_add_f32_e32 v61, 1.0, v61
	v_rcp_f32_e32 v61, v61
	v_add_f32_e32 v59, 1.0, v59
	v_rcp_f32_e32 v60, v59
	v_pk_mul_f32 v[58:59], v[58:59], v[66:67] op_sel_hi:[0,1]
	v_pk_mul_f32 v[58:59], v[2:3], v[58:59]
	v_pk_mul_f32 v[60:61], v[60:61], v[68:69]
	s_nop 0
	v_pk_mul_f32 v[58:59], v[60:61], v[58:59]
	s_nop 0
	v_cvt_pk_bf16_f32 v58, v58, v59
	global_store_dword v[56:57], v58, off
	v_lshlrev_b32_e32 v58, 16, v86
	v_and_b32_e32 v59, 0xffff0000, v86
	v_mul_f32_e32 v62, 0xbfb8aa3b, v58
	v_mul_f32_e32 v63, 0xbfb8aa3b, v59
	v_exp_f32_e32 v62, v62
	v_exp_f32_e32 v63, v63
	s_waitcnt vmcnt(15)
	v_lshlrev_b32_e32 v56, 16, v85
	v_and_b32_e32 v57, 0xffff0000, v85
	v_add_f32_e32 v62, 1.0, v62
	v_add_f32_e32 v63, 1.0, v63
	v_rcp_f32_e32 v62, v62
	v_rcp_f32_e32 v63, v63
	v_pk_mul_f32 v[60:61], v[56:57], v[56:57]
	v_pk_mul_f32 v[58:59], v[62:63], v[58:59]
	s_waitcnt vmcnt(14)
	v_lshlrev_b32_e32 v62, 16, v83
	v_and_b32_e32 v63, 0xffff0000, v83
	v_pk_mul_f32 v[66:67], v[62:63], v[62:63]
	v_mov_b32_e32 v69, v60
	v_mov_b32_e32 v68, v66
	v_mov_b32_e32 v60, v67
	v_pk_add_f32 v[60:61], v[68:69], v[60:61]
	v_mov_b32_e32 v67, v61
	v_mov_b32_e32 v66, v60
	s_nop 0
	v_permlane32_swap_b32_e32 v67, v61
	v_permlane32_swap_b32_e32 v66, v60
	s_waitcnt lgkmcnt(0)
	v_pk_add_f32 v[60:61], v[60:61], v[66:67]
	v_mov_b32_e32 v67, v61
	v_mov_b32_e32 v66, v60
	s_nop 0
	v_permlane16_swap_b32_e32 v67, v61
	v_permlane16_swap_b32_e32 v66, v60
	s_waitcnt lgkmcnt(0)
	v_pk_add_f32 v[60:61], v[60:61], v[66:67]
	s_nop 1
	v_add_f32_dpp v61, v61, v61 row_ror:8 row_mask:0xf bank_mask:0xf
	v_add_f32_dpp v60, v60, v60 row_ror:8 row_mask:0xf bank_mask:0xf
	s_waitcnt lgkmcnt(0)
	s_nop 1
	v_add_f32_dpp v61, v61, v61 row_ror:4 row_mask:0xf bank_mask:0xf
	v_add_f32_dpp v60, v60, v60 row_ror:4 row_mask:0xf bank_mask:0xf
	s_waitcnt lgkmcnt(0)
	s_nop 1
	v_add_f32_dpp v61, v61, v61 quad_perm:[2,3,0,1] row_mask:0xf bank_mask:0xf
	v_add_f32_dpp v60, v60, v60 quad_perm:[2,3,0,1] row_mask:0xf bank_mask:0xf
	s_waitcnt lgkmcnt(0)
	s_nop 1
	v_add_f32_dpp v61, v61, v61 quad_perm:[1,0,3,2] row_mask:0xf bank_mask:0xf
	v_add_f32_dpp v60, v60, v60 quad_perm:[1,0,3,2] row_mask:0xf bank_mask:0xf
	s_waitcnt lgkmcnt(0)
	s_nop 0
	v_pk_fma_f32 v[60:61], v[60:61], s[96:97], v[44:45] op_sel_hi:[1,0,0]
	s_nop 0
	v_mul_f32_e32 v66, 0x4b800000, v61
	v_cmp_gt_f32_e64 s[0:1], s77, v61
	v_cmp_gt_f32_e32 vcc, s77, v60
	s_nop 0
	v_cndmask_b32_e64 v61, v61, v66, s[0:1]
	v_rsq_f32_e32 v61, v61
	s_nop 0
	v_mul_f32_e32 v66, 0x45800000, v61
	v_cndmask_b32_e64 v66, v61, v66, s[0:1]
	v_pk_mul_f32 v[56:57], v[66:67], v[56:57] op_sel_hi:[0,1]
	v_pk_mul_f32 v[56:57], v[2:3], v[56:57]
	v_and_b32_e32 v61, 0xffff0000, v80
	v_pk_mul_f32 v[56:57], v[58:59], v[56:57]
	s_nop 0
	v_cvt_pk_bf16_f32 v56, v56, v57
	global_store_dword v[54:55], v56, off
	v_rsq_f32_e32 v54, v60
	v_mul_f32_e32 v57, 0xbfb8aa3b, v65
	v_exp_f32_e32 v57, v57
	v_lshlrev_b32_e32 v60, 16, v80
	v_mul_f32_e32 v55, 0xbfb8aa3b, v64
	v_exp_f32_e32 v55, v55
	v_add_f32_e32 v57, 1.0, v57
	v_rcp_f32_e32 v57, v57
	v_add_f32_e32 v55, 1.0, v55
	v_rcp_f32_e32 v56, v55
	v_pk_mul_f32 v[54:55], v[54:55], v[62:63] op_sel_hi:[0,1]
	v_pk_mul_f32 v[54:55], v[2:3], v[54:55]
	v_pk_mul_f32 v[56:57], v[56:57], v[64:65]
	s_nop 0
	v_pk_mul_f32 v[54:55], v[56:57], v[54:55]
	s_nop 0
	v_cvt_pk_bf16_f32 v54, v54, v55
	global_store_dword v[52:53], v54, off
	v_lshlrev_b32_e32 v54, 16, v82
	v_and_b32_e32 v55, 0xffff0000, v82
	v_mul_f32_e32 v58, 0xbfb8aa3b, v54
	v_mul_f32_e32 v59, 0xbfb8aa3b, v55
	v_exp_f32_e32 v58, v58
	v_exp_f32_e32 v59, v59
	s_waitcnt vmcnt(15)
	v_lshlrev_b32_e32 v52, 16, v81
	v_and_b32_e32 v53, 0xffff0000, v81
	v_add_f32_e32 v58, 1.0, v58
	v_add_f32_e32 v59, 1.0, v59
	v_rcp_f32_e32 v58, v58
	v_rcp_f32_e32 v59, v59
	v_pk_mul_f32 v[56:57], v[52:53], v[52:53]
	v_pk_mul_f32 v[54:55], v[58:59], v[54:55]
	s_waitcnt vmcnt(14)
	v_lshlrev_b32_e32 v58, 16, v79
	v_and_b32_e32 v59, 0xffff0000, v79
	v_pk_mul_f32 v[62:63], v[58:59], v[58:59]
	v_mov_b32_e32 v65, v56
	v_mov_b32_e32 v64, v62
	v_mov_b32_e32 v56, v63
	v_pk_add_f32 v[56:57], v[64:65], v[56:57]
	v_mov_b32_e32 v63, v57
	v_mov_b32_e32 v62, v56
	s_nop 0
	v_permlane32_swap_b32_e32 v63, v57
	v_permlane32_swap_b32_e32 v62, v56
	s_waitcnt lgkmcnt(0)
	v_pk_add_f32 v[56:57], v[56:57], v[62:63]
	v_mov_b32_e32 v63, v57
	v_mov_b32_e32 v62, v56
	s_nop 0
	v_permlane16_swap_b32_e32 v63, v57
	v_permlane16_swap_b32_e32 v62, v56
	s_waitcnt lgkmcnt(0)
	v_pk_add_f32 v[56:57], v[56:57], v[62:63]
	s_nop 1
	v_add_f32_dpp v57, v57, v57 row_ror:8 row_mask:0xf bank_mask:0xf
	v_add_f32_dpp v56, v56, v56 row_ror:8 row_mask:0xf bank_mask:0xf
	s_waitcnt lgkmcnt(0)
	s_nop 1
	v_add_f32_dpp v57, v57, v57 row_ror:4 row_mask:0xf bank_mask:0xf
	v_add_f32_dpp v56, v56, v56 row_ror:4 row_mask:0xf bank_mask:0xf
	s_waitcnt lgkmcnt(0)
	s_nop 1
	v_add_f32_dpp v57, v57, v57 quad_perm:[2,3,0,1] row_mask:0xf bank_mask:0xf
	v_add_f32_dpp v56, v56, v56 quad_perm:[2,3,0,1] row_mask:0xf bank_mask:0xf
	s_waitcnt lgkmcnt(0)
	s_nop 1
	v_add_f32_dpp v57, v57, v57 quad_perm:[1,0,3,2] row_mask:0xf bank_mask:0xf
	v_add_f32_dpp v56, v56, v56 quad_perm:[1,0,3,2] row_mask:0xf bank_mask:0xf
	s_waitcnt lgkmcnt(0)
	s_nop 0
	v_pk_fma_f32 v[56:57], v[56:57], s[96:97], v[44:45] op_sel_hi:[1,0,0]
	s_nop 0
	v_mul_f32_e32 v62, 0x4b800000, v57
	v_cmp_gt_f32_e64 s[0:1], s77, v57
	v_cmp_gt_f32_e32 vcc, s77, v56
	s_nop 0
	v_cndmask_b32_e64 v57, v57, v62, s[0:1]
	v_rsq_f32_e32 v57, v57
	s_nop 0
	v_mul_f32_e32 v62, 0x45800000, v57
	v_cndmask_b32_e64 v62, v57, v62, s[0:1]
	v_pk_mul_f32 v[52:53], v[62:63], v[52:53] op_sel_hi:[0,1]
	v_pk_mul_f32 v[52:53], v[2:3], v[52:53]
	v_and_b32_e32 v57, 0xffff0000, v76
	v_pk_mul_f32 v[52:53], v[54:55], v[52:53]
	s_nop 0
	v_cvt_pk_bf16_f32 v52, v52, v53
	global_store_dword v[50:51], v52, off
	v_rsq_f32_e32 v50, v56
	v_mul_f32_e32 v53, 0xbfb8aa3b, v61
	v_exp_f32_e32 v53, v53
	v_lshlrev_b32_e32 v56, 16, v76
	v_mul_f32_e32 v51, 0xbfb8aa3b, v60
	v_exp_f32_e32 v51, v51
	v_add_f32_e32 v53, 1.0, v53
	v_rcp_f32_e32 v53, v53
	v_add_f32_e32 v51, 1.0, v51
	v_rcp_f32_e32 v52, v51
	v_pk_mul_f32 v[50:51], v[50:51], v[58:59] op_sel_hi:[0,1]
	v_pk_mul_f32 v[50:51], v[2:3], v[50:51]
	v_pk_mul_f32 v[52:53], v[52:53], v[60:61]
	s_nop 0
	v_pk_mul_f32 v[50:51], v[52:53], v[50:51]
	s_nop 0
	v_cvt_pk_bf16_f32 v50, v50, v51
	global_store_dword v[48:49], v50, off
	v_lshlrev_b32_e32 v50, 16, v78
	v_and_b32_e32 v51, 0xffff0000, v78
	v_mul_f32_e32 v54, 0xbfb8aa3b, v50
	v_mul_f32_e32 v55, 0xbfb8aa3b, v51
	v_exp_f32_e32 v54, v54
	v_exp_f32_e32 v55, v55
	s_waitcnt vmcnt(15)
	v_lshlrev_b32_e32 v48, 16, v77
	v_and_b32_e32 v49, 0xffff0000, v77
	v_add_f32_e32 v54, 1.0, v54
	v_add_f32_e32 v55, 1.0, v55
	v_rcp_f32_e32 v54, v54
	v_rcp_f32_e32 v55, v55
	v_pk_mul_f32 v[52:53], v[48:49], v[48:49]
	v_pk_mul_f32 v[50:51], v[54:55], v[50:51]
	s_waitcnt vmcnt(14)
	v_lshlrev_b32_e32 v54, 16, v75
	v_and_b32_e32 v55, 0xffff0000, v75
	v_pk_mul_f32 v[58:59], v[54:55], v[54:55]
	v_mov_b32_e32 v61, v52
	v_mov_b32_e32 v60, v58
	v_mov_b32_e32 v52, v59
	v_pk_add_f32 v[52:53], v[60:61], v[52:53]
	v_mov_b32_e32 v59, v53
	v_mov_b32_e32 v58, v52
	s_nop 0
	v_permlane32_swap_b32_e32 v59, v53
	v_permlane32_swap_b32_e32 v58, v52
	s_waitcnt lgkmcnt(0)
	v_pk_add_f32 v[52:53], v[52:53], v[58:59]
	v_mov_b32_e32 v59, v53
	v_mov_b32_e32 v58, v52
	s_nop 0
	v_permlane16_swap_b32_e32 v59, v53
	v_permlane16_swap_b32_e32 v58, v52
	s_waitcnt lgkmcnt(0)
	v_pk_add_f32 v[52:53], v[52:53], v[58:59]
	s_nop 1
	v_add_f32_dpp v53, v53, v53 row_ror:8 row_mask:0xf bank_mask:0xf
	v_add_f32_dpp v52, v52, v52 row_ror:8 row_mask:0xf bank_mask:0xf
	s_waitcnt lgkmcnt(0)
	s_nop 1
	v_add_f32_dpp v53, v53, v53 row_ror:4 row_mask:0xf bank_mask:0xf
	v_add_f32_dpp v52, v52, v52 row_ror:4 row_mask:0xf bank_mask:0xf
	s_waitcnt lgkmcnt(0)
	s_nop 1
	v_add_f32_dpp v53, v53, v53 quad_perm:[2,3,0,1] row_mask:0xf bank_mask:0xf
	v_add_f32_dpp v52, v52, v52 quad_perm:[2,3,0,1] row_mask:0xf bank_mask:0xf
	s_waitcnt lgkmcnt(0)
	s_nop 1
	v_add_f32_dpp v53, v53, v53 quad_perm:[1,0,3,2] row_mask:0xf bank_mask:0xf
	v_add_f32_dpp v52, v52, v52 quad_perm:[1,0,3,2] row_mask:0xf bank_mask:0xf
	s_waitcnt lgkmcnt(0)
	s_nop 0
	v_pk_fma_f32 v[52:53], v[52:53], s[96:97], v[44:45] op_sel_hi:[1,0,0]
	s_nop 0
	v_mul_f32_e32 v58, 0x4b800000, v53
	v_cmp_gt_f32_e64 s[0:1], s77, v53
	v_cmp_gt_f32_e32 vcc, s77, v52
	s_nop 0
	v_cndmask_b32_e64 v53, v53, v58, s[0:1]
	v_rsq_f32_e32 v53, v53
	s_nop 0
	v_mul_f32_e32 v58, 0x45800000, v53
	v_cndmask_b32_e64 v58, v53, v58, s[0:1]
	v_pk_mul_f32 v[48:49], v[58:59], v[48:49] op_sel_hi:[0,1]
	v_pk_mul_f32 v[48:49], v[2:3], v[48:49]
	v_and_b32_e32 v53, 0xffff0000, v72
	v_pk_mul_f32 v[48:49], v[50:51], v[48:49]
	s_nop 0
	v_cvt_pk_bf16_f32 v48, v48, v49
	global_store_dword v[46:47], v48, off
	v_rsq_f32_e32 v46, v52
	v_mul_f32_e32 v49, 0xbfb8aa3b, v57
	v_exp_f32_e32 v49, v49
	v_lshlrev_b32_e32 v52, 16, v72
	v_mul_f32_e32 v47, 0xbfb8aa3b, v56
	v_exp_f32_e32 v47, v47
	v_add_f32_e32 v49, 1.0, v49
	v_rcp_f32_e32 v49, v49
	v_add_f32_e32 v47, 1.0, v47
	v_rcp_f32_e32 v48, v47
	v_pk_mul_f32 v[46:47], v[46:47], v[54:55] op_sel_hi:[0,1]
	v_pk_mul_f32 v[46:47], v[2:3], v[46:47]
	v_pk_mul_f32 v[48:49], v[48:49], v[56:57]
	s_nop 0
	v_pk_mul_f32 v[46:47], v[48:49], v[46:47]
	s_nop 0
	v_cvt_pk_bf16_f32 v46, v46, v47
	global_store_dword v[42:43], v46, off
	v_lshlrev_b32_e32 v46, 16, v74
	v_and_b32_e32 v47, 0xffff0000, v74
	v_mul_f32_e32 v50, 0xbfb8aa3b, v46
	v_mul_f32_e32 v51, 0xbfb8aa3b, v47
	v_exp_f32_e32 v50, v50
	v_exp_f32_e32 v51, v51
	s_waitcnt vmcnt(15)
	v_lshlrev_b32_e32 v42, 16, v73
	v_and_b32_e32 v43, 0xffff0000, v73
	v_add_f32_e32 v50, 1.0, v50
	v_add_f32_e32 v51, 1.0, v51
	v_rcp_f32_e32 v50, v50
	v_rcp_f32_e32 v51, v51
	v_pk_mul_f32 v[48:49], v[42:43], v[42:43]
	v_pk_mul_f32 v[46:47], v[50:51], v[46:47]
	s_waitcnt vmcnt(14)
	v_lshlrev_b32_e32 v50, 16, v0
	v_and_b32_e32 v51, 0xffff0000, v0
	v_pk_mul_f32 v[54:55], v[50:51], v[50:51]
	v_mov_b32_e32 v57, v48
	v_mov_b32_e32 v56, v54
	v_mov_b32_e32 v48, v55
	v_pk_add_f32 v[48:49], v[56:57], v[48:49]
	v_mov_b32_e32 v55, v49
	v_mov_b32_e32 v54, v48
	s_nop 0
	v_permlane32_swap_b32_e32 v55, v49
	v_permlane32_swap_b32_e32 v54, v48
	s_waitcnt lgkmcnt(0)
	v_pk_add_f32 v[48:49], v[48:49], v[54:55]
	v_mov_b32_e32 v55, v49
	v_mov_b32_e32 v54, v48
	s_nop 0
	v_permlane16_swap_b32_e32 v55, v49
	v_permlane16_swap_b32_e32 v54, v48
	s_waitcnt lgkmcnt(0)
	v_pk_add_f32 v[48:49], v[48:49], v[54:55]
	s_nop 1
	v_add_f32_dpp v49, v49, v49 row_ror:8 row_mask:0xf bank_mask:0xf
	v_add_f32_dpp v48, v48, v48 row_ror:8 row_mask:0xf bank_mask:0xf
	s_waitcnt lgkmcnt(0)
	s_nop 1
	v_add_f32_dpp v49, v49, v49 row_ror:4 row_mask:0xf bank_mask:0xf
	v_add_f32_dpp v48, v48, v48 row_ror:4 row_mask:0xf bank_mask:0xf
	s_waitcnt lgkmcnt(0)
	s_nop 1
	v_add_f32_dpp v49, v49, v49 quad_perm:[2,3,0,1] row_mask:0xf bank_mask:0xf
	v_add_f32_dpp v48, v48, v48 quad_perm:[2,3,0,1] row_mask:0xf bank_mask:0xf
	s_waitcnt lgkmcnt(0)
	s_nop 1
	v_add_f32_dpp v49, v49, v49 quad_perm:[1,0,3,2] row_mask:0xf bank_mask:0xf
	v_add_f32_dpp v48, v48, v48 quad_perm:[1,0,3,2] row_mask:0xf bank_mask:0xf
	s_waitcnt lgkmcnt(0)
	s_nop 0
	v_pk_fma_f32 v[44:45], v[48:49], s[96:97], v[44:45] op_sel_hi:[1,0,0]
	s_nop 0
	v_cmp_gt_f32_e64 s[0:1], s77, v45
	v_cmp_gt_f32_e32 vcc, s77, v44
	s_nop 0
	v_rsq_f32_e32 v0, v45
	s_nop 0
	v_pk_mul_f32 v[42:43], v[0:1], v[42:43] op_sel_hi:[0,1]
	v_pk_mul_f32 v[42:43], v[2:3], v[42:43]
	s_nop 0
	v_pk_mul_f32 v[42:43], v[46:47], v[42:43]
	s_nop 0
	v_cvt_pk_bf16_f32 v0, v42, v43
	global_store_dword v[40:41], v0, off
	v_rsq_f32_e32 v0, v44
	s_nop 0
	v_mul_f32_e32 v40, 0xbfb8aa3b, v52
	v_pk_mul_f32 v[42:43], v[0:1], v[50:51] op_sel_hi:[0,1]
	v_mul_f32_e32 v0, 0xbfb8aa3b, v53
	v_exp_f32_e32 v40, v40
	v_exp_f32_e32 v0, v0
	v_pk_mul_f32 v[42:43], v[2:3], v[42:43]
	v_add_f32_e32 v40, 1.0, v40
	v_add_f32_e32 v0, 1.0, v0
	v_rcp_f32_e32 v40, v40
	v_rcp_f32_e32 v41, v0
	s_nop 0
	v_pk_mul_f32 v[40:41], v[40:41], v[52:53]
	s_nop 0
	v_pk_mul_f32 v[40:41], v[40:41], v[42:43]
	s_nop 0
	v_cvt_pk_bf16_f32 v0, v40, v41
	global_store_dword v[38:39], v0, off
	s_branch .LBB0_313

; DI bf16_t f2bf(float f) { unsigned u = __float_as_uint(f); u += 0x7fffu + ((u >> 16) & 1u); return (bf16_t)(u >> 16); }
; DI float wave_sum(float v) { for (int o = 32; o; o >>= 1) v += __shfl_xor(v, o); return v; }
; DI void run_phase(const Params& p, int ph, unsigned char* smem, const int tid, const int rep) {
;     ...
;             for (int u = 0; u < 2; ++u) { const int t = t0 + u;
;                 const float ang = (float)ps[u] * invf; float sn, cs; sincosf(ang, &sn, &cs);
;                 const float kr = krv[u];
; #pragma unroll
;                 for (int h = 0; h < 4; ++h) {
;                     { const float a0 = qa[u][h][0], a1 = qa[u][h][1], a2 = qa[u][h][2];
;                       const float rs = rsqrtf(wave_sum(a0 * a0 + a1 * a1 + a2 * a2) * (1.f / 192.f) + NEPS) * (0.07216878364870322f * LOG2E);
;                       const float y2 = a2 * rs * gq2; const float oth = __shfl_xor(y2, 32);
;                       const float rot = (lane < 32) ? (y2 * cs - oth * sn) : (y2 * cs + oth * sn);
;                       bf16_t* qo = mlaq + (size_t)t * 768 + h * 192; qo[lane] = f2bf(a0 * rs * gq0); qo[lane + 64] = f2bf(a1 * rs * gq1); qo[lane + 128] = f2bf(rot); }
;                     { const float a0 = ka[u][h][0], a1 = ka[u][h][1];
;                       const float rs = rsqrtf(wave_sum(a0 * a0 + a1 * a1 + kr * kr) * (1.f / 192.f) + NEPS);
;                       const float y2 = kr * rs * gk2; const float oth = __shfl_xor(y2, 32);
;                       const float rot = (lane < 32) ? (y2 * cs - oth * sn) : (y2 * cs + oth * sn);
;                       bf16_t* ko = mlak + (size_t)t * 768 + h * 192; ko[lane] = f2bf(a0 * rs * gk0); ko[lane + 64] = f2bf(a1 * rs * gk1); ko[lane + 128] = f2bf(rot); }
.LBB0_331:
	s_or_b64 exec, exec, s[0:1]
	v_mul_f32_e32 v26, v24, v24
	v_fmamk_f32 v27, v26, 0xb94c1982, v249
	v_fmaak_f32 v27, v26, v27, 0xbe2aaa9d
	v_mul_f32_e32 v27, v26, v27
	v_fmac_f32_e32 v24, v24, v27
	v_fmamk_f32 v27, v26, 0x37d75334, v223
	v_fmaak_f32 v27, v26, v27, 0x3d2aabf7
	v_fmaak_f32 v27, v26, v27, 0xbf000004
	v_fma_f32 v26, v26, v27, 1.0
	v_lshlrev_b32_e32 v27, 30, v25
	v_and_b32_e32 v25, 1, v25
	v_cmp_eq_u32_e32 vcc, 0, v25
	s_brev_b32 s0, 1
	s_waitcnt vmcnt(41)
	v_lshlrev_b32_e32 v19, 16, v58
	v_cndmask_b32_e32 v25, v26, v24, vcc
	v_xor_b32_e32 v24, 0x80000000, v24
	v_cndmask_b32_e32 v24, v24, v26, vcc
	v_lshlrev_b32_e32 v18, 16, v51
	s_waitcnt vmcnt(39)
	v_lshlrev_b32_e32 v33, 16, v53
	v_lshlrev_b32_e32 v32, 16, v50
	v_xor_b32_e32 v17, v17, v16
	v_bitop3_b32 v24, v24, v27, s0 bitop3:0x78
	s_movk_i32 s0, 0x1f8
	v_lshlrev_b32_e32 v70, 16, v57
	s_waitcnt vmcnt(38)
	v_lshlrev_b32_e32 v30, 16, v55
	s_waitcnt vmcnt(35)
	v_lshlrev_b32_e32 v28, 16, v54
	s_waitcnt vmcnt(25)
	v_lshlrev_b32_e32 v13, 16, v61
	v_lshlrev_b32_e32 v12, 16, v49
	v_and_b32_e32 v34, 0x80000000, v27
	v_xor_b32_e32 v17, v17, v25
	v_cmp_class_f32_e64 vcc, v16, s0
	v_pk_mul_f32 v[26:27], v[18:19], v[18:19]
	v_pk_mul_f32 v[54:55], v[32:33], v[32:33]
	v_lshlrev_b32_e32 v11, 16, v52
	s_waitcnt vmcnt(24)
	v_lshlrev_b32_e32 v10, 16, v56
	v_xor_b32_e32 v17, v17, v34
	v_cndmask_b32_e32 v34, v224, v24, vcc
	v_pk_mul_f32 v[24:25], v[12:13], v[12:13]
	v_mul_f32_e32 v53, v70, v70
	v_mov_b32_e32 v56, v54
	v_mov_b32_e32 v57, v26
	v_mov_b32_e32 v52, v55
	v_pk_add_f32 v[52:53], v[56:57], v[52:53]
	v_mov_b32_e32 v26, v24
	v_pk_add_f32 v[26:27], v[26:27], v[52:53]
	v_mov_b32_e32 v53, v27
	v_mov_b32_e32 v52, v26
	s_nop 0
	v_permlane32_swap_b32_e32 v53, v27
	v_permlane32_swap_b32_e32 v52, v26
	s_mov_b32 s4, 0x3baaaaab
	v_cndmask_b32_e32 v35, v224, v17, vcc
	v_mad_i64_i32 v[16:17], s[0:1], v3, s7, v[6:7]
	s_waitcnt lgkmcnt(0)
	v_pk_add_f32 v[26:27], v[26:27], v[52:53]
	v_mov_b32_e32 v53, v27
	v_mov_b32_e32 v52, v26
	s_nop 0
	v_permlane16_swap_b32_e32 v53, v27
	v_permlane16_swap_b32_e32 v52, v26
	v_lshlrev_b32_e32 v31, 16, v63
	v_lshlrev_b32_e32 v29, 16, v59
	v_lshlrev_b32_e32 v51, 16, v62
	v_pk_mul_f32 v[54:55], v[28:29], v[28:29]
	s_waitcnt lgkmcnt(0)
	v_pk_add_f32 v[26:27], v[26:27], v[52:53]
	s_nop 1
	v_mov_b32_dpp v53, v27 row_ror:8 row_mask:0xf bank_mask:0xf
	v_mov_b32_dpp v52, v26 row_ror:8 row_mask:0xf bank_mask:0xf
	v_mov_b32_e32 v56, v54
	v_lshlrev_b32_e32 v23, 16, v66
	v_lshlrev_b32_e32 v22, 16, v60
	v_lshlrev_b32_e32 v21, 16, v67
	s_waitcnt lgkmcnt(0)
	v_pk_add_f32 v[26:27], v[26:27], v[52:53]
	s_nop 1
	v_mov_b32_dpp v53, v27 row_shl:4 row_mask:0xf bank_mask:0x5
	v_mov_b32_dpp v53, v27 row_shr:4 row_mask:0xf bank_mask:0xa
	v_mov_b32_dpp v52, v26 row_shl:4 row_mask:0xf bank_mask:0x5
	v_mov_b32_dpp v52, v26 row_shr:4 row_mask:0xf bank_mask:0xa
	v_lshlrev_b32_e32 v20, 16, v64
	v_lshlrev_b32_e32 v50, 16, v65
	v_lshlrev_b32_e32 v15, 16, v69
	v_lshlrev_b32_e32 v14, 16, v68
	s_waitcnt lgkmcnt(0)
	v_pk_add_f32 v[26:27], v[26:27], v[52:53]
	s_nop 1
	v_mov_b32_dpp v53, v27 quad_perm:[2,3,0,1] row_mask:0xf bank_mask:0xf
	v_mov_b32_dpp v52, v26 quad_perm:[2,3,0,1] row_mask:0xf bank_mask:0xf
	v_add_u32_e32 v2, s17, v2
	s_waitcnt lgkmcnt(0)
	v_pk_add_f32 v[26:27], v[26:27], v[52:53]
	s_nop 1
	v_add_f32_dpp v53, v27, v27 quad_perm:[1,0,3,2] row_mask:0xf bank_mask:0xf
	v_add_f32_dpp v52, v26, v26 quad_perm:[1,0,3,2] row_mask:0xf bank_mask:0xf
	s_waitcnt lgkmcnt(0)
	v_mov_b64_e32 v[26:27], s[72:73]
	v_pk_fma_f32 v[52:53], v[52:53], s[4:5], v[26:27] op_sel_hi:[1,0,0]
	s_nop 0
	v_cmp_gt_f32_e64 s[0:1], s77, v53
	v_cmp_gt_f32_e32 vcc, s77, v52
	s_nop 0
	v_rsq_f32_e32 v49, v53
	s_nop 0
	v_mul_f32_e32 v49, 0x3dd53b94, v49
	v_mul_f32_e32 v19, v49, v19
	v_mul_f32_e32 v19, v41, v19
	ds_bpermute_b32 v53, v43, v19
	v_mul_f32_e32 v18, v49, v18
	v_mul_f32_e32 v18, v36, v18
	s_waitcnt lgkmcnt(0)
	v_mul_f32_e32 v53, v35, v53
	v_cndmask_b32_e64 v53, v53, -v53, s[38:39]
	v_fmac_f32_e32 v53, v34, v19
	v_bfe_u32 v19, v18, 16, 1
	v_add3_u32 v18, v18, v19, s11
	global_store_short_d16_hi v[16:17], v18, off
	v_mul_f32_e32 v18, v49, v70
	v_mul_f32_e32 v18, v37, v18
	v_bfe_u32 v19, v18, 16, 1
	v_add3_u32 v18, v18, v19, s11
	global_store_short_d16_hi v[16:17], v18, off offset:128
	v_bfe_u32 v18, v53, 16, 1
	v_add3_u32 v18, v53, v18, s11
	global_store_short_d16_hi v[16:17], v18, off offset:256
	v_rsq_f32_e32 v18, v52
	v_mul_f32_e32 v53, v51, v51
	v_mov_b32_e32 v49, v18
	v_mul_f32_e32 v18, v49, v12
	v_mul_f32_e32 v18, v40, v18
	ds_bpermute_b32 v19, v43, v18
	s_waitcnt lgkmcnt(0)
	v_mul_f32_e32 v19, v35, v19
	v_cndmask_b32_e64 v52, v19, -v19, s[38:39]
	v_fmac_f32_e32 v52, v34, v18
	v_mul_f32_e32 v18, v49, v32
	v_mul_f32_e32 v18, v38, v18
	v_bfe_u32 v19, v18, 16, 1
	v_add3_u32 v32, v18, v19, s11
	v_mad_i64_i32 v[18:19], s[0:1], v3, s7, v[8:9]
	v_mul_f32_e32 v3, v49, v33
	v_mul_f32_e32 v3, v39, v3
	global_store_short_d16_hi v[18:19], v32, off
	v_bfe_u32 v32, v3, 16, 1
	v_add3_u32 v3, v3, v32, s11
	global_store_short_d16_hi v[18:19], v3, off offset:128
	v_bfe_u32 v3, v52, 16, 1
	v_pk_mul_f32 v[32:33], v[30:31], v[30:31]
	v_add3_u32 v3, v52, v3, s11
	v_mov_b32_e32 v57, v32
	v_mov_b32_e32 v52, v55
	v_pk_add_f32 v[52:53], v[56:57], v[52:53]
	v_mov_b32_e32 v32, v24
	v_pk_add_f32 v[32:33], v[32:33], v[52:53]
	v_mov_b32_e32 v53, v33
	v_mov_b32_e32 v52, v32
	s_nop 0
	v_permlane32_swap_b32_e32 v53, v33
	v_permlane32_swap_b32_e32 v52, v32
	global_store_short_d16_hi v[18:19], v3, off offset:256
	s_waitcnt lgkmcnt(0)
	v_pk_add_f32 v[32:33], v[32:33], v[52:53]
	v_mov_b32_e32 v53, v33
	v_mov_b32_e32 v52, v32
	s_nop 0
	v_permlane16_swap_b32_e32 v53, v33
	v_permlane16_swap_b32_e32 v52, v32
	s_waitcnt lgkmcnt(0)
; DI bf16_t f2bf(float f) { unsigned u = __float_as_uint(f); u += 0x7fffu + ((u >> 16) & 1u); return (bf16_t)(u >> 16); }
; DI float wave_sum(float v) { for (int o = 32; o; o >>= 1) v += __shfl_xor(v, o); return v; }
; DI void run_phase(const Params& p, int ph, unsigned char* smem, const int tid, const int rep) {
;     ...
;             for (int u = 0; u < 2; ++u) { const int t = t0 + u;
;                 const float ang = (float)ps[u] * invf; float sn, cs; sincosf(ang, &sn, &cs);
;                 const float kr = krv[u];
; #pragma unroll
;                 for (int h = 0; h < 4; ++h) {
;                     { const float a0 = qa[u][h][0], a1 = qa[u][h][1], a2 = qa[u][h][2];
;                       const float rs = rsqrtf(wave_sum(a0 * a0 + a1 * a1 + a2 * a2) * (1.f / 192.f) + NEPS) * (0.07216878364870322f * LOG2E);
;                       const float y2 = a2 * rs * gq2; const float oth = __shfl_xor(y2, 32);
;                       const float rot = (lane < 32) ? (y2 * cs - oth * sn) : (y2 * cs + oth * sn);
;                       bf16_t* qo = mlaq + (size_t)t * 768 + h * 192; qo[lane] = f2bf(a0 * rs * gq0); qo[lane + 64] = f2bf(a1 * rs * gq1); qo[lane + 128] = f2bf(rot); }
;                     { const float a0 = ka[u][h][0], a1 = ka[u][h][1];
;                       const float rs = rsqrtf(wave_sum(a0 * a0 + a1 * a1 + kr * kr) * (1.f / 192.f) + NEPS);
;                       const float y2 = kr * rs * gk2; const float oth = __shfl_xor(y2, 32);
;                       const float rot = (lane < 32) ? (y2 * cs - oth * sn) : (y2 * cs + oth * sn);
;                       bf16_t* ko = mlak + (size_t)t * 768 + h * 192; ko[lane] = f2bf(a0 * rs * gk0); ko[lane + 64] = f2bf(a1 * rs * gk1); ko[lane + 128] = f2bf(rot); }
	v_pk_add_f32 v[32:33], v[32:33], v[52:53]
	s_nop 1
	v_add_f32_dpp v33, v33, v33 row_ror:8 row_mask:0xf bank_mask:0xf
	v_add_f32_dpp v32, v32, v32 row_ror:8 row_mask:0xf bank_mask:0xf
	s_waitcnt lgkmcnt(0)
	s_nop 1
	v_add_f32_dpp v33, v33, v33 row_ror:4 row_mask:0xf bank_mask:0xf
	v_add_f32_dpp v32, v32, v32 row_ror:4 row_mask:0xf bank_mask:0xf
	s_waitcnt lgkmcnt(0)
	s_nop 1
	v_add_f32_dpp v33, v33, v33 quad_perm:[2,3,0,1] row_mask:0xf bank_mask:0xf
	v_add_f32_dpp v32, v32, v32 quad_perm:[2,3,0,1] row_mask:0xf bank_mask:0xf
	s_waitcnt lgkmcnt(0)
	s_nop 1
	v_add_f32_dpp v33, v33, v33 quad_perm:[1,0,3,2] row_mask:0xf bank_mask:0xf
	v_add_f32_dpp v32, v32, v32 quad_perm:[1,0,3,2] row_mask:0xf bank_mask:0xf
	s_waitcnt lgkmcnt(0)
	s_nop 0
	v_pk_fma_f32 v[32:33], v[32:33], s[4:5], v[26:27] op_sel_hi:[1,0,0]
	s_nop 0
	v_cmp_gt_f32_e64 s[0:1], s77, v33
	v_cmp_gt_f32_e32 vcc, s77, v32
	s_nop 0
	v_rsq_f32_e32 v3, v33
	s_nop 0
	v_mul_f32_e32 v3, 0x3dd53b94, v3
	v_mul_f32_e32 v31, v3, v31
	v_mul_f32_e32 v31, v41, v31
	ds_bpermute_b32 v33, v43, v31
	v_mul_f32_e32 v30, v3, v30
	v_mul_f32_e32 v30, v36, v30
	v_mul_f32_e32 v3, v3, v51
	v_mul_f32_e32 v3, v37, v3
	s_waitcnt lgkmcnt(0)
	v_mul_f32_e32 v33, v35, v33
	v_cndmask_b32_e64 v33, v33, -v33, s[38:39]
	v_fmac_f32_e32 v33, v34, v31
	v_bfe_u32 v31, v30, 16, 1
	v_add3_u32 v30, v30, v31, s11
	global_store_short_d16_hi v[16:17], v30, off offset:384
	v_bfe_u32 v30, v3, 16, 1
	v_add3_u32 v3, v3, v30, s11
	global_store_short_d16_hi v[16:17], v3, off offset:512
	v_bfe_u32 v3, v33, 16, 1
	v_add3_u32 v3, v33, v3, s11
	global_store_short_d16_hi v[16:17], v3, off offset:640
	v_rsq_f32_e32 v3, v32
	v_pk_mul_f32 v[32:33], v[20:21], v[20:21]
	v_mul_f32_e32 v30, v3, v12
	v_mul_f32_e32 v30, v40, v30
	ds_bpermute_b32 v31, v43, v30
	v_mul_f32_e32 v28, v3, v28
	v_mul_f32_e32 v28, v38, v28
	v_mul_f32_e32 v3, v3, v29
	v_mul_f32_e32 v3, v39, v3
	s_waitcnt lgkmcnt(0)
	v_mul_f32_e32 v31, v35, v31
	v_cndmask_b32_e64 v31, v31, -v31, s[38:39]
	v_fmac_f32_e32 v31, v34, v30
	v_bfe_u32 v30, v28, 16, 1
	v_add3_u32 v28, v28, v30, s11
	global_store_short_d16_hi v[18:19], v28, off offset:384
	v_bfe_u32 v28, v3, 16, 1
	v_add3_u32 v3, v3, v28, s11
	global_store_short_d16_hi v[18:19], v3, off offset:512
	v_bfe_u32 v3, v31, 16, 1
	v_pk_mul_f32 v[28:29], v[22:23], v[22:23]
	v_add3_u32 v3, v31, v3, s11
	v_mul_f32_e32 v31, v50, v50
	v_mov_b32_e32 v52, v32
	v_mov_b32_e32 v53, v28
	v_mov_b32_e32 v30, v33
	v_pk_add_f32 v[30:31], v[52:53], v[30:31]
	v_mov_b32_e32 v28, v24
	v_pk_add_f32 v[28:29], v[28:29], v[30:31]
	v_mov_b32_e32 v31, v29
	v_mov_b32_e32 v30, v28
	s_nop 0
	v_permlane32_swap_b32_e32 v31, v29
	v_permlane32_swap_b32_e32 v30, v28
	global_store_short_d16_hi v[18:19], v3, off offset:640
	s_waitcnt lgkmcnt(0)
	v_pk_add_f32 v[28:29], v[28:29], v[30:31]
	v_mov_b32_e32 v31, v29
	v_mov_b32_e32 v30, v28
	s_nop 0
	v_permlane16_swap_b32_e32 v31, v29
	v_permlane16_swap_b32_e32 v30, v28
	s_waitcnt lgkmcnt(0)
	v_pk_add_f32 v[28:29], v[28:29], v[30:31]
	s_nop 1
	v_add_f32_dpp v29, v29, v29 row_ror:8 row_mask:0xf bank_mask:0xf
	v_add_f32_dpp v28, v28, v28 row_ror:8 row_mask:0xf bank_mask:0xf
	s_waitcnt lgkmcnt(0)
	s_nop 1
	v_add_f32_dpp v29, v29, v29 row_ror:4 row_mask:0xf bank_mask:0xf
	v_add_f32_dpp v28, v28, v28 row_ror:4 row_mask:0xf bank_mask:0xf
	s_waitcnt lgkmcnt(0)
	s_nop 1
	v_add_f32_dpp v29, v29, v29 quad_perm:[2,3,0,1] row_mask:0xf bank_mask:0xf
	v_add_f32_dpp v28, v28, v28 quad_perm:[2,3,0,1] row_mask:0xf bank_mask:0xf
	s_waitcnt lgkmcnt(0)
	s_nop 1
	v_add_f32_dpp v29, v29, v29 quad_perm:[1,0,3,2] row_mask:0xf bank_mask:0xf
	v_add_f32_dpp v28, v28, v28 quad_perm:[1,0,3,2] row_mask:0xf bank_mask:0xf
	s_waitcnt lgkmcnt(0)
	s_nop 0
	v_pk_fma_f32 v[28:29], v[28:29], s[4:5], v[26:27] op_sel_hi:[1,0,0]
	s_nop 0
	v_cmp_gt_f32_e64 s[0:1], s77, v29
	v_cmp_gt_f32_e32 vcc, s77, v28
	s_nop 0
	v_rsq_f32_e32 v3, v29
	s_nop 0
	v_mul_f32_e32 v3, 0x3dd53b94, v3
	v_mul_f32_e32 v23, v3, v23
	v_mul_f32_e32 v23, v41, v23
	ds_bpermute_b32 v29, v43, v23
	v_mul_f32_e32 v22, v3, v22
	v_mul_f32_e32 v22, v36, v22
	v_mul_f32_e32 v3, v3, v50
	v_mul_f32_e32 v3, v37, v3
	s_waitcnt lgkmcnt(0)
; DI bf16_t f2bf(float f) { unsigned u = __float_as_uint(f); u += 0x7fffu + ((u >> 16) & 1u); return (bf16_t)(u >> 16); }
; DI float wave_sum(float v) { for (int o = 32; o; o >>= 1) v += __shfl_xor(v, o); return v; }
; DI void run_phase(const Params& p, int ph, unsigned char* smem, const int tid, const int rep) {
;     ...
;             for (int u = 0; u < 2; ++u) { const int t = t0 + u;
;                 const float ang = (float)ps[u] * invf; float sn, cs; sincosf(ang, &sn, &cs);
;                 const float kr = krv[u];
; #pragma unroll
;                 for (int h = 0; h < 4; ++h) {
;                     { const float a0 = qa[u][h][0], a1 = qa[u][h][1], a2 = qa[u][h][2];
;                       const float rs = rsqrtf(wave_sum(a0 * a0 + a1 * a1 + a2 * a2) * (1.f / 192.f) + NEPS) * (0.07216878364870322f * LOG2E);
;                       const float y2 = a2 * rs * gq2; const float oth = __shfl_xor(y2, 32);
;                       const float rot = (lane < 32) ? (y2 * cs - oth * sn) : (y2 * cs + oth * sn);
;                       bf16_t* qo = mlaq + (size_t)t * 768 + h * 192; qo[lane] = f2bf(a0 * rs * gq0); qo[lane + 64] = f2bf(a1 * rs * gq1); qo[lane + 128] = f2bf(rot); }
;                     { const float a0 = ka[u][h][0], a1 = ka[u][h][1];
;                       const float rs = rsqrtf(wave_sum(a0 * a0 + a1 * a1 + kr * kr) * (1.f / 192.f) + NEPS);
;                       const float y2 = kr * rs * gk2; const float oth = __shfl_xor(y2, 32);
;                       const float rot = (lane < 32) ? (y2 * cs - oth * sn) : (y2 * cs + oth * sn);
;                       bf16_t* ko = mlak + (size_t)t * 768 + h * 192; ko[lane] = f2bf(a0 * rs * gk0); ko[lane + 64] = f2bf(a1 * rs * gk1); ko[lane + 128] = f2bf(rot); }
	v_mul_f32_e32 v29, v35, v29
	v_cndmask_b32_e64 v29, v29, -v29, s[38:39]
	v_fmac_f32_e32 v29, v34, v23
	v_bfe_u32 v23, v22, 16, 1
	v_add3_u32 v22, v22, v23, s11
	global_store_short_d16_hi v[16:17], v22, off offset:768
	v_bfe_u32 v22, v3, 16, 1
	v_add3_u32 v3, v3, v22, s11
	global_store_short_d16_hi v[16:17], v3, off offset:896
	v_bfe_u32 v3, v29, 16, 1
	v_add3_u32 v3, v29, v3, s11
	global_store_short_d16_hi v[16:17], v3, off offset:1024
	v_rsq_f32_e32 v3, v28
	s_nop 0
	v_mul_f32_e32 v22, v3, v12
	v_mul_f32_e32 v22, v40, v22
	ds_bpermute_b32 v23, v43, v22
	v_mul_f32_e32 v20, v3, v20
	v_mul_f32_e32 v20, v38, v20
	v_mul_f32_e32 v3, v3, v21
	v_mul_f32_e32 v3, v39, v3
	s_waitcnt lgkmcnt(0)
	v_mul_f32_e32 v23, v35, v23
	v_cndmask_b32_e64 v23, v23, -v23, s[38:39]
	v_fmac_f32_e32 v23, v34, v22
	v_bfe_u32 v22, v20, 16, 1
	v_add3_u32 v20, v20, v22, s11
	global_store_short_d16_hi v[18:19], v20, off offset:768
	v_bfe_u32 v20, v3, 16, 1
	v_add3_u32 v3, v3, v20, s11
	global_store_short_d16_hi v[18:19], v3, off offset:896
	v_bfe_u32 v3, v23, 16, 1
	v_pk_mul_f32 v[20:21], v[14:15], v[14:15]
	v_add3_u32 v3, v23, v3, s11
	v_pk_mov_b32 v[22:23], v[24:25], v[20:21] op_sel:[1,0]
	v_mov_b32_e32 v25, v21
	v_pk_fma_f32 v[22:23], v[10:11], v[10:11], v[22:23]
	global_store_short_d16_hi v[18:19], v3, off offset:1024
	v_pk_add_f32 v[20:21], v[24:25], v[22:23]
	v_mov_b32_e32 v23, v21
	v_mov_b32_e32 v22, v20
	s_nop 0
	v_permlane32_swap_b32_e32 v23, v21
	v_permlane32_swap_b32_e32 v22, v20
	s_waitcnt lgkmcnt(0)
	v_pk_add_f32 v[20:21], v[20:21], v[22:23]
	v_mov_b32_e32 v23, v21
	v_mov_b32_e32 v22, v20
	s_nop 0
	v_permlane16_swap_b32_e32 v23, v21
	v_permlane16_swap_b32_e32 v22, v20
	s_waitcnt lgkmcnt(0)
	v_pk_add_f32 v[20:21], v[20:21], v[22:23]
	s_nop 1
	v_add_f32_dpp v21, v21, v21 row_ror:8 row_mask:0xf bank_mask:0xf
	v_add_f32_dpp v20, v20, v20 row_ror:8 row_mask:0xf bank_mask:0xf
	s_waitcnt lgkmcnt(0)
	s_nop 1
	v_add_f32_dpp v21, v21, v21 row_ror:4 row_mask:0xf bank_mask:0xf
	v_add_f32_dpp v20, v20, v20 row_ror:4 row_mask:0xf bank_mask:0xf
	s_waitcnt lgkmcnt(0)
	s_nop 1
	v_add_f32_dpp v21, v21, v21 quad_perm:[2,3,0,1] row_mask:0xf bank_mask:0xf
	v_add_f32_dpp v20, v20, v20 quad_perm:[2,3,0,1] row_mask:0xf bank_mask:0xf
	s_waitcnt lgkmcnt(0)
	s_nop 1
	v_add_f32_dpp v21, v21, v21 quad_perm:[1,0,3,2] row_mask:0xf bank_mask:0xf
	v_add_f32_dpp v20, v20, v20 quad_perm:[1,0,3,2] row_mask:0xf bank_mask:0xf
	s_waitcnt lgkmcnt(0)
	s_nop 0
	v_pk_fma_f32 v[20:21], v[20:21], s[4:5], v[26:27] op_sel_hi:[1,0,0]
	s_nop 0
	v_cmp_gt_f32_e64 s[0:1], s77, v21
	v_cmp_gt_f32_e32 vcc, s77, v20
	s_nop 0
	v_rsq_f32_e32 v3, v21
	s_nop 0
	v_mul_f32_e32 v3, 0x3dd53b94, v3
	v_mul_f32_e32 v15, v3, v15
	v_mul_f32_e32 v15, v41, v15
	ds_bpermute_b32 v21, v43, v15
	v_mul_f32_e32 v14, v3, v14
	v_mul_f32_e32 v3, v3, v11
	v_mul_f32_e32 v3, v37, v3
	v_bfe_u32 v11, v3, 16, 1
	s_waitcnt lgkmcnt(0)
	v_mul_f32_e32 v21, v35, v21
	v_cndmask_b32_e64 v21, v21, -v21, s[38:39]
	v_fmac_f32_e32 v21, v34, v15
	v_add3_u32 v3, v3, v11, s11
	global_store_short_d16_hi v[16:17], v3, off offset:1280
	v_bfe_u32 v3, v21, 16, 1
	v_add3_u32 v3, v21, v3, s11
	global_store_short_d16_hi v[16:17], v3, off offset:1408
	v_rsq_f32_e32 v3, v20
	v_mul_f32_e32 v14, v36, v14
	v_bfe_u32 v15, v14, 16, 1
	v_add3_u32 v14, v14, v15, s11
	v_mul_f32_e32 v11, v3, v12
	v_mul_f32_e32 v11, v40, v11
	ds_bpermute_b32 v12, v43, v11
	v_cmp_lt_i32_e32 vcc, s11, v2
	s_or_b64 s[34:35], vcc, s[34:35]
	global_store_short_d16_hi v[16:17], v14, off offset:1152
	s_waitcnt lgkmcnt(0)
	v_mul_f32_e32 v12, v35, v12
	v_cndmask_b32_e64 v12, v12, -v12, s[38:39]
	v_fmac_f32_e32 v12, v34, v11
	v_mul_f32_e32 v11, v3, v13
	v_mul_f32_e32 v3, v3, v10
	v_mul_f32_e32 v3, v39, v3
	v_bfe_u32 v10, v3, 16, 1
	v_mul_f32_e32 v11, v38, v11
	v_add3_u32 v3, v3, v10, s11
	v_bfe_u32 v13, v11, 16, 1
	global_store_short_d16_hi v[18:19], v3, off offset:1280
	v_bfe_u32 v3, v12, 16, 1
	v_add3_u32 v11, v11, v13, s11
	v_add3_u32 v3, v12, v3, s11
	global_store_short_d16_hi v[18:19], v11, off offset:1152
	global_store_short_d16_hi v[18:19], v3, off offset:1408
	s_andn2_b64 exec, exec, s[34:35]
	s_cbranch_execz .LBB0_340

; DI bf16_t f2bf(float f) { unsigned u = __float_as_uint(f); u += 0x7fffu + ((u >> 16) & 1u); return (bf16_t)(u >> 16); }
; DI float wave_sum(float v) { for (int o = 32; o; o >>= 1) v += __shfl_xor(v, o); return v; }
; DI void run_phase(const Params& p, int ph, unsigned char* smem, const int tid, const int rep) {
;     ...
;             for (int u = 0; u < 2; ++u) { const int t = t0 + u;
;                 const float ang = (float)ps[u] * invf; float sn, cs; sincosf(ang, &sn, &cs);
;                 const float kr = krv[u];
; #pragma unroll
;                 for (int h = 0; h < 4; ++h) {
;                     { const float a0 = qa[u][h][0], a1 = qa[u][h][1], a2 = qa[u][h][2];
;                       const float rs = rsqrtf(wave_sum(a0 * a0 + a1 * a1 + a2 * a2) * (1.f / 192.f) + NEPS) * (0.07216878364870322f * LOG2E);
;                       const float y2 = a2 * rs * gq2; const float oth = __shfl_xor(y2, 32);
;                       const float rot = (lane < 32) ? (y2 * cs - oth * sn) : (y2 * cs + oth * sn);
;                       bf16_t* qo = mlaq + (size_t)t * 768 + h * 192; qo[lane] = f2bf(a0 * rs * gq0); qo[lane + 64] = f2bf(a1 * rs * gq1); qo[lane + 128] = f2bf(rot); }
;                     { const float a0 = ka[u][h][0], a1 = ka[u][h][1];
;                       const float rs = rsqrtf(wave_sum(a0 * a0 + a1 * a1 + kr * kr) * (1.f / 192.f) + NEPS);
;                       const float y2 = kr * rs * gk2; const float oth = __shfl_xor(y2, 32);
;                       const float rot = (lane < 32) ? (y2 * cs - oth * sn) : (y2 * cs + oth * sn);
;                       bf16_t* ko = mlak + (size_t)t * 768 + h * 192; ko[lane] = f2bf(a0 * rs * gk0); ko[lane + 64] = f2bf(a1 * rs * gk1); ko[lane + 128] = f2bf(rot); }
.LBB0_336:
	s_or_b64 exec, exec, s[0:1]
	s_waitcnt vmcnt(40)
	v_lshlrev_b32_e32 v20, 16, v15
	s_waitcnt vmcnt(22)
	v_lshlrev_b32_e32 v15, 16, v14
	v_lshlrev_b32_e32 v14, 16, v12
	s_waitcnt vmcnt(21)
	v_lshlrev_b32_e32 v12, 16, v18
	v_mul_f32_e32 v18, v78, v78
	v_lshlrev_b32_e32 v32, 16, v19
	v_fmamk_f32 v19, v18, 0xb94c1982, v249
	v_fmaak_f32 v19, v18, v19, 0xbe2aaa9d
	v_mul_f32_e32 v19, v18, v19
	v_fmac_f32_e32 v78, v78, v19
	v_fmamk_f32 v19, v18, 0x37d75334, v223
	v_fmaak_f32 v19, v18, v19, 0x3d2aabf7
	v_lshlrev_b32_e32 v30, 16, v27
	v_fmaak_f32 v19, v18, v19, 0xbf000004
	v_and_b32_e32 v27, 1, v79
	v_fma_f32 v18, v18, v19, 1.0
	v_cmp_eq_u32_e32 vcc, 0, v27
	v_lshlrev_b32_e32 v31, 16, v28
	v_lshlrev_b32_e32 v19, 30, v79
	v_cndmask_b32_e32 v27, v18, v78, vcc
	v_xor_b32_e32 v28, v77, v10
	v_lshlrev_b32_e32 v33, 16, v24
	v_lshlrev_b32_e32 v24, 16, v26
	v_and_b32_e32 v26, 0x80000000, v19
	v_xor_b32_e32 v27, v28, v27
	v_xor_b32_e32 v26, v27, v26
	v_xor_b32_e32 v27, 0x80000000, v78
	v_cndmask_b32_e32 v18, v27, v18, vcc
	s_brev_b32 s0, 1
	v_lshlrev_b32_e32 v21, 16, v17
	v_lshlrev_b32_e32 v35, 16, v25
	v_lshlrev_b32_e32 v34, 16, v22
	v_bitop3_b32 v18, v18, v19, s0 bitop3:0x78
	s_movk_i32 s0, 0x1f8
	v_lshlrev_b32_e32 v80, 16, v16
	v_lshlrev_b32_e32 v22, 16, v29
	v_lshlrev_b32_e32 v17, 16, v76
	v_cmp_class_f32_e64 vcc, v10, s0
	v_pk_mul_f32 v[28:29], v[20:21], v[20:21]
	v_pk_mul_f32 v[76:77], v[34:35], v[34:35]
	v_lshlrev_b32_e32 v72, 16, v23
	v_lshlrev_b32_e32 v71, 16, v70
	v_lshlrev_b32_e32 v23, 16, v74
	v_lshlrev_b32_e32 v16, 16, v75
	v_cndmask_b32_e32 v70, v224, v26, vcc
	v_pk_mul_f32 v[26:27], v[14:15], v[14:15]
	v_mul_f32_e32 v75, v80, v80
	v_mov_b32_e32 v78, v76
	v_mov_b32_e32 v79, v28
	v_mov_b32_e32 v74, v77
	v_pk_add_f32 v[74:75], v[78:79], v[74:75]
	v_mov_b32_e32 v28, v26
	v_pk_add_f32 v[28:29], v[28:29], v[74:75]
	v_mov_b32_e32 v75, v29
	v_mov_b32_e32 v74, v28
	s_nop 0
	v_permlane32_swap_b32_e32 v75, v29
	v_permlane32_swap_b32_e32 v74, v28
	s_mov_b32 s4, 0x3baaaaab
	v_cndmask_b32_e32 v10, v224, v18, vcc
	v_mad_i64_i32 v[18:19], s[0:1], v2, s7, v[6:7]
	s_waitcnt lgkmcnt(0)
	v_pk_add_f32 v[28:29], v[28:29], v[74:75]
	v_mov_b32_e32 v75, v29
	v_mov_b32_e32 v74, v28
	s_nop 0
	v_permlane16_swap_b32_e32 v75, v29
	v_permlane16_swap_b32_e32 v74, v28
	v_lshlrev_b32_e32 v25, 16, v73
	v_pk_mul_f32 v[76:77], v[30:31], v[30:31]
	v_lshlrev_b32_e32 v13, 16, v13
	v_mov_b32_e32 v78, v76
	s_waitcnt lgkmcnt(0)
	v_pk_add_f32 v[28:29], v[28:29], v[74:75]
	s_nop 1
	v_add_f32_dpp v29, v29, v29 row_ror:8 row_mask:0xf bank_mask:0xf
	v_add_f32_dpp v28, v28, v28 row_ror:8 row_mask:0xf bank_mask:0xf
	s_waitcnt lgkmcnt(0)
	s_nop 1
	v_add_f32_dpp v29, v29, v29 row_ror:4 row_mask:0xf bank_mask:0xf
	v_add_f32_dpp v28, v28, v28 row_ror:4 row_mask:0xf bank_mask:0xf
	s_waitcnt lgkmcnt(0)
	s_nop 1
	v_add_f32_dpp v29, v29, v29 quad_perm:[2,3,0,1] row_mask:0xf bank_mask:0xf
	v_add_f32_dpp v28, v28, v28 quad_perm:[2,3,0,1] row_mask:0xf bank_mask:0xf
	s_waitcnt lgkmcnt(0)
	s_nop 1
	v_add_f32_dpp v75, v29, v29 quad_perm:[1,0,3,2] row_mask:0xf bank_mask:0xf
	v_add_f32_dpp v74, v28, v28 quad_perm:[1,0,3,2] row_mask:0xf bank_mask:0xf
	s_waitcnt lgkmcnt(0)
	v_mov_b64_e32 v[28:29], s[72:73]
	v_pk_fma_f32 v[74:75], v[74:75], s[4:5], v[28:29] op_sel_hi:[1,0,0]
	s_nop 0
	v_cmp_gt_f32_e64 s[0:1], s77, v75
	v_cmp_gt_f32_e32 vcc, s77, v74
	s_nop 0
	v_rsq_f32_e32 v73, v75
	s_nop 0
	v_mul_f32_e32 v73, 0x3dd53b94, v73
	v_mul_f32_e32 v21, v73, v21
	v_mul_f32_e32 v21, v41, v21
	ds_bpermute_b32 v75, v43, v21
	v_mul_f32_e32 v20, v73, v20
	v_mul_f32_e32 v20, v36, v20
	s_waitcnt lgkmcnt(0)
	v_mul_f32_e32 v75, v70, v75
	v_cndmask_b32_e64 v75, v75, -v75, s[38:39]
	v_fmac_f32_e32 v75, v10, v21
	v_bfe_u32 v21, v20, 16, 1
	v_add3_u32 v20, v20, v21, s11
	global_store_short_d16_hi v[18:19], v20, off
	v_mul_f32_e32 v20, v73, v80
	v_mul_f32_e32 v20, v37, v20
	v_bfe_u32 v21, v20, 16, 1
	v_add3_u32 v20, v20, v21, s11
	global_store_short_d16_hi v[18:19], v20, off offset:128
	v_bfe_u32 v20, v75, 16, 1
	v_add3_u32 v20, v75, v20, s11
	global_store_short_d16_hi v[18:19], v20, off offset:256
	v_rsq_f32_e32 v20, v74
	v_mul_f32_e32 v75, v72, v72
	v_mov_b32_e32 v73, v20
	v_mul_f32_e32 v20, v73, v14
	v_mul_f32_e32 v20, v40, v20
	ds_bpermute_b32 v21, v43, v20
	s_waitcnt lgkmcnt(0)
	v_mul_f32_e32 v21, v70, v21
	v_cndmask_b32_e64 v74, v21, -v21, s[38:39]
	v_fmac_f32_e32 v74, v10, v20
	v_mul_f32_e32 v20, v73, v34
	v_mul_f32_e32 v20, v38, v20
	v_bfe_u32 v21, v20, 16, 1
	v_add3_u32 v34, v20, v21, s11
	v_mad_i64_i32 v[20:21], s[0:1], v2, s7, v[8:9]
	global_store_short_d16_hi v[20:21], v34, off
	v_mul_f32_e32 v34, v73, v35
	v_mul_f32_e32 v34, v39, v34
	v_bfe_u32 v35, v34, 16, 1
	v_add3_u32 v34, v34, v35, s11
	global_store_short_d16_hi v[20:21], v34, off offset:128
	v_bfe_u32 v34, v74, 16, 1
	v_add3_u32 v34, v74, v34, s11
	global_store_short_d16_hi v[20:21], v34, off offset:256
	v_pk_mul_f32 v[34:35], v[32:33], v[32:33]
	v_mov_b32_e32 v74, v77
	v_mov_b32_e32 v79, v34
	v_pk_add_f32 v[74:75], v[78:79], v[74:75]
	v_mov_b32_e32 v34, v26
	v_pk_add_f32 v[34:35], v[34:35], v[74:75]
	v_mov_b32_e32 v75, v35
	v_mov_b32_e32 v74, v34
	s_nop 0
	v_permlane32_swap_b32_e32 v75, v35
	v_permlane32_swap_b32_e32 v74, v34
	s_waitcnt lgkmcnt(0)
	v_pk_add_f32 v[34:35], v[34:35], v[74:75]
	v_mov_b32_e32 v75, v35
	v_mov_b32_e32 v74, v34
	s_nop 0
	v_permlane16_swap_b32_e32 v75, v35
	v_permlane16_swap_b32_e32 v74, v34
	s_waitcnt lgkmcnt(0)
	v_pk_add_f32 v[34:35], v[34:35], v[74:75]
	s_nop 1
	v_add_f32_dpp v35, v35, v35 row_ror:8 row_mask:0xf bank_mask:0xf
	v_add_f32_dpp v34, v34, v34 row_ror:8 row_mask:0xf bank_mask:0xf
	s_waitcnt lgkmcnt(0)
; DI bf16_t f2bf(float f) { unsigned u = __float_as_uint(f); u += 0x7fffu + ((u >> 16) & 1u); return (bf16_t)(u >> 16); }
; DI float wave_sum(float v) { for (int o = 32; o; o >>= 1) v += __shfl_xor(v, o); return v; }
; DI void run_phase(const Params& p, int ph, unsigned char* smem, const int tid, const int rep) {
;     ...
;             for (int u = 0; u < 2; ++u) { const int t = t0 + u;
;                 const float ang = (float)ps[u] * invf; float sn, cs; sincosf(ang, &sn, &cs);
;                 const float kr = krv[u];
; #pragma unroll
;                 for (int h = 0; h < 4; ++h) {
;                     { const float a0 = qa[u][h][0], a1 = qa[u][h][1], a2 = qa[u][h][2];
;                       const float rs = rsqrtf(wave_sum(a0 * a0 + a1 * a1 + a2 * a2) * (1.f / 192.f) + NEPS) * (0.07216878364870322f * LOG2E);
;                       const float y2 = a2 * rs * gq2; const float oth = __shfl_xor(y2, 32);
;                       const float rot = (lane < 32) ? (y2 * cs - oth * sn) : (y2 * cs + oth * sn);
;                       bf16_t* qo = mlaq + (size_t)t * 768 + h * 192; qo[lane] = f2bf(a0 * rs * gq0); qo[lane + 64] = f2bf(a1 * rs * gq1); qo[lane + 128] = f2bf(rot); }
;                     { const float a0 = ka[u][h][0], a1 = ka[u][h][1];
;                       const float rs = rsqrtf(wave_sum(a0 * a0 + a1 * a1 + kr * kr) * (1.f / 192.f) + NEPS);
;                       const float y2 = kr * rs * gk2; const float oth = __shfl_xor(y2, 32);
;                       const float rot = (lane < 32) ? (y2 * cs - oth * sn) : (y2 * cs + oth * sn);
;                       bf16_t* ko = mlak + (size_t)t * 768 + h * 192; ko[lane] = f2bf(a0 * rs * gk0); ko[lane + 64] = f2bf(a1 * rs * gk1); ko[lane + 128] = f2bf(rot); }
	s_nop 1
	v_add_f32_dpp v35, v35, v35 row_ror:4 row_mask:0xf bank_mask:0xf
	v_add_f32_dpp v34, v34, v34 row_ror:4 row_mask:0xf bank_mask:0xf
	s_waitcnt lgkmcnt(0)
	s_nop 1
	v_add_f32_dpp v35, v35, v35 quad_perm:[2,3,0,1] row_mask:0xf bank_mask:0xf
	v_add_f32_dpp v34, v34, v34 quad_perm:[2,3,0,1] row_mask:0xf bank_mask:0xf
	s_waitcnt lgkmcnt(0)
	s_nop 1
	v_add_f32_dpp v35, v35, v35 quad_perm:[1,0,3,2] row_mask:0xf bank_mask:0xf
	v_add_f32_dpp v34, v34, v34 quad_perm:[1,0,3,2] row_mask:0xf bank_mask:0xf
	s_waitcnt lgkmcnt(0)
	s_nop 0
	v_pk_fma_f32 v[34:35], v[34:35], s[4:5], v[28:29] op_sel_hi:[1,0,0]
	s_nop 0
	v_mul_f32_e32 v73, 0x4b800000, v35
	v_cmp_gt_f32_e64 s[0:1], s77, v35
	v_cmp_gt_f32_e32 vcc, s77, v34
	s_nop 0
	v_cndmask_b32_e64 v35, v35, v73, s[0:1]
	v_rsq_f32_e32 v35, v35
	s_nop 0
	v_mul_f32_e32 v73, 0x45800000, v35
	v_cndmask_b32_e64 v35, v35, v73, s[0:1]
	v_mul_f32_e32 v35, 0x3dd53b94, v35
	v_mul_f32_e32 v33, v35, v33
	v_mul_f32_e32 v33, v41, v33
	ds_bpermute_b32 v73, v43, v33
	v_mul_f32_e32 v32, v35, v32
	v_mul_f32_e32 v32, v36, v32
	s_waitcnt lgkmcnt(0)
	v_mul_f32_e32 v73, v70, v73
	v_cndmask_b32_e64 v73, v73, -v73, s[38:39]
	v_fmac_f32_e32 v73, v10, v33
	v_bfe_u32 v33, v32, 16, 1
	v_add3_u32 v32, v32, v33, s11
	global_store_short_d16_hi v[18:19], v32, off offset:384
	v_mul_f32_e32 v32, v35, v72
	v_mul_f32_e32 v32, v37, v32
	v_bfe_u32 v33, v32, 16, 1
	v_add3_u32 v32, v32, v33, s11
	global_store_short_d16_hi v[18:19], v32, off offset:512
	v_bfe_u32 v32, v73, 16, 1
	v_add3_u32 v32, v73, v32, s11
	global_store_short_d16_hi v[18:19], v32, off offset:640
	v_rsq_f32_e32 v32, v34
	s_nop 0
	v_mul_f32_e32 v33, v32, v14
	v_mul_f32_e32 v33, v40, v33
	ds_bpermute_b32 v34, v43, v33
	v_mul_f32_e32 v30, v32, v30
	v_mul_f32_e32 v30, v38, v30
	s_waitcnt lgkmcnt(0)
	v_mul_f32_e32 v34, v70, v34
	v_cndmask_b32_e64 v34, v34, -v34, s[38:39]
	v_fmac_f32_e32 v34, v10, v33
	v_bfe_u32 v33, v30, 16, 1
	v_add3_u32 v30, v30, v33, s11
	global_store_short_d16_hi v[20:21], v30, off offset:384
	v_mul_f32_e32 v30, v32, v31
	v_mul_f32_e32 v30, v39, v30
	v_bfe_u32 v31, v30, 16, 1
	v_add3_u32 v30, v30, v31, s11
	global_store_short_d16_hi v[20:21], v30, off offset:512
	v_bfe_u32 v30, v34, 16, 1
	v_add3_u32 v30, v34, v30, s11
	global_store_short_d16_hi v[20:21], v30, off offset:640
	v_pk_mul_f32 v[30:31], v[24:25], v[24:25]
	v_pk_mul_f32 v[34:35], v[22:23], v[22:23]
	v_mul_f32_e32 v33, v71, v71
	v_mov_b32_e32 v72, v34
	v_mov_b32_e32 v73, v30
	v_mov_b32_e32 v32, v35
	v_pk_add_f32 v[32:33], v[72:73], v[32:33]
	v_mov_b32_e32 v30, v26
	v_pk_add_f32 v[30:31], v[30:31], v[32:33]
	v_mov_b32_e32 v33, v31
	v_mov_b32_e32 v32, v30
	s_nop 0
	v_permlane32_swap_b32_e32 v33, v31
	v_permlane32_swap_b32_e32 v32, v30
	s_waitcnt lgkmcnt(0)
	v_pk_add_f32 v[30:31], v[30:31], v[32:33]
	v_mov_b32_e32 v33, v31
	v_mov_b32_e32 v32, v30
	s_nop 0
	v_permlane16_swap_b32_e32 v33, v31
	v_permlane16_swap_b32_e32 v32, v30
	s_waitcnt lgkmcnt(0)
	v_pk_add_f32 v[30:31], v[30:31], v[32:33]
	s_nop 1
	v_add_f32_dpp v31, v31, v31 row_ror:8 row_mask:0xf bank_mask:0xf
	v_add_f32_dpp v30, v30, v30 row_ror:8 row_mask:0xf bank_mask:0xf
	s_waitcnt lgkmcnt(0)
	s_nop 1
	v_add_f32_dpp v31, v31, v31 row_ror:4 row_mask:0xf bank_mask:0xf
	v_add_f32_dpp v30, v30, v30 row_ror:4 row_mask:0xf bank_mask:0xf
	s_waitcnt lgkmcnt(0)
	s_nop 1
	v_add_f32_dpp v31, v31, v31 quad_perm:[2,3,0,1] row_mask:0xf bank_mask:0xf
	v_add_f32_dpp v30, v30, v30 quad_perm:[2,3,0,1] row_mask:0xf bank_mask:0xf
	s_waitcnt lgkmcnt(0)
	s_nop 1
	v_add_f32_dpp v31, v31, v31 quad_perm:[1,0,3,2] row_mask:0xf bank_mask:0xf
	v_add_f32_dpp v30, v30, v30 quad_perm:[1,0,3,2] row_mask:0xf bank_mask:0xf
	s_waitcnt lgkmcnt(0)
	s_nop 0
	v_pk_fma_f32 v[30:31], v[30:31], s[4:5], v[28:29] op_sel_hi:[1,0,0]
	s_nop 0
	v_mul_f32_e32 v32, 0x4b800000, v31
	v_cmp_gt_f32_e64 s[0:1], s77, v31
	v_cmp_gt_f32_e32 vcc, s77, v30
	s_nop 0
	v_cndmask_b32_e64 v31, v31, v32, s[0:1]
	v_rsq_f32_e32 v31, v31
	s_nop 0
	v_mul_f32_e32 v32, 0x45800000, v31
	v_cndmask_b32_e64 v31, v31, v32, s[0:1]
	v_mul_f32_e32 v31, 0x3dd53b94, v31
	v_mul_f32_e32 v25, v31, v25
	v_mul_f32_e32 v25, v41, v25
	ds_bpermute_b32 v32, v43, v25
	v_mul_f32_e32 v24, v31, v24
	v_mul_f32_e32 v24, v36, v24
	s_waitcnt lgkmcnt(0)
	v_mul_f32_e32 v32, v70, v32
	v_cndmask_b32_e64 v32, v32, -v32, s[38:39]
	v_fmac_f32_e32 v32, v10, v25
	v_bfe_u32 v25, v24, 16, 1
	v_add3_u32 v24, v24, v25, s11
	global_store_short_d16_hi v[18:19], v24, off offset:768
	v_mul_f32_e32 v24, v31, v71
	v_mul_f32_e32 v24, v37, v24
	v_bfe_u32 v25, v24, 16, 1
	v_add3_u32 v24, v24, v25, s11
	global_store_short_d16_hi v[18:19], v24, off offset:896
	v_bfe_u32 v24, v32, 16, 1
	v_add3_u32 v24, v32, v24, s11
	global_store_short_d16_hi v[18:19], v24, off offset:1024
	v_rsq_f32_e32 v24, v30
	s_nop 0
	v_mul_f32_e32 v25, v24, v14
	v_mul_f32_e32 v25, v40, v25
	ds_bpermute_b32 v30, v43, v25
	v_mul_f32_e32 v22, v24, v22
	v_mul_f32_e32 v22, v38, v22
	s_waitcnt lgkmcnt(0)
	v_mul_f32_e32 v30, v70, v30
	v_cndmask_b32_e64 v30, v30, -v30, s[38:39]
	v_fmac_f32_e32 v30, v10, v25
	v_bfe_u32 v25, v22, 16, 1
	v_add3_u32 v22, v22, v25, s11
	global_store_short_d16_hi v[20:21], v22, off offset:768
	v_mul_f32_e32 v22, v24, v23
	v_mul_f32_e32 v22, v39, v22
	v_bfe_u32 v23, v22, 16, 1
	v_add3_u32 v22, v22, v23, s11
	global_store_short_d16_hi v[20:21], v22, off offset:896
	v_bfe_u32 v22, v30, 16, 1
	v_add3_u32 v22, v30, v22, s11
	global_store_short_d16_hi v[20:21], v22, off offset:1024
	v_pk_mul_f32 v[22:23], v[16:17], v[16:17]
	s_nop 0
	v_pk_mov_b32 v[24:25], v[26:27], v[22:23] op_sel:[1,0]
	v_mov_b32_e32 v27, v23
	v_pk_fma_f32 v[24:25], v[12:13], v[12:13], v[24:25]
	s_nop 0
	v_pk_add_f32 v[22:23], v[26:27], v[24:25]
	v_mov_b32_e32 v25, v23
	v_mov_b32_e32 v24, v22
	s_nop 0
	v_permlane32_swap_b32_e32 v25, v23
	v_permlane32_swap_b32_e32 v24, v22
	s_waitcnt lgkmcnt(0)
; DI bf16_t f2bf(float f) { unsigned u = __float_as_uint(f); u += 0x7fffu + ((u >> 16) & 1u); return (bf16_t)(u >> 16); }
; DI float wave_sum(float v) { for (int o = 32; o; o >>= 1) v += __shfl_xor(v, o); return v; }
; DI void run_phase(const Params& p, int ph, unsigned char* smem, const int tid, const int rep) {
;     ...
;             for (int u = 0; u < 2; ++u) { const int t = t0 + u;
;                 const float ang = (float)ps[u] * invf; float sn, cs; sincosf(ang, &sn, &cs);
;                 const float kr = krv[u];
; #pragma unroll
;                 for (int h = 0; h < 4; ++h) {
;                     { const float a0 = qa[u][h][0], a1 = qa[u][h][1], a2 = qa[u][h][2];
;                       const float rs = rsqrtf(wave_sum(a0 * a0 + a1 * a1 + a2 * a2) * (1.f / 192.f) + NEPS) * (0.07216878364870322f * LOG2E);
;                       const float y2 = a2 * rs * gq2; const float oth = __shfl_xor(y2, 32);
;                       const float rot = (lane < 32) ? (y2 * cs - oth * sn) : (y2 * cs + oth * sn);
;                       bf16_t* qo = mlaq + (size_t)t * 768 + h * 192; qo[lane] = f2bf(a0 * rs * gq0); qo[lane + 64] = f2bf(a1 * rs * gq1); qo[lane + 128] = f2bf(rot); }
;                     { const float a0 = ka[u][h][0], a1 = ka[u][h][1];
;                       const float rs = rsqrtf(wave_sum(a0 * a0 + a1 * a1 + kr * kr) * (1.f / 192.f) + NEPS);
;                       const float y2 = kr * rs * gk2; const float oth = __shfl_xor(y2, 32);
;                       const float rot = (lane < 32) ? (y2 * cs - oth * sn) : (y2 * cs + oth * sn);
;                       bf16_t* ko = mlak + (size_t)t * 768 + h * 192; ko[lane] = f2bf(a0 * rs * gk0); ko[lane + 64] = f2bf(a1 * rs * gk1); ko[lane + 128] = f2bf(rot); }
	v_pk_add_f32 v[22:23], v[22:23], v[24:25]
	v_mov_b32_e32 v25, v23
	v_mov_b32_e32 v24, v22
	s_nop 0
	v_permlane16_swap_b32_e32 v25, v23
	v_permlane16_swap_b32_e32 v24, v22
	s_waitcnt lgkmcnt(0)
	v_pk_add_f32 v[22:23], v[22:23], v[24:25]
	s_nop 1
	v_add_f32_dpp v23, v23, v23 row_ror:8 row_mask:0xf bank_mask:0xf
	v_add_f32_dpp v22, v22, v22 row_ror:8 row_mask:0xf bank_mask:0xf
	s_waitcnt lgkmcnt(0)
	s_nop 1
	v_add_f32_dpp v23, v23, v23 row_ror:4 row_mask:0xf bank_mask:0xf
	v_add_f32_dpp v22, v22, v22 row_ror:4 row_mask:0xf bank_mask:0xf
	s_waitcnt lgkmcnt(0)
	s_nop 1
	v_add_f32_dpp v23, v23, v23 quad_perm:[2,3,0,1] row_mask:0xf bank_mask:0xf
	v_add_f32_dpp v22, v22, v22 quad_perm:[2,3,0,1] row_mask:0xf bank_mask:0xf
	s_waitcnt lgkmcnt(0)
	s_nop 1
	v_add_f32_dpp v23, v23, v23 quad_perm:[1,0,3,2] row_mask:0xf bank_mask:0xf
	v_add_f32_dpp v22, v22, v22 quad_perm:[1,0,3,2] row_mask:0xf bank_mask:0xf
	s_waitcnt lgkmcnt(0)
	s_nop 0
	v_pk_fma_f32 v[22:23], v[22:23], s[4:5], v[28:29] op_sel_hi:[1,0,0]
	s_nop 0
	v_mul_f32_e32 v24, 0x4b800000, v23
	v_cmp_gt_f32_e64 s[0:1], s77, v23
	v_cmp_gt_f32_e32 vcc, s77, v22
	s_nop 0
	v_cndmask_b32_e64 v23, v23, v24, s[0:1]
	v_rsq_f32_e32 v23, v23
	s_nop 0
	v_mul_f32_e32 v24, 0x45800000, v23
	v_cndmask_b32_e64 v23, v23, v24, s[0:1]
	v_mul_f32_e32 v23, 0x3dd53b94, v23
	v_mul_f32_e32 v17, v23, v17
	v_mul_f32_e32 v17, v41, v17
	ds_bpermute_b32 v24, v43, v17
	v_mul_f32_e32 v16, v23, v16
	v_mul_f32_e32 v16, v36, v16
	v_mul_f32_e32 v13, v23, v13
	v_mul_f32_e32 v13, v37, v13
	s_waitcnt lgkmcnt(0)
	v_mul_f32_e32 v24, v70, v24
	v_cndmask_b32_e64 v24, v24, -v24, s[38:39]
	v_fmac_f32_e32 v24, v10, v17
	v_bfe_u32 v17, v16, 16, 1
	v_add3_u32 v16, v16, v17, s11
	global_store_short_d16_hi v[18:19], v16, off offset:1152
	v_bfe_u32 v16, v13, 16, 1
	v_add3_u32 v13, v13, v16, s11
	global_store_short_d16_hi v[18:19], v13, off offset:1280
	v_bfe_u32 v13, v24, 16, 1
	v_add3_u32 v13, v24, v13, s11
	global_store_short_d16_hi v[18:19], v13, off offset:1408
	v_rsq_f32_e32 v13, v22
	s_brev_b32 s0, 18
	v_mul_f32_e32 v14, v13, v14
	v_mul_f32_e32 v14, v40, v14
	ds_bpermute_b32 v16, v43, v14
	s_waitcnt lgkmcnt(0)
	v_mul_f32_e32 v16, v70, v16
	v_cndmask_b32_e64 v16, v16, -v16, s[38:39]
	v_fmac_f32_e32 v16, v10, v14
	v_mul_f32_e32 v10, v13, v15
	v_mul_f32_e32 v10, v38, v10
	v_bfe_u32 v14, v10, 16, 1
	v_add3_u32 v10, v10, v14, s11
	global_store_short_d16_hi v[20:21], v10, off offset:1152
	v_mul_f32_e32 v10, v13, v12
	v_mul_f32_e32 v10, v39, v10
	v_bfe_u32 v12, v10, 16, 1
	v_add3_u32 v10, v10, v12, s11
	global_store_short_d16_hi v[20:21], v10, off offset:1280
	v_bfe_u32 v10, v16, 16, 1
	v_add3_u32 v10, v16, v10, s11
	global_store_short_d16_hi v[20:21], v10, off offset:1408
	v_cvt_f32_i32_e32 v10, v11
	v_mul_f32_e32 v16, v42, v10
	v_and_b32_e32 v17, 0x7fffffff, v16
	v_cmp_nlt_f32_e64 s[0:1], |v16|, s0
	s_and_saveexec_b64 s[40:41], s[0:1]
	s_xor_b64 s[44:45], exec, s[40:41]
	s_cbranch_execz .LBB0_338
	v_lshrrev_b32_e32 v10, 23, v17
	v_add_u32_e32 v10, 0xffffff88, v10
	v_cmp_lt_u32_e32 vcc, 63, v10
	s_mov_b32 s4, 0xfe5163ab
	v_mov_b32_e32 v13, v1
	v_cndmask_b32_e32 v11, 0, v195, vcc
	v_add_u32_e32 v10, v11, v10
	v_cmp_lt_u32_e64 s[0:1], 31, v10
	v_mov_b32_e32 v15, v1
	v_mov_b32_e32 v19, v1
	v_cndmask_b32_e64 v11, 0, v184, s[0:1]
	v_add_u32_e32 v10, v11, v10
	v_cmp_lt_u32_e64 s[40:41], 31, v10
	v_mov_b32_e32 v21, v1
	v_mov_b32_e32 v23, v1
	v_cndmask_b32_e64 v11, 0, v184, s[40:41]
	v_add_u32_e32 v26, v11, v10
	v_and_b32_e32 v10, 0x7fffff, v17
	v_or_b32_e32 v27, 0x800000, v10
	v_mad_u64_u32 v[10:11], s[42:43], v27, s4, 0
	v_mov_b32_e32 v12, v11
	s_mov_b32 s4, 0x3c439041
	v_mad_u64_u32 v[12:13], s[42:43], v27, s4, v[12:13]
	v_mov_b32_e32 v14, v13
	s_mov_b32 s4, 0xdb629599
	v_mad_u64_u32 v[14:15], s[42:43], v27, s4, v[14:15]
	v_mov_b32_e32 v18, v15
	s_mov_b32 s4, 0xf534ddc0
	v_mad_u64_u32 v[18:19], s[42:43], v27, s4, v[18:19]
	v_mov_b32_e32 v20, v19
	s_mov_b32 s4, 0xfc2757d1
	v_mad_u64_u32 v[20:21], s[42:43], v27, s4, v[20:21]
	v_mov_b32_e32 v22, v21
	s_mov_b32 s4, 0x4e441529
	v_mad_u64_u32 v[22:23], s[42:43], v27, s4, v[22:23]
	v_mov_b32_e32 v24, v23
	v_mov_b32_e32 v25, v1
	s_mov_b32 s4, 0xa2f9836e
	v_mad_u64_u32 v[24:25], s[42:43], v27, s4, v[24:25]
	v_cndmask_b32_e32 v11, v22, v18, vcc
	v_cndmask_b32_e32 v13, v24, v20, vcc
	v_cndmask_b32_e32 v19, v25, v22, vcc
	v_cndmask_b32_e64 v15, v13, v11, s[0:1]
	v_cndmask_b32_e64 v13, v19, v13, s[0:1]
	v_cndmask_b32_e32 v19, v20, v14, vcc
	v_cndmask_b32_e64 v11, v11, v19, s[0:1]
	v_cndmask_b32_e32 v12, v18, v12, vcc
	v_cndmask_b32_e64 v13, v13, v15, s[40:41]
	v_cndmask_b32_e64 v15, v15, v11, s[40:41]
	v_sub_u32_e32 v20, 32, v26
	v_cndmask_b32_e64 v18, v19, v12, s[0:1]
	v_alignbit_b32 v21, v13, v15, v20
	v_cmp_eq_u32_e64 s[42:43], 0, v26
	v_cndmask_b32_e64 v11, v11, v18, s[40:41]
	v_alignbit_b32 v19, v15, v11, v20
	v_cndmask_b32_e64 v13, v21, v13, s[42:43]
	v_cndmask_b32_e32 v10, v14, v10, vcc
	v_cndmask_b32_e64 v15, v19, v15, s[42:43]
	v_bfe_u32 v22, v13, 29, 1
	v_cndmask_b32_e64 v10, v12, v10, s[0:1]
	v_alignbit_b32 v19, v13, v15, 30
	v_sub_u32_e32 v23, 0, v22
	v_cndmask_b32_e64 v10, v18, v10, s[40:41]
	v_xor_b32_e32 v19, v19, v23
	v_alignbit_b32 v12, v11, v10, v20
	v_cndmask_b32_e64 v11, v12, v11, s[42:43]
	v_ffbh_u32_e32 v14, v19
	v_alignbit_b32 v12, v15, v11, 30
	v_min_u32_e32 v14, 32, v14
	v_alignbit_b32 v10, v11, v10, 30
	v_xor_b32_e32 v12, v12, v23
	v_sub_u32_e32 v15, 31, v14
	v_xor_b32_e32 v10, v10, v23
	v_alignbit_b32 v18, v19, v12, v15
	v_alignbit_b32 v10, v12, v10, v15
	v_alignbit_b32 v11, v18, v10, 9
	v_ffbh_u32_e32 v12, v11
	v_min_u32_e32 v12, 32, v12
	v_lshrrev_b32_e32 v21, 29, v13
	v_not_b32_e32 v15, v12
	v_alignbit_b32 v10, v11, v10, v15
	v_lshlrev_b32_e32 v11, 31, v21
	v_or_b32_e32 v15, 0x33000000, v11
	v_add_lshl_u32 v12, v12, v14, 23
	v_lshrrev_b32_e32 v10, 9, v10
	v_sub_u32_e32 v12, v15, v12
	v_or_b32_e32 v11, 0.5, v11
	v_lshlrev_b32_e32 v14, 23, v14
	v_or_b32_e32 v10, v12, v10
	v_lshrrev_b32_e32 v12, 9, v18
	v_sub_u32_e32 v11, v11, v14
	v_or_b32_e32 v11, v12, v11
	v_mul_f32_e32 v12, 0x3fc90fda, v11
	s_mov_b32 s0, 0x3fc90fda
	v_fma_f32 v14, v11, s0, -v12
	v_fmac_f32_e32 v14, 0x33a22168, v11
	v_fmac_f32_e32 v14, 0x3fc90fda, v10
	v_lshrrev_b32_e32 v10, 30, v13
	v_add_f32_e32 v24, v12, v14
	v_add_u32_e32 v25, v22, v10

; DI unsigned pk2(float lo, float hi) { const f32x2 v = {lo, hi}; return __builtin_bit_cast(unsigned, __builtin_convertvector(v, bf16v2_t)); }
; DI float wave_sum(float v) { for (int o = 32; o; o >>= 1) v += __shfl_xor(v, o); return v; }
; DI void run_phase(const Params& p, int ph, unsigned char* smem, const int tid, const int rep) {
;     ...
;           for (int t0 = (blockIdx.x * 8 + wv) * 4; t0 < TS; t0 += gridDim.x * 32) {
;               u32x2 vq[4]; unsigned vkv[4], vf[4][8];
; #pragma unroll
;               for (int u = 0; u < 4; ++u) { const bf16_t* pr = proj + (size_t)(t0 + u) * PLD; vq[u] = *(const u32x2*)(pr + 2048 + 4 * lane); vkv[u] = *(const unsigned*)(pr + 2304 + 2 * lane);
; #pragma unroll
;                   for (int hq = 0; hq < 8; ++hq) vf[u][hq] = *(const unsigned*)(pr + 3520 + hq * 128 + 2 * lane); }
; #pragma unroll
;               for (int u = 0; u < 4; ++u) { const int t = t0 + u; bf16_t* pr = proj + (size_t)t * PLD;
;                   { const u32x2 v = vq[u]; const float a0 = __uint_as_float(v[0] << 16), a1 = __uint_as_float(v[0] & 0xffff0000u), a2 = __uint_as_float(v[1] << 16), a3 = __uint_as_float(v[1] & 0xffff0000u);
;                     const float rs = rsqrtf(wave_sum(a0 * a0 + a1 * a1 + a2 * a2 + a3 * a3) * (1.f / 256.f) + NEPS);
;                     u32x2 o; o[0] = pk2(a0 * rs * ggq[0], a1 * rs * ggq[1]); o[1] = pk2(a2 * rs * ggq[2], a3 * rs * ggq[3]); *(u32x2*)(mlaa + (size_t)t * 384 + 4 * lane) = o; }
;                   { const unsigned v = vkv[u]; const float a0 = __uint_as_float(v << 16), a1 = __uint_as_float(v & 0xffff0000u);
;                     const float rs = rsqrtf(wave_sum(a0 * a0 + a1 * a1) * (1.f / 128.f) + NEPS);
;                     *(unsigned*)(mlaa + (size_t)t * 384 + 256 + 2 * lane) = pk2(a0 * rs * gkv0, a1 * rs * gkv1); }
.LBB0_372:
	v_mov_b64_e32 v[14:15], s[30:31]
	v_mad_i64_i32 v[16:17], s[0:1], v44, s3, v[14:15]
	v_lshl_add_u64 v[18:19], v[16:17], 0, v[0:1]
	v_add_co_u32_e32 v18, vcc, 0x1000, v18
	v_mov_b32_e32 v13, v1
	s_nop 0
	v_addc_co_u32_e32 v19, vcc, 0, v19, vcc
	v_lshl_add_u64 v[16:17], v[16:17], 0, v[12:13]
	global_load_dwordx2 v[18:19], v[18:19], off
	v_add_co_u32_e32 v36, vcc, 0x1000, v16
	v_add_u32_e32 v79, 1, v44
	s_nop 0
	v_addc_co_u32_e32 v37, vcc, 0, v17, vcc
	global_load_dword v89, v[36:37], off offset:512
	v_lshl_add_u64 v[34:35], v[16:17], 0, s[34:35]
	global_load_dword v88, v[36:37], off offset:2944
	global_load_dword v87, v[34:35], off offset:256
	global_load_dword v86, v[34:35], off offset:512
	global_load_dword v85, v[34:35], off offset:768
	global_load_dword v84, v[34:35], off offset:1024
	global_load_dword v83, v[34:35], off offset:1280
	global_load_dword v82, v[34:35], off offset:1536
	global_load_dword v81, v[34:35], off offset:1792
	v_mad_i64_i32 v[16:17], s[0:1], v79, s3, v[14:15]
	v_lshl_add_u64 v[20:21], v[16:17], 0, v[0:1]
	v_add_co_u32_e32 v20, vcc, s87, v20
	v_lshl_add_u64 v[16:17], v[16:17], 0, v[12:13]
	s_nop 0
	v_addc_co_u32_e32 v21, vcc, 0, v21, vcc
	v_add_co_u32_e32 v32, vcc, s87, v16
	v_add_u32_e32 v69, 2, v44
	s_nop 0
	v_addc_co_u32_e32 v33, vcc, 0, v17, vcc
	v_lshl_add_u64 v[28:29], v[16:17], 0, s[34:35]
	v_mad_i64_i32 v[16:17], s[0:1], v69, s3, v[14:15]
	global_load_dwordx2 v[40:41], v[20:21], off
	global_load_dword v80, v[32:33], off offset:512
	v_lshl_add_u64 v[20:21], v[16:17], 0, v[0:1]
	v_add_co_u32_e32 v20, vcc, s87, v20
	v_lshl_add_u64 v[16:17], v[16:17], 0, v[12:13]
	s_nop 0
	v_addc_co_u32_e32 v21, vcc, 0, v21, vcc
	v_add_co_u32_e32 v26, vcc, s87, v16
	v_add_u32_e32 v59, 3, v44
	s_nop 0
	v_addc_co_u32_e32 v27, vcc, 0, v17, vcc
	v_mad_i64_i32 v[14:15], s[0:1], v59, s3, v[14:15]
	global_load_dword v78, v[32:33], off offset:2944
	global_load_dword v77, v[28:29], off offset:256
	global_load_dword v76, v[28:29], off offset:512
	global_load_dword v75, v[28:29], off offset:768
	global_load_dword v74, v[28:29], off offset:1024
	global_load_dword v73, v[28:29], off offset:1280
	global_load_dword v72, v[28:29], off offset:1536
	global_load_dword v71, v[28:29], off offset:1792
	global_load_dwordx2 v[30:31], v[20:21], off
	global_load_dword v70, v[26:27], off offset:512
	v_lshl_add_u64 v[22:23], v[16:17], 0, s[34:35]
	v_lshl_add_u64 v[16:17], v[14:15], 0, v[0:1]
	v_add_co_u32_e32 v16, vcc, s87, v16
	v_lshl_add_u64 v[14:15], v[14:15], 0, v[12:13]
	s_nop 0
	v_addc_co_u32_e32 v17, vcc, 0, v17, vcc
	global_load_dword v68, v[26:27], off offset:2944
	global_load_dword v67, v[22:23], off offset:256
	global_load_dword v66, v[22:23], off offset:512
	global_load_dword v65, v[22:23], off offset:768
	global_load_dword v64, v[22:23], off offset:1024
	global_load_dword v63, v[22:23], off offset:1280
	global_load_dword v62, v[22:23], off offset:1536
	global_load_dword v61, v[22:23], off offset:1792
	global_load_dwordx2 v[24:25], v[16:17], off
	v_add_co_u32_e32 v16, vcc, s87, v14
	s_waitcnt vmcnt(0)
	v_and_b32_e32 v43, 0xffff0000, v18
	v_and_b32_e32 v21, 0xffff0000, v19
	v_and_b32_e32 v20, s0, v18
	v_lshlrev_b32_e32 v42, 16, v18
	v_mul_f32_e32 v18, v43, v43
	v_lshlrev_b32_e32 v38, 16, v19
	v_mov_b32_e32 v39, v21
	v_pk_fma_f32 v[18:19], v[42:43], v[42:43], v[18:19] op_sel_hi:[1,1,0]
	v_lshlrev_b32_e32 v96, 16, v89
	v_and_b32_e32 v97, 0xffff0000, v89
	v_pk_mul_f32 v[90:91], v[20:21], v[20:21]
	v_pk_fma_f32 v[18:19], v[38:39], v[38:39], v[18:19]
	v_pk_mul_f32 v[98:99], v[96:97], v[96:97]
	v_mov_b64_e32 v[20:21], s[12:13]
	v_mov_b32_e32 v90, v98
	v_pk_mov_b32 v[18:19], v[98:99], v[18:19] op_sel:[1,0]
	v_mad_i64_i32 v[92:93], s[0:1], v44, s22, v[20:21]
	v_pk_add_f32 v[18:19], v[90:91], v[18:19]
	v_mov_b32_e32 v91, v19
	v_mov_b32_e32 v90, v18
	s_nop 0
	v_permlane32_swap_b32_e32 v91, v19
	v_permlane32_swap_b32_e32 v90, v18
	v_addc_co_u32_e32 v17, vcc, 0, v15, vcc
	v_lshl_add_u64 v[94:95], v[92:93], 0, v[0:1]
	global_load_dword v60, v[16:17], off offset:512
	s_waitcnt lgkmcnt(0)
	v_pk_add_f32 v[18:19], v[18:19], v[90:91]
	v_mov_b32_e32 v91, v19
	v_mov_b32_e32 v90, v18
	s_nop 0
	v_permlane16_swap_b32_e32 v91, v19
	v_permlane16_swap_b32_e32 v90, v18
	v_lshl_add_u64 v[14:15], v[14:15], 0, s[34:35]
	global_load_dword v58, v[16:17], off offset:2944
	global_load_dword v57, v[14:15], off offset:256
	global_load_dword v56, v[14:15], off offset:512
	global_load_dword v55, v[14:15], off offset:768
	global_load_dword v54, v[14:15], off offset:1024
	global_load_dword v53, v[14:15], off offset:1280
	global_load_dword v52, v[14:15], off offset:1536
	global_load_dword v51, v[14:15], off offset:1792
	v_add_u32_e32 v44, s4, v44
	s_waitcnt lgkmcnt(0)
	v_pk_add_f32 v[18:19], v[18:19], v[90:91]
	s_nop 1
	v_add_f32_dpp v19, v19, v19 row_ror:8 row_mask:0xf bank_mask:0xf
	v_add_f32_dpp v18, v18, v18 row_ror:8 row_mask:0xf bank_mask:0xf
	s_waitcnt lgkmcnt(0)
	s_nop 1
	v_add_f32_dpp v19, v19, v19 row_ror:4 row_mask:0xf bank_mask:0xf
	v_add_f32_dpp v18, v18, v18 row_ror:4 row_mask:0xf bank_mask:0xf
	s_waitcnt lgkmcnt(0)
	s_nop 1
	v_add_f32_dpp v19, v19, v19 quad_perm:[2,3,0,1] row_mask:0xf bank_mask:0xf
	v_add_f32_dpp v18, v18, v18 quad_perm:[2,3,0,1] row_mask:0xf bank_mask:0xf
	s_waitcnt lgkmcnt(0)
	s_nop 1
	v_add_f32_dpp v91, v19, v19 quad_perm:[1,0,3,2] row_mask:0xf bank_mask:0xf
	v_add_f32_dpp v90, v18, v18 quad_perm:[1,0,3,2] row_mask:0xf bank_mask:0xf
	s_waitcnt lgkmcnt(0)
; DI unsigned pk2(float lo, float hi) { const f32x2 v = {lo, hi}; return __builtin_bit_cast(unsigned, __builtin_convertvector(v, bf16v2_t)); }
; DI float wave_sum(float v) { for (int o = 32; o; o >>= 1) v += __shfl_xor(v, o); return v; }
; DI void run_phase(const Params& p, int ph, unsigned char* smem, const int tid, const int rep) {
;     ...
;               for (int u = 0; u < 4; ++u) { const int t = t0 + u; bf16_t* pr = proj + (size_t)t * PLD;
;                   { const u32x2 v = vq[u]; const float a0 = __uint_as_float(v[0] << 16), a1 = __uint_as_float(v[0] & 0xffff0000u), a2 = __uint_as_float(v[1] << 16), a3 = __uint_as_float(v[1] & 0xffff0000u);
;                     const float rs = rsqrtf(wave_sum(a0 * a0 + a1 * a1 + a2 * a2 + a3 * a3) * (1.f / 256.f) + NEPS);
;                     u32x2 o; o[0] = pk2(a0 * rs * ggq[0], a1 * rs * ggq[1]); o[1] = pk2(a2 * rs * ggq[2], a3 * rs * ggq[3]); *(u32x2*)(mlaa + (size_t)t * 384 + 4 * lane) = o; }
;                   { const unsigned v = vkv[u]; const float a0 = __uint_as_float(v << 16), a1 = __uint_as_float(v & 0xffff0000u);
;                     const float rs = rsqrtf(wave_sum(a0 * a0 + a1 * a1) * (1.f / 128.f) + NEPS);
;                     *(unsigned*)(mlaa + (size_t)t * 384 + 256 + 2 * lane) = pk2(a0 * rs * gkv0, a1 * rs * gkv1); }
; #pragma unroll
;                   for (int hq = 0; hq < 8; ++hq) { const unsigned v = vf[u][hq]; const float a0 = __uint_as_float(v << 16), a1 = __uint_as_float(v & 0xffff0000u);
;                     const float rs = rsqrtf(wave_sum(a0 * a0 + a1 * a1) * (1.f / 128.f) + NEPS) * ((hq < 4) ? 0.08838834764831845f * LOG2E : 1.f);
;                     *(unsigned*)(pr + 3520 + hq * 128 + 2 * lane) = pk2(a0 * rs * ((hq < 4) ? fq0 : fk0), a1 * rs * ((hq < 4) ? fq1 : fk1)); } } } }
	v_mov_b64_e32 v[18:19], s[72:73]
	v_pk_fma_f32 v[90:91], v[90:91], s[96:97], v[18:19] op_sel_hi:[1,1,0]
	s_nop 0
	v_cmp_gt_f32_e64 s[0:1], s77, v91
	v_cmp_gt_f32_e32 vcc, s77, v90
	s_nop 0
	v_rsq_f32_e32 v89, v91
	s_nop 0
	v_mov_b32_e32 v98, v89
	v_pk_mul_f32 v[42:43], v[98:99], v[42:43] op_sel_hi:[0,1]
	v_pk_mul_f32 v[38:39], v[98:99], v[38:39] op_sel_hi:[0,1]
	v_pk_mul_f32 v[42:43], v[2:3], v[42:43]
	v_pk_mul_f32 v[38:39], v[4:5], v[38:39]
	v_cvt_pk_bf16_f32 v42, v42, v43
	v_cvt_pk_bf16_f32 v43, v38, v39
	v_rsq_f32_e32 v38, v90
	global_store_dwordx2 v[94:95], v[42:43], off
	v_and_b32_e32 v89, 0xffff0000, v87
	v_pk_mul_f32 v[38:39], v[38:39], v[96:97] op_sel_hi:[0,1]
	v_pk_mul_f32 v[38:39], v[6:7], v[38:39]
	s_nop 0
	v_cvt_pk_bf16_f32 v42, v38, v39
	v_lshl_add_u64 v[38:39], v[92:93], 0, v[12:13]
	global_store_dword v[38:39], v42, off offset:512
	v_lshlrev_b32_e32 v38, 16, v88
	v_and_b32_e32 v39, 0xffff0000, v88
	v_lshlrev_b32_e32 v88, 16, v87
	v_pk_mul_f32 v[42:43], v[38:39], v[38:39]
	v_pk_mul_f32 v[90:91], v[88:89], v[88:89]
	v_mov_b32_e32 v93, v42
	v_mov_b32_e32 v92, v90
	v_mov_b32_e32 v42, v91
	v_pk_add_f32 v[42:43], v[92:93], v[42:43]
	v_mov_b32_e32 v91, v43
	v_mov_b32_e32 v90, v42
	s_nop 0
	v_permlane32_swap_b32_e32 v91, v43
	v_permlane32_swap_b32_e32 v90, v42
	s_waitcnt lgkmcnt(0)
	v_pk_add_f32 v[42:43], v[42:43], v[90:91]
	v_mov_b32_e32 v91, v43
	v_mov_b32_e32 v90, v42
	s_nop 0
	v_permlane16_swap_b32_e32 v91, v43
	v_permlane16_swap_b32_e32 v90, v42
	s_waitcnt lgkmcnt(0)
	v_pk_add_f32 v[42:43], v[42:43], v[90:91]
	s_nop 1
	v_add_f32_dpp v43, v43, v43 row_ror:8 row_mask:0xf bank_mask:0xf
	v_add_f32_dpp v42, v42, v42 row_ror:8 row_mask:0xf bank_mask:0xf
	s_waitcnt lgkmcnt(0)
	s_nop 1
	v_add_f32_dpp v43, v43, v43 row_ror:4 row_mask:0xf bank_mask:0xf
	v_add_f32_dpp v42, v42, v42 row_ror:4 row_mask:0xf bank_mask:0xf
	s_waitcnt lgkmcnt(0)
	s_nop 1
	v_add_f32_dpp v43, v43, v43 quad_perm:[2,3,0,1] row_mask:0xf bank_mask:0xf
	v_add_f32_dpp v42, v42, v42 quad_perm:[2,3,0,1] row_mask:0xf bank_mask:0xf
	s_waitcnt lgkmcnt(0)
	s_nop 1
	v_add_f32_dpp v43, v43, v43 quad_perm:[1,0,3,2] row_mask:0xf bank_mask:0xf
	v_add_f32_dpp v42, v42, v42 quad_perm:[1,0,3,2] row_mask:0xf bank_mask:0xf
	s_waitcnt lgkmcnt(0)
	s_nop 0
	v_pk_fma_f32 v[42:43], v[42:43], s[96:97], v[18:19] op_sel_hi:[1,0,0]
	s_nop 0
	v_mul_f32_e32 v87, 0x4b800000, v43
	v_cmp_gt_f32_e64 s[0:1], s77, v43
	v_cmp_gt_f32_e32 vcc, s77, v42
	s_nop 0
	v_cndmask_b32_e64 v43, v43, v87, s[0:1]
	v_rsq_f32_e32 v43, v43
	s_nop 0
	v_mul_f32_e32 v87, 0x45800000, v43
	v_cndmask_b32_e64 v43, v43, v87, s[0:1]
	v_mul_f32_e32 v90, 0x3e0293ee, v43
	v_pk_mul_f32 v[38:39], v[90:91], v[38:39] op_sel_hi:[0,1]
	v_pk_mul_f32 v[38:39], v[8:9], v[38:39]
	v_and_b32_e32 v43, 0xffff0000, v85
	v_cvt_pk_bf16_f32 v38, v38, v39
	global_store_dword v[36:37], v38, off offset:2944
	v_rsq_f32_e32 v36, v42
	v_lshlrev_b32_e32 v42, 16, v85
	v_mul_f32_e32 v36, 0x3e0293ee, v36
	v_pk_mul_f32 v[36:37], v[36:37], v[88:89] op_sel_hi:[0,1]
	v_pk_mul_f32 v[36:37], v[8:9], v[36:37]
	s_nop 0
	v_cvt_pk_bf16_f32 v36, v36, v37
	global_store_dword v[34:35], v36, off offset:256
	v_lshlrev_b32_e32 v36, 16, v86
	v_and_b32_e32 v37, 0xffff0000, v86
	v_pk_mul_f32 v[38:39], v[36:37], v[36:37]
	v_pk_mul_f32 v[86:87], v[42:43], v[42:43]
	v_mov_b32_e32 v89, v38
	v_mov_b32_e32 v88, v86
	v_mov_b32_e32 v38, v87
	v_pk_add_f32 v[38:39], v[88:89], v[38:39]
	v_mov_b32_e32 v87, v39
	v_mov_b32_e32 v86, v38
	s_nop 0
	v_permlane32_swap_b32_e32 v87, v39
	v_permlane32_swap_b32_e32 v86, v38
	s_waitcnt lgkmcnt(0)
	v_pk_add_f32 v[38:39], v[38:39], v[86:87]
	v_mov_b32_e32 v87, v39
	v_mov_b32_e32 v86, v38
	s_nop 0
	v_permlane16_swap_b32_e32 v87, v39
	v_permlane16_swap_b32_e32 v86, v38
	s_waitcnt lgkmcnt(0)
	v_pk_add_f32 v[38:39], v[38:39], v[86:87]
	s_nop 1
	v_add_f32_dpp v39, v39, v39 row_ror:8 row_mask:0xf bank_mask:0xf
	v_add_f32_dpp v38, v38, v38 row_ror:8 row_mask:0xf bank_mask:0xf
	s_waitcnt lgkmcnt(0)
	s_nop 1
	v_add_f32_dpp v39, v39, v39 row_ror:4 row_mask:0xf bank_mask:0xf
	v_add_f32_dpp v38, v38, v38 row_ror:4 row_mask:0xf bank_mask:0xf
	s_waitcnt lgkmcnt(0)
	s_nop 1
	v_add_f32_dpp v39, v39, v39 quad_perm:[2,3,0,1] row_mask:0xf bank_mask:0xf
	v_add_f32_dpp v38, v38, v38 quad_perm:[2,3,0,1] row_mask:0xf bank_mask:0xf
	s_waitcnt lgkmcnt(0)
	s_nop 1
	v_add_f32_dpp v39, v39, v39 quad_perm:[1,0,3,2] row_mask:0xf bank_mask:0xf
	v_add_f32_dpp v38, v38, v38 quad_perm:[1,0,3,2] row_mask:0xf bank_mask:0xf
	s_waitcnt lgkmcnt(0)
	s_nop 0
	v_pk_fma_f32 v[38:39], v[38:39], s[96:97], v[18:19] op_sel_hi:[1,0,0]
	s_nop 0
	v_mul_f32_e32 v85, 0x4b800000, v39
	v_cmp_gt_f32_e64 s[0:1], s77, v39
	v_cmp_gt_f32_e32 vcc, s77, v38
	s_nop 0
	v_cndmask_b32_e64 v39, v39, v85, s[0:1]
	v_rsq_f32_e32 v39, v39
	s_nop 0
	v_mul_f32_e32 v85, 0x45800000, v39
	v_cndmask_b32_e64 v39, v39, v85, s[0:1]
	v_mul_f32_e32 v86, 0x3e0293ee, v39
	v_pk_mul_f32 v[36:37], v[86:87], v[36:37] op_sel_hi:[0,1]
	v_pk_mul_f32 v[36:37], v[8:9], v[36:37]
	s_nop 0
	v_cvt_pk_bf16_f32 v36, v36, v37
	global_store_dword v[34:35], v36, off offset:512
	v_rsq_f32_e32 v36, v38
	s_nop 0
	v_mul_f32_e32 v36, 0x3e0293ee, v36
	v_pk_mul_f32 v[36:37], v[36:37], v[42:43] op_sel_hi:[0,1]
	v_pk_mul_f32 v[36:37], v[8:9], v[36:37]
	v_lshlrev_b32_e32 v42, 16, v83
	v_cvt_pk_bf16_f32 v36, v36, v37
	global_store_dword v[34:35], v36, off offset:768
	v_lshlrev_b32_e32 v36, 16, v84
	v_and_b32_e32 v37, 0xffff0000, v84
	v_and_b32_e32 v43, 0xffff0000, v83
	v_pk_mul_f32 v[38:39], v[36:37], v[36:37]
	v_pk_mul_f32 v[84:85], v[42:43], v[42:43]
	v_mov_b32_e32 v87, v38
	v_mov_b32_e32 v86, v84
	v_mov_b32_e32 v38, v85
	v_pk_add_f32 v[38:39], v[86:87], v[38:39]
	v_mov_b32_e32 v85, v39
	v_mov_b32_e32 v84, v38
	s_nop 0
	v_permlane32_swap_b32_e32 v85, v39
	v_permlane32_swap_b32_e32 v84, v38
	s_waitcnt lgkmcnt(0)
; DI unsigned pk2(float lo, float hi) { const f32x2 v = {lo, hi}; return __builtin_bit_cast(unsigned, __builtin_convertvector(v, bf16v2_t)); }
; DI float wave_sum(float v) { for (int o = 32; o; o >>= 1) v += __shfl_xor(v, o); return v; }
; DI void run_phase(const Params& p, int ph, unsigned char* smem, const int tid, const int rep) {
;     ...
;               for (int u = 0; u < 4; ++u) { const int t = t0 + u; bf16_t* pr = proj + (size_t)t * PLD;
;                   { const u32x2 v = vq[u]; const float a0 = __uint_as_float(v[0] << 16), a1 = __uint_as_float(v[0] & 0xffff0000u), a2 = __uint_as_float(v[1] << 16), a3 = __uint_as_float(v[1] & 0xffff0000u);
;                     const float rs = rsqrtf(wave_sum(a0 * a0 + a1 * a1 + a2 * a2 + a3 * a3) * (1.f / 256.f) + NEPS);
;                     u32x2 o; o[0] = pk2(a0 * rs * ggq[0], a1 * rs * ggq[1]); o[1] = pk2(a2 * rs * ggq[2], a3 * rs * ggq[3]); *(u32x2*)(mlaa + (size_t)t * 384 + 4 * lane) = o; }
;                   { const unsigned v = vkv[u]; const float a0 = __uint_as_float(v << 16), a1 = __uint_as_float(v & 0xffff0000u);
;                     const float rs = rsqrtf(wave_sum(a0 * a0 + a1 * a1) * (1.f / 128.f) + NEPS);
;                     *(unsigned*)(mlaa + (size_t)t * 384 + 256 + 2 * lane) = pk2(a0 * rs * gkv0, a1 * rs * gkv1); }
; #pragma unroll
;                   for (int hq = 0; hq < 8; ++hq) { const unsigned v = vf[u][hq]; const float a0 = __uint_as_float(v << 16), a1 = __uint_as_float(v & 0xffff0000u);
;                     const float rs = rsqrtf(wave_sum(a0 * a0 + a1 * a1) * (1.f / 128.f) + NEPS) * ((hq < 4) ? 0.08838834764831845f * LOG2E : 1.f);
;                     *(unsigned*)(pr + 3520 + hq * 128 + 2 * lane) = pk2(a0 * rs * ((hq < 4) ? fq0 : fk0), a1 * rs * ((hq < 4) ? fq1 : fk1)); } } } }
	v_pk_add_f32 v[38:39], v[38:39], v[84:85]
	v_mov_b32_e32 v85, v39
	v_mov_b32_e32 v84, v38
	s_nop 0
	v_permlane16_swap_b32_e32 v85, v39
	v_permlane16_swap_b32_e32 v84, v38
	s_waitcnt lgkmcnt(0)
	v_pk_add_f32 v[38:39], v[38:39], v[84:85]
	s_nop 1
	v_add_f32_dpp v39, v39, v39 row_ror:8 row_mask:0xf bank_mask:0xf
	v_add_f32_dpp v38, v38, v38 row_ror:8 row_mask:0xf bank_mask:0xf
	s_waitcnt lgkmcnt(0)
	s_nop 1
	v_add_f32_dpp v39, v39, v39 row_ror:4 row_mask:0xf bank_mask:0xf
	v_add_f32_dpp v38, v38, v38 row_ror:4 row_mask:0xf bank_mask:0xf
	s_waitcnt lgkmcnt(0)
	s_nop 1
	v_add_f32_dpp v39, v39, v39 quad_perm:[2,3,0,1] row_mask:0xf bank_mask:0xf
	v_add_f32_dpp v38, v38, v38 quad_perm:[2,3,0,1] row_mask:0xf bank_mask:0xf
	s_waitcnt lgkmcnt(0)
	s_nop 1
	v_add_f32_dpp v39, v39, v39 quad_perm:[1,0,3,2] row_mask:0xf bank_mask:0xf
	v_add_f32_dpp v38, v38, v38 quad_perm:[1,0,3,2] row_mask:0xf bank_mask:0xf
	s_waitcnt lgkmcnt(0)
	s_nop 0
	v_pk_fma_f32 v[38:39], v[38:39], s[96:97], v[18:19] op_sel_hi:[1,0,0]
	s_nop 0
	v_mul_f32_e32 v83, 0x4b800000, v39
	v_cmp_gt_f32_e64 s[0:1], s77, v39
	v_cmp_gt_f32_e32 vcc, s77, v38
	s_nop 0
	v_cndmask_b32_e64 v39, v39, v83, s[0:1]
	v_rsq_f32_e32 v39, v39
	s_nop 0
	v_mul_f32_e32 v83, 0x45800000, v39
	v_cndmask_b32_e64 v84, v39, v83, s[0:1]
	v_pk_mul_f32 v[36:37], v[84:85], v[36:37] op_sel_hi:[0,1]
	v_pk_mul_f32 v[36:37], v[10:11], v[36:37]
	s_nop 0
	v_cvt_pk_bf16_f32 v36, v36, v37
	global_store_dword v[34:35], v36, off offset:1024
	v_rsq_f32_e32 v36, v38
	s_nop 0
	v_pk_mul_f32 v[36:37], v[36:37], v[42:43] op_sel_hi:[0,1]
	v_pk_mul_f32 v[36:37], v[10:11], v[36:37]
	v_lshlrev_b32_e32 v42, 16, v81
	v_cvt_pk_bf16_f32 v36, v36, v37
	global_store_dword v[34:35], v36, off offset:1280
	v_lshlrev_b32_e32 v36, 16, v82
	v_and_b32_e32 v37, 0xffff0000, v82
	v_and_b32_e32 v43, 0xffff0000, v81
	v_pk_mul_f32 v[38:39], v[36:37], v[36:37]
	v_pk_mul_f32 v[82:83], v[42:43], v[42:43]
	v_mov_b32_e32 v85, v38
	v_mov_b32_e32 v84, v82
	v_mov_b32_e32 v38, v83
	v_pk_add_f32 v[38:39], v[84:85], v[38:39]
	v_mov_b32_e32 v83, v39
	v_mov_b32_e32 v82, v38
	s_nop 0
	v_permlane32_swap_b32_e32 v83, v39
	v_permlane32_swap_b32_e32 v82, v38
	v_lshlrev_b32_e32 v84, 16, v80
	v_and_b32_e32 v85, 0xffff0000, v80
	s_waitcnt lgkmcnt(0)
	v_pk_add_f32 v[38:39], v[38:39], v[82:83]
	v_mov_b32_e32 v83, v39
	v_mov_b32_e32 v82, v38
	s_nop 0
	v_permlane16_swap_b32_e32 v83, v39
	v_permlane16_swap_b32_e32 v82, v38
	s_waitcnt lgkmcnt(0)
	v_pk_add_f32 v[38:39], v[38:39], v[82:83]
	s_nop 1
	v_add_f32_dpp v39, v39, v39 row_ror:8 row_mask:0xf bank_mask:0xf
	v_add_f32_dpp v38, v38, v38 row_ror:8 row_mask:0xf bank_mask:0xf
	s_waitcnt lgkmcnt(0)
	s_nop 1
	v_add_f32_dpp v39, v39, v39 row_ror:4 row_mask:0xf bank_mask:0xf
	v_add_f32_dpp v38, v38, v38 row_ror:4 row_mask:0xf bank_mask:0xf
	s_waitcnt lgkmcnt(0)
	s_nop 1
	v_add_f32_dpp v39, v39, v39 quad_perm:[2,3,0,1] row_mask:0xf bank_mask:0xf
	v_add_f32_dpp v38, v38, v38 quad_perm:[2,3,0,1] row_mask:0xf bank_mask:0xf
	s_waitcnt lgkmcnt(0)
	s_nop 1
	v_add_f32_dpp v39, v39, v39 quad_perm:[1,0,3,2] row_mask:0xf bank_mask:0xf
	v_add_f32_dpp v38, v38, v38 quad_perm:[1,0,3,2] row_mask:0xf bank_mask:0xf
	s_waitcnt lgkmcnt(0)
	s_nop 0
	v_pk_fma_f32 v[38:39], v[38:39], s[96:97], v[18:19] op_sel_hi:[1,0,0]
	s_nop 0
	v_mul_f32_e32 v81, 0x4b800000, v39
	v_cmp_gt_f32_e64 s[0:1], s77, v39
	v_cmp_gt_f32_e32 vcc, s77, v38
	s_nop 0
	v_cndmask_b32_e64 v39, v39, v81, s[0:1]
	v_rsq_f32_e32 v39, v39
	s_nop 0
	v_mul_f32_e32 v81, 0x45800000, v39
	v_cndmask_b32_e64 v82, v39, v81, s[0:1]
	v_pk_mul_f32 v[36:37], v[82:83], v[36:37] op_sel_hi:[0,1]
	v_pk_mul_f32 v[36:37], v[10:11], v[36:37]
	v_pk_mul_f32 v[80:81], v[84:85], v[84:85]
	v_cvt_pk_bf16_f32 v36, v36, v37
	global_store_dword v[34:35], v36, off offset:1536
	v_rsq_f32_e32 v36, v38
	s_nop 0
	v_pk_mul_f32 v[36:37], v[36:37], v[42:43] op_sel_hi:[0,1]
	v_pk_mul_f32 v[36:37], v[10:11], v[36:37]
	s_nop 0
	v_cvt_pk_bf16_f32 v36, v36, v37
	global_store_dword v[34:35], v36, off offset:1792
	v_and_b32_e32 v37, 0xffff0000, v41
	v_and_b32_e32 v36, s0, v40
	v_mov_b32_e32 v35, v37
	v_pk_mul_f32 v[38:39], v[36:37], v[36:37]
	v_and_b32_e32 v37, 0xffff0000, v40
	v_lshlrev_b32_e32 v36, 16, v40
	v_mul_f32_e32 v38, v37, v37
	v_lshlrev_b32_e32 v34, 16, v41
	v_pk_fma_f32 v[40:41], v[36:37], v[36:37], v[38:39] op_sel_hi:[1,1,0]
	v_mov_b32_e32 v38, v80
	v_pk_fma_f32 v[40:41], v[34:35], v[34:35], v[40:41]
	v_mad_i64_i32 v[42:43], s[0:1], v79, s22, v[20:21]
	v_pk_mov_b32 v[40:41], v[80:81], v[40:41] op_sel:[1,0]
	v_lshl_add_u64 v[82:83], v[42:43], 0, v[0:1]
	v_pk_add_f32 v[38:39], v[38:39], v[40:41]
	v_mov_b32_e32 v41, v39
	v_mov_b32_e32 v40, v38
	s_nop 0
	v_permlane32_swap_b32_e32 v41, v39
	v_permlane32_swap_b32_e32 v40, v38
	s_waitcnt lgkmcnt(0)
	v_pk_add_f32 v[38:39], v[38:39], v[40:41]
	v_mov_b32_e32 v41, v39
	v_mov_b32_e32 v40, v38
	s_nop 0
	v_permlane16_swap_b32_e32 v41, v39
	v_permlane16_swap_b32_e32 v40, v38
	s_waitcnt lgkmcnt(0)
	v_pk_add_f32 v[38:39], v[38:39], v[40:41]
	s_nop 1
	v_add_f32_dpp v39, v39, v39 row_ror:8 row_mask:0xf bank_mask:0xf
	v_add_f32_dpp v38, v38, v38 row_ror:8 row_mask:0xf bank_mask:0xf
	s_waitcnt lgkmcnt(0)
	s_nop 1
	v_add_f32_dpp v39, v39, v39 row_ror:4 row_mask:0xf bank_mask:0xf
	v_add_f32_dpp v38, v38, v38 row_ror:4 row_mask:0xf bank_mask:0xf
	s_waitcnt lgkmcnt(0)
	s_nop 1
	v_add_f32_dpp v39, v39, v39 quad_perm:[2,3,0,1] row_mask:0xf bank_mask:0xf
	v_add_f32_dpp v38, v38, v38 quad_perm:[2,3,0,1] row_mask:0xf bank_mask:0xf
	s_waitcnt lgkmcnt(0)
	s_nop 1
	v_add_f32_dpp v39, v39, v39 quad_perm:[1,0,3,2] row_mask:0xf bank_mask:0xf
	v_add_f32_dpp v38, v38, v38 quad_perm:[1,0,3,2] row_mask:0xf bank_mask:0xf
	s_waitcnt lgkmcnt(0)
; DI unsigned pk2(float lo, float hi) { const f32x2 v = {lo, hi}; return __builtin_bit_cast(unsigned, __builtin_convertvector(v, bf16v2_t)); }
; DI float wave_sum(float v) { for (int o = 32; o; o >>= 1) v += __shfl_xor(v, o); return v; }
; DI void run_phase(const Params& p, int ph, unsigned char* smem, const int tid, const int rep) {
;     ...
;               for (int u = 0; u < 4; ++u) { const int t = t0 + u; bf16_t* pr = proj + (size_t)t * PLD;
;                   { const u32x2 v = vq[u]; const float a0 = __uint_as_float(v[0] << 16), a1 = __uint_as_float(v[0] & 0xffff0000u), a2 = __uint_as_float(v[1] << 16), a3 = __uint_as_float(v[1] & 0xffff0000u);
;                     const float rs = rsqrtf(wave_sum(a0 * a0 + a1 * a1 + a2 * a2 + a3 * a3) * (1.f / 256.f) + NEPS);
;                     u32x2 o; o[0] = pk2(a0 * rs * ggq[0], a1 * rs * ggq[1]); o[1] = pk2(a2 * rs * ggq[2], a3 * rs * ggq[3]); *(u32x2*)(mlaa + (size_t)t * 384 + 4 * lane) = o; }
;                   { const unsigned v = vkv[u]; const float a0 = __uint_as_float(v << 16), a1 = __uint_as_float(v & 0xffff0000u);
;                     const float rs = rsqrtf(wave_sum(a0 * a0 + a1 * a1) * (1.f / 128.f) + NEPS);
;                     *(unsigned*)(mlaa + (size_t)t * 384 + 256 + 2 * lane) = pk2(a0 * rs * gkv0, a1 * rs * gkv1); }
; #pragma unroll
;                   for (int hq = 0; hq < 8; ++hq) { const unsigned v = vf[u][hq]; const float a0 = __uint_as_float(v << 16), a1 = __uint_as_float(v & 0xffff0000u);
;                     const float rs = rsqrtf(wave_sum(a0 * a0 + a1 * a1) * (1.f / 128.f) + NEPS) * ((hq < 4) ? 0.08838834764831845f * LOG2E : 1.f);
;                     *(unsigned*)(pr + 3520 + hq * 128 + 2 * lane) = pk2(a0 * rs * ((hq < 4) ? fq0 : fk0), a1 * rs * ((hq < 4) ? fq1 : fk1)); } } } }
	s_nop 0
	v_pk_fma_f32 v[38:39], v[38:39], s[96:97], v[18:19] op_sel_hi:[1,1,0]
	s_nop 0
	v_mul_f32_e32 v40, 0x4b800000, v39
	v_cmp_gt_f32_e64 s[0:1], s77, v39
	v_cmp_gt_f32_e32 vcc, s77, v38
	s_nop 0
	v_cndmask_b32_e64 v39, v39, v40, s[0:1]
	v_rsq_f32_e32 v39, v39
	s_nop 0
	v_mul_f32_e32 v40, 0x45800000, v39
	v_cndmask_b32_e64 v40, v39, v40, s[0:1]
	v_pk_mul_f32 v[36:37], v[40:41], v[36:37] op_sel_hi:[0,1]
	v_pk_mul_f32 v[34:35], v[40:41], v[34:35] op_sel_hi:[0,1]
	v_pk_mul_f32 v[36:37], v[2:3], v[36:37]
	v_pk_mul_f32 v[34:35], v[4:5], v[34:35]
	v_cvt_pk_bf16_f32 v36, v36, v37
	v_cvt_pk_bf16_f32 v37, v34, v35
	v_rsq_f32_e32 v34, v38
	global_store_dwordx2 v[82:83], v[36:37], off
	v_lshlrev_b32_e32 v38, 16, v77
	v_and_b32_e32 v39, 0xffff0000, v77
	v_pk_mul_f32 v[34:35], v[34:35], v[84:85] op_sel_hi:[0,1]
	v_pk_mul_f32 v[34:35], v[6:7], v[34:35]
	v_pk_mul_f32 v[40:41], v[38:39], v[38:39]
	v_cvt_pk_bf16_f32 v36, v34, v35
	v_lshl_add_u64 v[34:35], v[42:43], 0, v[12:13]
	global_store_dword v[34:35], v36, off offset:512
	v_lshlrev_b32_e32 v34, 16, v78
	v_and_b32_e32 v35, 0xffff0000, v78
	v_pk_mul_f32 v[36:37], v[34:35], v[34:35]
	v_mov_b32_e32 v42, v40
	v_mov_b32_e32 v43, v36
	v_mov_b32_e32 v36, v41
	v_pk_add_f32 v[36:37], v[42:43], v[36:37]
	v_mov_b32_e32 v41, v37
	v_mov_b32_e32 v40, v36
	s_nop 0
	v_permlane32_swap_b32_e32 v41, v37
	v_permlane32_swap_b32_e32 v40, v36
	s_waitcnt lgkmcnt(0)
	v_pk_add_f32 v[36:37], v[36:37], v[40:41]
	v_mov_b32_e32 v41, v37
	v_mov_b32_e32 v40, v36
	s_nop 0
	v_permlane16_swap_b32_e32 v41, v37
	v_permlane16_swap_b32_e32 v40, v36
	s_waitcnt lgkmcnt(0)
	v_pk_add_f32 v[36:37], v[36:37], v[40:41]
	s_nop 1
	v_add_f32_dpp v37, v37, v37 row_ror:8 row_mask:0xf bank_mask:0xf
	v_add_f32_dpp v36, v36, v36 row_ror:8 row_mask:0xf bank_mask:0xf
	s_waitcnt lgkmcnt(0)
	s_nop 1
	v_add_f32_dpp v37, v37, v37 row_ror:4 row_mask:0xf bank_mask:0xf
	v_add_f32_dpp v36, v36, v36 row_ror:4 row_mask:0xf bank_mask:0xf
	s_waitcnt lgkmcnt(0)
	s_nop 1
	v_add_f32_dpp v37, v37, v37 quad_perm:[2,3,0,1] row_mask:0xf bank_mask:0xf
	v_add_f32_dpp v36, v36, v36 quad_perm:[2,3,0,1] row_mask:0xf bank_mask:0xf
	s_waitcnt lgkmcnt(0)
	s_nop 1
	v_add_f32_dpp v37, v37, v37 quad_perm:[1,0,3,2] row_mask:0xf bank_mask:0xf
	v_add_f32_dpp v36, v36, v36 quad_perm:[1,0,3,2] row_mask:0xf bank_mask:0xf
	s_waitcnt lgkmcnt(0)
	s_nop 0
	v_pk_fma_f32 v[36:37], v[36:37], s[96:97], v[18:19] op_sel_hi:[1,0,0]
	s_nop 0
	v_mul_f32_e32 v40, 0x4b800000, v37
	v_cmp_gt_f32_e64 s[0:1], s77, v37
	v_cmp_gt_f32_e32 vcc, s77, v36
	s_nop 0
	v_cndmask_b32_e64 v37, v37, v40, s[0:1]
	v_rsq_f32_e32 v37, v37
	s_nop 0
	v_mul_f32_e32 v40, 0x45800000, v37
	v_cndmask_b32_e64 v37, v37, v40, s[0:1]
	v_mul_f32_e32 v40, 0x3e0293ee, v37
	v_pk_mul_f32 v[34:35], v[40:41], v[34:35] op_sel_hi:[0,1]
	v_pk_mul_f32 v[34:35], v[8:9], v[34:35]
	v_and_b32_e32 v37, 0xffff0000, v75
	v_cvt_pk_bf16_f32 v34, v34, v35
	global_store_dword v[32:33], v34, off offset:2944
	v_rsq_f32_e32 v32, v36
	v_lshlrev_b32_e32 v36, 16, v75
	v_mul_f32_e32 v32, 0x3e0293ee, v32
	v_pk_mul_f32 v[32:33], v[32:33], v[38:39] op_sel_hi:[0,1]
	v_pk_mul_f32 v[32:33], v[8:9], v[32:33]
	v_pk_mul_f32 v[38:39], v[36:37], v[36:37]
	v_cvt_pk_bf16_f32 v32, v32, v33
	global_store_dword v[28:29], v32, off offset:256
	v_lshlrev_b32_e32 v32, 16, v76
	v_and_b32_e32 v33, 0xffff0000, v76
	v_pk_mul_f32 v[34:35], v[32:33], v[32:33]
	v_mov_b32_e32 v40, v38
	v_mov_b32_e32 v41, v34
	v_mov_b32_e32 v34, v39
	v_pk_add_f32 v[34:35], v[40:41], v[34:35]
	v_mov_b32_e32 v39, v35
	v_mov_b32_e32 v38, v34
	s_nop 0
	v_permlane32_swap_b32_e32 v39, v35
	v_permlane32_swap_b32_e32 v38, v34
	s_waitcnt lgkmcnt(0)
	v_pk_add_f32 v[34:35], v[34:35], v[38:39]
	v_mov_b32_e32 v39, v35
	v_mov_b32_e32 v38, v34
	s_nop 0
	v_permlane16_swap_b32_e32 v39, v35
	v_permlane16_swap_b32_e32 v38, v34
	s_waitcnt lgkmcnt(0)
	v_pk_add_f32 v[34:35], v[34:35], v[38:39]
	s_nop 1
	v_add_f32_dpp v35, v35, v35 row_ror:8 row_mask:0xf bank_mask:0xf
	v_add_f32_dpp v34, v34, v34 row_ror:8 row_mask:0xf bank_mask:0xf
	s_waitcnt lgkmcnt(0)
	s_nop 1
	v_add_f32_dpp v35, v35, v35 row_ror:4 row_mask:0xf bank_mask:0xf
	v_add_f32_dpp v34, v34, v34 row_ror:4 row_mask:0xf bank_mask:0xf
	s_waitcnt lgkmcnt(0)
	s_nop 1
	v_add_f32_dpp v35, v35, v35 quad_perm:[2,3,0,1] row_mask:0xf bank_mask:0xf
	v_add_f32_dpp v34, v34, v34 quad_perm:[2,3,0,1] row_mask:0xf bank_mask:0xf
	s_waitcnt lgkmcnt(0)
	s_nop 1
	v_add_f32_dpp v35, v35, v35 quad_perm:[1,0,3,2] row_mask:0xf bank_mask:0xf
	v_add_f32_dpp v34, v34, v34 quad_perm:[1,0,3,2] row_mask:0xf bank_mask:0xf
	s_waitcnt lgkmcnt(0)
	s_nop 0
	v_pk_fma_f32 v[34:35], v[34:35], s[96:97], v[18:19] op_sel_hi:[1,0,0]
	s_nop 0
	v_mul_f32_e32 v38, 0x4b800000, v35
	v_cmp_gt_f32_e64 s[0:1], s77, v35
	v_cmp_gt_f32_e32 vcc, s77, v34
	s_nop 0
	v_cndmask_b32_e64 v35, v35, v38, s[0:1]
	v_rsq_f32_e32 v35, v35
	s_nop 0
	v_mul_f32_e32 v38, 0x45800000, v35
	v_cndmask_b32_e64 v35, v35, v38, s[0:1]
	v_mul_f32_e32 v38, 0x3e0293ee, v35
	v_pk_mul_f32 v[32:33], v[38:39], v[32:33] op_sel_hi:[0,1]
	v_pk_mul_f32 v[32:33], v[8:9], v[32:33]
	s_nop 0
	v_cvt_pk_bf16_f32 v32, v32, v33
	global_store_dword v[28:29], v32, off offset:512
	v_rsq_f32_e32 v32, v34
	s_nop 0
	v_mul_f32_e32 v32, 0x3e0293ee, v32
	v_pk_mul_f32 v[32:33], v[32:33], v[36:37] op_sel_hi:[0,1]
	v_pk_mul_f32 v[32:33], v[8:9], v[32:33]
	v_lshlrev_b32_e32 v36, 16, v73
	v_cvt_pk_bf16_f32 v32, v32, v33
	global_store_dword v[28:29], v32, off offset:768
	v_lshlrev_b32_e32 v32, 16, v74
	v_and_b32_e32 v33, 0xffff0000, v74
	v_and_b32_e32 v37, 0xffff0000, v73
	v_pk_mul_f32 v[34:35], v[32:33], v[32:33]
	v_pk_mul_f32 v[38:39], v[36:37], v[36:37]
	v_mov_b32_e32 v41, v34
	v_mov_b32_e32 v40, v38
	v_mov_b32_e32 v34, v39
	v_pk_add_f32 v[34:35], v[40:41], v[34:35]
	v_mov_b32_e32 v39, v35
	v_mov_b32_e32 v38, v34
	s_nop 0
	v_permlane32_swap_b32_e32 v39, v35
	v_permlane32_swap_b32_e32 v38, v34
	s_waitcnt lgkmcnt(0)
; DI unsigned pk2(float lo, float hi) { const f32x2 v = {lo, hi}; return __builtin_bit_cast(unsigned, __builtin_convertvector(v, bf16v2_t)); }
; DI float wave_sum(float v) { for (int o = 32; o; o >>= 1) v += __shfl_xor(v, o); return v; }
; DI void run_phase(const Params& p, int ph, unsigned char* smem, const int tid, const int rep) {
;     ...
;               for (int u = 0; u < 4; ++u) { const int t = t0 + u; bf16_t* pr = proj + (size_t)t * PLD;
;                   { const u32x2 v = vq[u]; const float a0 = __uint_as_float(v[0] << 16), a1 = __uint_as_float(v[0] & 0xffff0000u), a2 = __uint_as_float(v[1] << 16), a3 = __uint_as_float(v[1] & 0xffff0000u);
;                     const float rs = rsqrtf(wave_sum(a0 * a0 + a1 * a1 + a2 * a2 + a3 * a3) * (1.f / 256.f) + NEPS);
;                     u32x2 o; o[0] = pk2(a0 * rs * ggq[0], a1 * rs * ggq[1]); o[1] = pk2(a2 * rs * ggq[2], a3 * rs * ggq[3]); *(u32x2*)(mlaa + (size_t)t * 384 + 4 * lane) = o; }
;                   { const unsigned v = vkv[u]; const float a0 = __uint_as_float(v << 16), a1 = __uint_as_float(v & 0xffff0000u);
;                     const float rs = rsqrtf(wave_sum(a0 * a0 + a1 * a1) * (1.f / 128.f) + NEPS);
;                     *(unsigned*)(mlaa + (size_t)t * 384 + 256 + 2 * lane) = pk2(a0 * rs * gkv0, a1 * rs * gkv1); }
; #pragma unroll
;                   for (int hq = 0; hq < 8; ++hq) { const unsigned v = vf[u][hq]; const float a0 = __uint_as_float(v << 16), a1 = __uint_as_float(v & 0xffff0000u);
;                     const float rs = rsqrtf(wave_sum(a0 * a0 + a1 * a1) * (1.f / 128.f) + NEPS) * ((hq < 4) ? 0.08838834764831845f * LOG2E : 1.f);
;                     *(unsigned*)(pr + 3520 + hq * 128 + 2 * lane) = pk2(a0 * rs * ((hq < 4) ? fq0 : fk0), a1 * rs * ((hq < 4) ? fq1 : fk1)); } } } }
	v_pk_add_f32 v[34:35], v[34:35], v[38:39]
	v_mov_b32_e32 v39, v35
	v_mov_b32_e32 v38, v34
	s_nop 0
	v_permlane16_swap_b32_e32 v39, v35
	v_permlane16_swap_b32_e32 v38, v34
	s_waitcnt lgkmcnt(0)
	v_pk_add_f32 v[34:35], v[34:35], v[38:39]
	s_nop 1
	v_add_f32_dpp v35, v35, v35 row_ror:8 row_mask:0xf bank_mask:0xf
	v_add_f32_dpp v34, v34, v34 row_ror:8 row_mask:0xf bank_mask:0xf
	s_waitcnt lgkmcnt(0)
	s_nop 1
	v_add_f32_dpp v35, v35, v35 row_ror:4 row_mask:0xf bank_mask:0xf
	v_add_f32_dpp v34, v34, v34 row_ror:4 row_mask:0xf bank_mask:0xf
	s_waitcnt lgkmcnt(0)
	s_nop 1
	v_add_f32_dpp v35, v35, v35 quad_perm:[2,3,0,1] row_mask:0xf bank_mask:0xf
	v_add_f32_dpp v34, v34, v34 quad_perm:[2,3,0,1] row_mask:0xf bank_mask:0xf
	s_waitcnt lgkmcnt(0)
	s_nop 1
	v_add_f32_dpp v35, v35, v35 quad_perm:[1,0,3,2] row_mask:0xf bank_mask:0xf
	v_add_f32_dpp v34, v34, v34 quad_perm:[1,0,3,2] row_mask:0xf bank_mask:0xf
	s_waitcnt lgkmcnt(0)
	s_nop 0
	v_pk_fma_f32 v[34:35], v[34:35], s[96:97], v[18:19] op_sel_hi:[1,0,0]
	s_nop 0
	v_mul_f32_e32 v38, 0x4b800000, v35
	v_cmp_gt_f32_e64 s[0:1], s77, v35
	v_cmp_gt_f32_e32 vcc, s77, v34
	s_nop 0
	v_cndmask_b32_e64 v35, v35, v38, s[0:1]
	v_rsq_f32_e32 v35, v35
	s_nop 0
	v_mul_f32_e32 v38, 0x45800000, v35
	v_cndmask_b32_e64 v38, v35, v38, s[0:1]
	v_pk_mul_f32 v[32:33], v[38:39], v[32:33] op_sel_hi:[0,1]
	v_pk_mul_f32 v[32:33], v[10:11], v[32:33]
	s_nop 0
	v_cvt_pk_bf16_f32 v32, v32, v33
	global_store_dword v[28:29], v32, off offset:1024
	v_rsq_f32_e32 v32, v34
	s_nop 0
	v_pk_mul_f32 v[32:33], v[32:33], v[36:37] op_sel_hi:[0,1]
	v_pk_mul_f32 v[32:33], v[10:11], v[32:33]
	v_lshlrev_b32_e32 v36, 16, v71
	v_cvt_pk_bf16_f32 v32, v32, v33
	global_store_dword v[28:29], v32, off offset:1280
	v_lshlrev_b32_e32 v32, 16, v72
	v_and_b32_e32 v33, 0xffff0000, v72
	v_and_b32_e32 v37, 0xffff0000, v71
	v_pk_mul_f32 v[34:35], v[32:33], v[32:33]
	v_pk_mul_f32 v[38:39], v[36:37], v[36:37]
	v_mov_b32_e32 v41, v34
	v_mov_b32_e32 v40, v38
	v_mov_b32_e32 v34, v39
	v_pk_add_f32 v[34:35], v[40:41], v[34:35]
	v_mov_b32_e32 v39, v35
	v_mov_b32_e32 v38, v34
	s_nop 0
	v_permlane32_swap_b32_e32 v39, v35
	v_permlane32_swap_b32_e32 v38, v34
	v_lshlrev_b32_e32 v40, 16, v70
	v_and_b32_e32 v41, 0xffff0000, v70
	v_pk_mul_f32 v[42:43], v[40:41], v[40:41]
	s_waitcnt lgkmcnt(0)
	v_pk_add_f32 v[34:35], v[34:35], v[38:39]
	v_mov_b32_e32 v39, v35
	v_mov_b32_e32 v38, v34
	s_nop 0
	v_permlane16_swap_b32_e32 v39, v35
	v_permlane16_swap_b32_e32 v38, v34
	s_waitcnt lgkmcnt(0)
	v_pk_add_f32 v[34:35], v[34:35], v[38:39]
	s_nop 1
	v_add_f32_dpp v35, v35, v35 row_ror:8 row_mask:0xf bank_mask:0xf
	v_add_f32_dpp v34, v34, v34 row_ror:8 row_mask:0xf bank_mask:0xf
	s_waitcnt lgkmcnt(0)
	s_nop 1
	v_add_f32_dpp v35, v35, v35 row_ror:4 row_mask:0xf bank_mask:0xf
	v_add_f32_dpp v34, v34, v34 row_ror:4 row_mask:0xf bank_mask:0xf
	s_waitcnt lgkmcnt(0)
	s_nop 1
	v_add_f32_dpp v35, v35, v35 quad_perm:[2,3,0,1] row_mask:0xf bank_mask:0xf
	v_add_f32_dpp v34, v34, v34 quad_perm:[2,3,0,1] row_mask:0xf bank_mask:0xf
	s_waitcnt lgkmcnt(0)
	s_nop 1
	v_add_f32_dpp v35, v35, v35 quad_perm:[1,0,3,2] row_mask:0xf bank_mask:0xf
	v_add_f32_dpp v34, v34, v34 quad_perm:[1,0,3,2] row_mask:0xf bank_mask:0xf
	s_waitcnt lgkmcnt(0)
	s_nop 0
	v_pk_fma_f32 v[34:35], v[34:35], s[96:97], v[18:19] op_sel_hi:[1,0,0]
	s_nop 0
	v_mul_f32_e32 v38, 0x4b800000, v35
	v_cmp_gt_f32_e64 s[0:1], s77, v35
	v_cmp_gt_f32_e32 vcc, s77, v34
	s_nop 0
	v_cndmask_b32_e64 v35, v35, v38, s[0:1]
	v_rsq_f32_e32 v35, v35
	s_nop 0
	v_mul_f32_e32 v38, 0x45800000, v35
	v_cndmask_b32_e64 v38, v35, v38, s[0:1]
	v_pk_mul_f32 v[32:33], v[38:39], v[32:33] op_sel_hi:[0,1]
	v_pk_mul_f32 v[32:33], v[10:11], v[32:33]
	s_nop 0
	v_cvt_pk_bf16_f32 v32, v32, v33
	global_store_dword v[28:29], v32, off offset:1536
	v_rsq_f32_e32 v32, v34
	s_nop 0
	v_pk_mul_f32 v[32:33], v[32:33], v[36:37] op_sel_hi:[0,1]
	v_pk_mul_f32 v[32:33], v[10:11], v[32:33]
	s_nop 0
	v_cvt_pk_bf16_f32 v32, v32, v33
	global_store_dword v[28:29], v32, off offset:1792
	v_and_b32_e32 v33, 0xffff0000, v31
	v_and_b32_e32 v32, s0, v30
	v_mov_b32_e32 v29, v33
	v_pk_mul_f32 v[34:35], v[32:33], v[32:33]
	v_and_b32_e32 v33, 0xffff0000, v30
	v_lshlrev_b32_e32 v32, 16, v30
	v_mul_f32_e32 v30, v33, v33
	v_lshlrev_b32_e32 v28, 16, v31
	v_pk_fma_f32 v[30:31], v[32:33], v[32:33], v[30:31] op_sel_hi:[1,1,0]
	v_mov_b32_e32 v34, v42
	v_pk_fma_f32 v[30:31], v[28:29], v[28:29], v[30:31]
	v_mad_i64_i32 v[36:37], s[0:1], v69, s22, v[20:21]
	v_pk_mov_b32 v[30:31], v[42:43], v[30:31] op_sel:[1,0]
	v_lshl_add_u64 v[38:39], v[36:37], 0, v[0:1]
	v_pk_add_f32 v[30:31], v[34:35], v[30:31]
	v_mov_b32_e32 v35, v31
	v_mov_b32_e32 v34, v30
	s_nop 0
	v_permlane32_swap_b32_e32 v35, v31
	v_permlane32_swap_b32_e32 v34, v30
	s_waitcnt lgkmcnt(0)
	v_pk_add_f32 v[30:31], v[30:31], v[34:35]
	v_mov_b32_e32 v35, v31
	v_mov_b32_e32 v34, v30
	s_nop 0
	v_permlane16_swap_b32_e32 v35, v31
	v_permlane16_swap_b32_e32 v34, v30
	s_waitcnt lgkmcnt(0)
	v_pk_add_f32 v[30:31], v[30:31], v[34:35]
	s_nop 1
	v_add_f32_dpp v31, v31, v31 row_ror:8 row_mask:0xf bank_mask:0xf
	v_add_f32_dpp v30, v30, v30 row_ror:8 row_mask:0xf bank_mask:0xf
	s_waitcnt lgkmcnt(0)
	s_nop 1
	v_add_f32_dpp v31, v31, v31 row_ror:4 row_mask:0xf bank_mask:0xf
	v_add_f32_dpp v30, v30, v30 row_ror:4 row_mask:0xf bank_mask:0xf
	s_waitcnt lgkmcnt(0)
	s_nop 1
	v_add_f32_dpp v31, v31, v31 quad_perm:[2,3,0,1] row_mask:0xf bank_mask:0xf
	v_add_f32_dpp v30, v30, v30 quad_perm:[2,3,0,1] row_mask:0xf bank_mask:0xf
	s_waitcnt lgkmcnt(0)
	s_nop 1
	v_add_f32_dpp v31, v31, v31 quad_perm:[1,0,3,2] row_mask:0xf bank_mask:0xf
	v_add_f32_dpp v30, v30, v30 quad_perm:[1,0,3,2] row_mask:0xf bank_mask:0xf
	s_waitcnt lgkmcnt(0)
; DI unsigned pk2(float lo, float hi) { const f32x2 v = {lo, hi}; return __builtin_bit_cast(unsigned, __builtin_convertvector(v, bf16v2_t)); }
; DI float wave_sum(float v) { for (int o = 32; o; o >>= 1) v += __shfl_xor(v, o); return v; }
; DI void run_phase(const Params& p, int ph, unsigned char* smem, const int tid, const int rep) {
;     ...
;               for (int u = 0; u < 4; ++u) { const int t = t0 + u; bf16_t* pr = proj + (size_t)t * PLD;
;                   { const u32x2 v = vq[u]; const float a0 = __uint_as_float(v[0] << 16), a1 = __uint_as_float(v[0] & 0xffff0000u), a2 = __uint_as_float(v[1] << 16), a3 = __uint_as_float(v[1] & 0xffff0000u);
;                     const float rs = rsqrtf(wave_sum(a0 * a0 + a1 * a1 + a2 * a2 + a3 * a3) * (1.f / 256.f) + NEPS);
;                     u32x2 o; o[0] = pk2(a0 * rs * ggq[0], a1 * rs * ggq[1]); o[1] = pk2(a2 * rs * ggq[2], a3 * rs * ggq[3]); *(u32x2*)(mlaa + (size_t)t * 384 + 4 * lane) = o; }
;                   { const unsigned v = vkv[u]; const float a0 = __uint_as_float(v << 16), a1 = __uint_as_float(v & 0xffff0000u);
;                     const float rs = rsqrtf(wave_sum(a0 * a0 + a1 * a1) * (1.f / 128.f) + NEPS);
;                     *(unsigned*)(mlaa + (size_t)t * 384 + 256 + 2 * lane) = pk2(a0 * rs * gkv0, a1 * rs * gkv1); }
; #pragma unroll
;                   for (int hq = 0; hq < 8; ++hq) { const unsigned v = vf[u][hq]; const float a0 = __uint_as_float(v << 16), a1 = __uint_as_float(v & 0xffff0000u);
;                     const float rs = rsqrtf(wave_sum(a0 * a0 + a1 * a1) * (1.f / 128.f) + NEPS) * ((hq < 4) ? 0.08838834764831845f * LOG2E : 1.f);
;                     *(unsigned*)(pr + 3520 + hq * 128 + 2 * lane) = pk2(a0 * rs * ((hq < 4) ? fq0 : fk0), a1 * rs * ((hq < 4) ? fq1 : fk1)); } } } }
	s_nop 0
	v_pk_fma_f32 v[30:31], v[30:31], s[96:97], v[18:19] op_sel_hi:[1,1,0]
	s_nop 0
	v_mul_f32_e32 v34, 0x4b800000, v31
	v_cmp_gt_f32_e64 s[0:1], s77, v31
	v_cmp_gt_f32_e32 vcc, s77, v30
	s_nop 0
	v_cndmask_b32_e64 v31, v31, v34, s[0:1]
	v_rsq_f32_e32 v31, v31
	s_nop 0
	v_mul_f32_e32 v34, 0x45800000, v31
	v_cndmask_b32_e64 v34, v31, v34, s[0:1]
	v_pk_mul_f32 v[32:33], v[34:35], v[32:33] op_sel_hi:[0,1]
	v_pk_mul_f32 v[28:29], v[34:35], v[28:29] op_sel_hi:[0,1]
	v_pk_mul_f32 v[32:33], v[2:3], v[32:33]
	v_pk_mul_f32 v[28:29], v[4:5], v[28:29]
	v_cvt_pk_bf16_f32 v32, v32, v33
	v_cvt_pk_bf16_f32 v33, v28, v29
	v_rsq_f32_e32 v28, v30
	global_store_dwordx2 v[38:39], v[32:33], off
	v_lshlrev_b32_e32 v32, 16, v67
	v_and_b32_e32 v33, 0xffff0000, v67
	v_pk_mul_f32 v[28:29], v[28:29], v[40:41] op_sel_hi:[0,1]
	v_pk_mul_f32 v[28:29], v[6:7], v[28:29]
	v_pk_mul_f32 v[34:35], v[32:33], v[32:33]
	v_cvt_pk_bf16_f32 v30, v28, v29
	v_lshl_add_u64 v[28:29], v[36:37], 0, v[12:13]
	global_store_dword v[28:29], v30, off offset:512
	v_lshlrev_b32_e32 v28, 16, v68
	v_and_b32_e32 v29, 0xffff0000, v68
	v_pk_mul_f32 v[30:31], v[28:29], v[28:29]
	v_mov_b32_e32 v36, v34
	v_mov_b32_e32 v37, v30
	v_mov_b32_e32 v30, v35
	v_pk_add_f32 v[30:31], v[36:37], v[30:31]
	v_mov_b32_e32 v35, v31
	v_mov_b32_e32 v34, v30
	s_nop 0
	v_permlane32_swap_b32_e32 v35, v31
	v_permlane32_swap_b32_e32 v34, v30
	s_waitcnt lgkmcnt(0)
	v_pk_add_f32 v[30:31], v[30:31], v[34:35]
	v_mov_b32_e32 v35, v31
	v_mov_b32_e32 v34, v30
	s_nop 0
	v_permlane16_swap_b32_e32 v35, v31
	v_permlane16_swap_b32_e32 v34, v30
	s_waitcnt lgkmcnt(0)
	v_pk_add_f32 v[30:31], v[30:31], v[34:35]
	s_nop 1
	v_add_f32_dpp v31, v31, v31 row_ror:8 row_mask:0xf bank_mask:0xf
	v_add_f32_dpp v30, v30, v30 row_ror:8 row_mask:0xf bank_mask:0xf
	s_waitcnt lgkmcnt(0)
	s_nop 1
	v_add_f32_dpp v31, v31, v31 row_ror:4 row_mask:0xf bank_mask:0xf
	v_add_f32_dpp v30, v30, v30 row_ror:4 row_mask:0xf bank_mask:0xf
	s_waitcnt lgkmcnt(0)
	s_nop 1
	v_add_f32_dpp v31, v31, v31 quad_perm:[2,3,0,1] row_mask:0xf bank_mask:0xf
	v_add_f32_dpp v30, v30, v30 quad_perm:[2,3,0,1] row_mask:0xf bank_mask:0xf
	s_waitcnt lgkmcnt(0)
	s_nop 1
	v_add_f32_dpp v31, v31, v31 quad_perm:[1,0,3,2] row_mask:0xf bank_mask:0xf
	v_add_f32_dpp v30, v30, v30 quad_perm:[1,0,3,2] row_mask:0xf bank_mask:0xf
	s_waitcnt lgkmcnt(0)
	s_nop 0
	v_pk_fma_f32 v[30:31], v[30:31], s[96:97], v[18:19] op_sel_hi:[1,0,0]
	s_nop 0
	v_mul_f32_e32 v34, 0x4b800000, v31
	v_cmp_gt_f32_e64 s[0:1], s77, v31
	v_cmp_gt_f32_e32 vcc, s77, v30
	s_nop 0
	v_cndmask_b32_e64 v31, v31, v34, s[0:1]
	v_rsq_f32_e32 v31, v31
	s_nop 0
	v_mul_f32_e32 v34, 0x45800000, v31
	v_cndmask_b32_e64 v31, v31, v34, s[0:1]
	v_mul_f32_e32 v34, 0x3e0293ee, v31
	v_pk_mul_f32 v[28:29], v[34:35], v[28:29] op_sel_hi:[0,1]
	v_pk_mul_f32 v[28:29], v[8:9], v[28:29]
	v_and_b32_e32 v31, 0xffff0000, v65
	v_cvt_pk_bf16_f32 v28, v28, v29
	global_store_dword v[26:27], v28, off offset:2944
	v_rsq_f32_e32 v26, v30
	v_lshlrev_b32_e32 v30, 16, v65
	v_mul_f32_e32 v26, 0x3e0293ee, v26
	v_pk_mul_f32 v[26:27], v[26:27], v[32:33] op_sel_hi:[0,1]
	v_pk_mul_f32 v[26:27], v[8:9], v[26:27]
	v_pk_mul_f32 v[32:33], v[30:31], v[30:31]
	v_cvt_pk_bf16_f32 v26, v26, v27
	global_store_dword v[22:23], v26, off offset:256
	v_lshlrev_b32_e32 v26, 16, v66
	v_and_b32_e32 v27, 0xffff0000, v66
	v_pk_mul_f32 v[28:29], v[26:27], v[26:27]
	v_mov_b32_e32 v34, v32
	v_mov_b32_e32 v35, v28
	v_mov_b32_e32 v28, v33
	v_pk_add_f32 v[28:29], v[34:35], v[28:29]
	v_mov_b32_e32 v33, v29
	v_mov_b32_e32 v32, v28
	s_nop 0
	v_permlane32_swap_b32_e32 v33, v29
	v_permlane32_swap_b32_e32 v32, v28
	s_waitcnt lgkmcnt(0)
	v_pk_add_f32 v[28:29], v[28:29], v[32:33]
	v_mov_b32_e32 v33, v29
	v_mov_b32_e32 v32, v28
	s_nop 0
	v_permlane16_swap_b32_e32 v33, v29
	v_permlane16_swap_b32_e32 v32, v28
	s_waitcnt lgkmcnt(0)
	v_pk_add_f32 v[28:29], v[28:29], v[32:33]
	s_nop 1
	v_add_f32_dpp v29, v29, v29 row_ror:8 row_mask:0xf bank_mask:0xf
	v_add_f32_dpp v28, v28, v28 row_ror:8 row_mask:0xf bank_mask:0xf
	s_waitcnt lgkmcnt(0)
	s_nop 1
	v_add_f32_dpp v29, v29, v29 row_ror:4 row_mask:0xf bank_mask:0xf
	v_add_f32_dpp v28, v28, v28 row_ror:4 row_mask:0xf bank_mask:0xf
	s_waitcnt lgkmcnt(0)
	s_nop 1
	v_add_f32_dpp v29, v29, v29 quad_perm:[2,3,0,1] row_mask:0xf bank_mask:0xf
	v_add_f32_dpp v28, v28, v28 quad_perm:[2,3,0,1] row_mask:0xf bank_mask:0xf
	s_waitcnt lgkmcnt(0)
	s_nop 1
	v_add_f32_dpp v29, v29, v29 quad_perm:[1,0,3,2] row_mask:0xf bank_mask:0xf
	v_add_f32_dpp v28, v28, v28 quad_perm:[1,0,3,2] row_mask:0xf bank_mask:0xf
	s_waitcnt lgkmcnt(0)
	s_nop 0
	v_pk_fma_f32 v[28:29], v[28:29], s[96:97], v[18:19] op_sel_hi:[1,0,0]
	s_nop 0
	v_mul_f32_e32 v32, 0x4b800000, v29
	v_cmp_gt_f32_e64 s[0:1], s77, v29
	v_cmp_gt_f32_e32 vcc, s77, v28
	s_nop 0
	v_cndmask_b32_e64 v29, v29, v32, s[0:1]
	v_rsq_f32_e32 v29, v29
	s_nop 0
	v_mul_f32_e32 v32, 0x45800000, v29
	v_cndmask_b32_e64 v29, v29, v32, s[0:1]
	v_mul_f32_e32 v32, 0x3e0293ee, v29
	v_pk_mul_f32 v[26:27], v[32:33], v[26:27] op_sel_hi:[0,1]
	v_pk_mul_f32 v[26:27], v[8:9], v[26:27]
	s_nop 0
	v_cvt_pk_bf16_f32 v26, v26, v27
	global_store_dword v[22:23], v26, off offset:512
	v_rsq_f32_e32 v26, v28
	s_nop 0
	v_mul_f32_e32 v26, 0x3e0293ee, v26
	v_pk_mul_f32 v[26:27], v[26:27], v[30:31] op_sel_hi:[0,1]
	v_pk_mul_f32 v[26:27], v[8:9], v[26:27]
	v_lshlrev_b32_e32 v30, 16, v63
	v_cvt_pk_bf16_f32 v26, v26, v27
	global_store_dword v[22:23], v26, off offset:768
	v_lshlrev_b32_e32 v26, 16, v64
	v_and_b32_e32 v27, 0xffff0000, v64
	v_and_b32_e32 v31, 0xffff0000, v63
	v_pk_mul_f32 v[28:29], v[26:27], v[26:27]
	v_pk_mul_f32 v[32:33], v[30:31], v[30:31]
	v_mov_b32_e32 v35, v28
	v_mov_b32_e32 v34, v32
	v_mov_b32_e32 v28, v33
	v_pk_add_f32 v[28:29], v[34:35], v[28:29]
	v_mov_b32_e32 v33, v29
	v_mov_b32_e32 v32, v28
	s_nop 0
	v_permlane32_swap_b32_e32 v33, v29
	v_permlane32_swap_b32_e32 v32, v28
	s_waitcnt lgkmcnt(0)
; DI unsigned pk2(float lo, float hi) { const f32x2 v = {lo, hi}; return __builtin_bit_cast(unsigned, __builtin_convertvector(v, bf16v2_t)); }
; DI float wave_sum(float v) { for (int o = 32; o; o >>= 1) v += __shfl_xor(v, o); return v; }
; DI void run_phase(const Params& p, int ph, unsigned char* smem, const int tid, const int rep) {
;     ...
;               for (int u = 0; u < 4; ++u) { const int t = t0 + u; bf16_t* pr = proj + (size_t)t * PLD;
;                   { const u32x2 v = vq[u]; const float a0 = __uint_as_float(v[0] << 16), a1 = __uint_as_float(v[0] & 0xffff0000u), a2 = __uint_as_float(v[1] << 16), a3 = __uint_as_float(v[1] & 0xffff0000u);
;                     const float rs = rsqrtf(wave_sum(a0 * a0 + a1 * a1 + a2 * a2 + a3 * a3) * (1.f / 256.f) + NEPS);
;                     u32x2 o; o[0] = pk2(a0 * rs * ggq[0], a1 * rs * ggq[1]); o[1] = pk2(a2 * rs * ggq[2], a3 * rs * ggq[3]); *(u32x2*)(mlaa + (size_t)t * 384 + 4 * lane) = o; }
;                   { const unsigned v = vkv[u]; const float a0 = __uint_as_float(v << 16), a1 = __uint_as_float(v & 0xffff0000u);
;                     const float rs = rsqrtf(wave_sum(a0 * a0 + a1 * a1) * (1.f / 128.f) + NEPS);
;                     *(unsigned*)(mlaa + (size_t)t * 384 + 256 + 2 * lane) = pk2(a0 * rs * gkv0, a1 * rs * gkv1); }
; #pragma unroll
;                   for (int hq = 0; hq < 8; ++hq) { const unsigned v = vf[u][hq]; const float a0 = __uint_as_float(v << 16), a1 = __uint_as_float(v & 0xffff0000u);
;                     const float rs = rsqrtf(wave_sum(a0 * a0 + a1 * a1) * (1.f / 128.f) + NEPS) * ((hq < 4) ? 0.08838834764831845f * LOG2E : 1.f);
;                     *(unsigned*)(pr + 3520 + hq * 128 + 2 * lane) = pk2(a0 * rs * ((hq < 4) ? fq0 : fk0), a1 * rs * ((hq < 4) ? fq1 : fk1)); } } } }
	v_pk_add_f32 v[28:29], v[28:29], v[32:33]
	v_mov_b32_e32 v33, v29
	v_mov_b32_e32 v32, v28
	s_nop 0
	v_permlane16_swap_b32_e32 v33, v29
	v_permlane16_swap_b32_e32 v32, v28
	s_waitcnt lgkmcnt(0)
	v_pk_add_f32 v[28:29], v[28:29], v[32:33]
	s_nop 1
	v_add_f32_dpp v29, v29, v29 row_ror:8 row_mask:0xf bank_mask:0xf
	v_add_f32_dpp v28, v28, v28 row_ror:8 row_mask:0xf bank_mask:0xf
	s_waitcnt lgkmcnt(0)
	s_nop 1
	v_add_f32_dpp v29, v29, v29 row_ror:4 row_mask:0xf bank_mask:0xf
	v_add_f32_dpp v28, v28, v28 row_ror:4 row_mask:0xf bank_mask:0xf
	s_waitcnt lgkmcnt(0)
	s_nop 1
	v_add_f32_dpp v29, v29, v29 quad_perm:[2,3,0,1] row_mask:0xf bank_mask:0xf
	v_add_f32_dpp v28, v28, v28 quad_perm:[2,3,0,1] row_mask:0xf bank_mask:0xf
	s_waitcnt lgkmcnt(0)
	s_nop 1
	v_add_f32_dpp v29, v29, v29 quad_perm:[1,0,3,2] row_mask:0xf bank_mask:0xf
	v_add_f32_dpp v28, v28, v28 quad_perm:[1,0,3,2] row_mask:0xf bank_mask:0xf
	s_waitcnt lgkmcnt(0)
	s_nop 0
	v_pk_fma_f32 v[28:29], v[28:29], s[96:97], v[18:19] op_sel_hi:[1,0,0]
	s_nop 0
	v_mul_f32_e32 v32, 0x4b800000, v29
	v_cmp_gt_f32_e64 s[0:1], s77, v29
	v_cmp_gt_f32_e32 vcc, s77, v28
	s_nop 0
	v_cndmask_b32_e64 v29, v29, v32, s[0:1]
	v_rsq_f32_e32 v29, v29
	s_nop 0
	v_mul_f32_e32 v32, 0x45800000, v29
	v_cndmask_b32_e64 v32, v29, v32, s[0:1]
	v_pk_mul_f32 v[26:27], v[32:33], v[26:27] op_sel_hi:[0,1]
	v_pk_mul_f32 v[26:27], v[10:11], v[26:27]
	s_nop 0
	v_cvt_pk_bf16_f32 v26, v26, v27
	global_store_dword v[22:23], v26, off offset:1024
	v_rsq_f32_e32 v26, v28
	s_nop 0
	v_pk_mul_f32 v[26:27], v[26:27], v[30:31] op_sel_hi:[0,1]
	v_pk_mul_f32 v[26:27], v[10:11], v[26:27]
	v_lshlrev_b32_e32 v30, 16, v61
	v_cvt_pk_bf16_f32 v26, v26, v27
	global_store_dword v[22:23], v26, off offset:1280
	v_lshlrev_b32_e32 v26, 16, v62
	v_and_b32_e32 v27, 0xffff0000, v62
	v_and_b32_e32 v31, 0xffff0000, v61
	v_pk_mul_f32 v[28:29], v[26:27], v[26:27]
	v_pk_mul_f32 v[32:33], v[30:31], v[30:31]
	v_mov_b32_e32 v35, v28
	v_mov_b32_e32 v34, v32
	v_mov_b32_e32 v28, v33
	v_pk_add_f32 v[28:29], v[34:35], v[28:29]
	v_mov_b32_e32 v33, v29
	v_mov_b32_e32 v32, v28
	s_nop 0
	v_permlane32_swap_b32_e32 v33, v29
	v_permlane32_swap_b32_e32 v32, v28
	s_waitcnt lgkmcnt(0)
	v_pk_add_f32 v[28:29], v[28:29], v[32:33]
	v_mov_b32_e32 v33, v29
	v_mov_b32_e32 v32, v28
	s_nop 0
	v_permlane16_swap_b32_e32 v33, v29
	v_permlane16_swap_b32_e32 v32, v28
	s_waitcnt lgkmcnt(0)
	v_pk_add_f32 v[28:29], v[28:29], v[32:33]
	s_nop 1
	v_add_f32_dpp v29, v29, v29 row_ror:8 row_mask:0xf bank_mask:0xf
	v_add_f32_dpp v28, v28, v28 row_ror:8 row_mask:0xf bank_mask:0xf
	s_waitcnt lgkmcnt(0)
	s_nop 1
	v_add_f32_dpp v29, v29, v29 row_ror:4 row_mask:0xf bank_mask:0xf
	v_add_f32_dpp v28, v28, v28 row_ror:4 row_mask:0xf bank_mask:0xf
	s_waitcnt lgkmcnt(0)
	s_nop 1
	v_add_f32_dpp v29, v29, v29 quad_perm:[2,3,0,1] row_mask:0xf bank_mask:0xf
	v_add_f32_dpp v28, v28, v28 quad_perm:[2,3,0,1] row_mask:0xf bank_mask:0xf
	s_waitcnt lgkmcnt(0)
	s_nop 1
	v_add_f32_dpp v29, v29, v29 quad_perm:[1,0,3,2] row_mask:0xf bank_mask:0xf
	v_add_f32_dpp v28, v28, v28 quad_perm:[1,0,3,2] row_mask:0xf bank_mask:0xf
	s_waitcnt lgkmcnt(0)
	s_nop 0
	v_pk_fma_f32 v[28:29], v[28:29], s[96:97], v[18:19] op_sel_hi:[1,0,0]
	s_nop 0
	v_mul_f32_e32 v32, 0x4b800000, v29
	v_cmp_gt_f32_e64 s[0:1], s77, v29
	v_cmp_gt_f32_e32 vcc, s77, v28
	s_nop 0
	v_cndmask_b32_e64 v29, v29, v32, s[0:1]
	v_rsq_f32_e32 v29, v29
	s_nop 0
	v_mul_f32_e32 v32, 0x45800000, v29
	v_cndmask_b32_e64 v32, v29, v32, s[0:1]
	v_pk_mul_f32 v[26:27], v[32:33], v[26:27] op_sel_hi:[0,1]
	v_pk_mul_f32 v[26:27], v[10:11], v[26:27]
	s_waitcnt vmcnt(36)
	v_lshlrev_b32_e32 v32, 16, v60
	v_cvt_pk_bf16_f32 v26, v26, v27
	global_store_dword v[22:23], v26, off offset:1536
	v_rsq_f32_e32 v26, v28
	v_and_b32_e32 v33, 0xffff0000, v60
	v_pk_mul_f32 v[34:35], v[32:33], v[32:33]
	v_pk_mul_f32 v[26:27], v[26:27], v[30:31] op_sel_hi:[0,1]
	v_pk_mul_f32 v[26:27], v[10:11], v[26:27]
	s_nop 0
	v_cvt_pk_bf16_f32 v26, v26, v27
	global_store_dword v[22:23], v26, off offset:1792
	v_and_b32_e32 v27, 0xffff0000, v25
	v_and_b32_e32 v26, s0, v24
	v_mov_b32_e32 v23, v27
	v_pk_mul_f32 v[28:29], v[26:27], v[26:27]
	v_and_b32_e32 v27, 0xffff0000, v24
	v_lshlrev_b32_e32 v26, 16, v24
	v_mul_f32_e32 v24, v27, v27
	v_lshlrev_b32_e32 v22, 16, v25
	v_pk_fma_f32 v[24:25], v[26:27], v[26:27], v[24:25] op_sel_hi:[1,1,0]
	v_mov_b32_e32 v28, v34
	v_pk_fma_f32 v[24:25], v[22:23], v[22:23], v[24:25]
	v_mad_i64_i32 v[20:21], s[0:1], v59, s22, v[20:21]
	v_pk_mov_b32 v[24:25], v[34:35], v[24:25] op_sel:[1,0]
	v_lshl_add_u64 v[30:31], v[20:21], 0, v[0:1]
	v_pk_add_f32 v[24:25], v[28:29], v[24:25]
	v_mov_b32_e32 v29, v25
	v_mov_b32_e32 v28, v24
	s_nop 0
	v_permlane32_swap_b32_e32 v29, v25
	v_permlane32_swap_b32_e32 v28, v24
	v_lshl_add_u64 v[20:21], v[20:21], 0, v[12:13]
	s_waitcnt lgkmcnt(0)
	v_pk_add_f32 v[24:25], v[24:25], v[28:29]
	v_mov_b32_e32 v29, v25
	v_mov_b32_e32 v28, v24
	s_nop 0
	v_permlane16_swap_b32_e32 v29, v25
	v_permlane16_swap_b32_e32 v28, v24
	s_waitcnt lgkmcnt(0)
	v_pk_add_f32 v[24:25], v[24:25], v[28:29]
	s_nop 1
	v_add_f32_dpp v25, v25, v25 row_ror:8 row_mask:0xf bank_mask:0xf
	v_add_f32_dpp v24, v24, v24 row_ror:8 row_mask:0xf bank_mask:0xf
	s_waitcnt lgkmcnt(0)
	s_nop 1
	v_add_f32_dpp v25, v25, v25 row_ror:4 row_mask:0xf bank_mask:0xf
	v_add_f32_dpp v24, v24, v24 row_ror:4 row_mask:0xf bank_mask:0xf
	s_waitcnt lgkmcnt(0)
	s_nop 1
	v_add_f32_dpp v25, v25, v25 quad_perm:[2,3,0,1] row_mask:0xf bank_mask:0xf
	v_add_f32_dpp v24, v24, v24 quad_perm:[2,3,0,1] row_mask:0xf bank_mask:0xf
	s_waitcnt lgkmcnt(0)
; DI unsigned pk2(float lo, float hi) { const f32x2 v = {lo, hi}; return __builtin_bit_cast(unsigned, __builtin_convertvector(v, bf16v2_t)); }
; DI float wave_sum(float v) { for (int o = 32; o; o >>= 1) v += __shfl_xor(v, o); return v; }
; DI void run_phase(const Params& p, int ph, unsigned char* smem, const int tid, const int rep) {
;     ...
;               for (int u = 0; u < 4; ++u) { const int t = t0 + u; bf16_t* pr = proj + (size_t)t * PLD;
;                   { const u32x2 v = vq[u]; const float a0 = __uint_as_float(v[0] << 16), a1 = __uint_as_float(v[0] & 0xffff0000u), a2 = __uint_as_float(v[1] << 16), a3 = __uint_as_float(v[1] & 0xffff0000u);
;                     const float rs = rsqrtf(wave_sum(a0 * a0 + a1 * a1 + a2 * a2 + a3 * a3) * (1.f / 256.f) + NEPS);
;                     u32x2 o; o[0] = pk2(a0 * rs * ggq[0], a1 * rs * ggq[1]); o[1] = pk2(a2 * rs * ggq[2], a3 * rs * ggq[3]); *(u32x2*)(mlaa + (size_t)t * 384 + 4 * lane) = o; }
;                   { const unsigned v = vkv[u]; const float a0 = __uint_as_float(v << 16), a1 = __uint_as_float(v & 0xffff0000u);
;                     const float rs = rsqrtf(wave_sum(a0 * a0 + a1 * a1) * (1.f / 128.f) + NEPS);
;                     *(unsigned*)(mlaa + (size_t)t * 384 + 256 + 2 * lane) = pk2(a0 * rs * gkv0, a1 * rs * gkv1); }
; #pragma unroll
;                   for (int hq = 0; hq < 8; ++hq) { const unsigned v = vf[u][hq]; const float a0 = __uint_as_float(v << 16), a1 = __uint_as_float(v & 0xffff0000u);
;                     const float rs = rsqrtf(wave_sum(a0 * a0 + a1 * a1) * (1.f / 128.f) + NEPS) * ((hq < 4) ? 0.08838834764831845f * LOG2E : 1.f);
;                     *(unsigned*)(pr + 3520 + hq * 128 + 2 * lane) = pk2(a0 * rs * ((hq < 4) ? fq0 : fk0), a1 * rs * ((hq < 4) ? fq1 : fk1)); } } } }
	s_nop 1
	v_add_f32_dpp v25, v25, v25 quad_perm:[1,0,3,2] row_mask:0xf bank_mask:0xf
	v_add_f32_dpp v24, v24, v24 quad_perm:[1,0,3,2] row_mask:0xf bank_mask:0xf
	s_waitcnt lgkmcnt(0)
	s_nop 0
	v_pk_fma_f32 v[24:25], v[24:25], s[96:97], v[18:19] op_sel_hi:[1,1,0]
	s_nop 0
	v_mul_f32_e32 v28, 0x4b800000, v25
	v_cmp_gt_f32_e64 s[0:1], s77, v25
	v_cmp_gt_f32_e32 vcc, s77, v24
	s_nop 0
	v_cndmask_b32_e64 v25, v25, v28, s[0:1]
	v_rsq_f32_e32 v25, v25
	s_nop 0
	v_mul_f32_e32 v28, 0x45800000, v25
	v_cndmask_b32_e64 v28, v25, v28, s[0:1]
	v_pk_mul_f32 v[26:27], v[28:29], v[26:27] op_sel_hi:[0,1]
	v_pk_mul_f32 v[22:23], v[28:29], v[22:23] op_sel_hi:[0,1]
	v_pk_mul_f32 v[26:27], v[2:3], v[26:27]
	v_pk_mul_f32 v[22:23], v[4:5], v[22:23]
	v_cvt_pk_bf16_f32 v26, v26, v27
	v_cvt_pk_bf16_f32 v27, v22, v23
	v_rsq_f32_e32 v22, v24
	s_waitcnt vmcnt(36)
	v_lshlrev_b32_e32 v24, 16, v57
	v_and_b32_e32 v25, 0xffff0000, v57
	global_store_dwordx2 v[30:31], v[26:27], off
	v_pk_mul_f32 v[22:23], v[22:23], v[32:33] op_sel_hi:[0,1]
	v_pk_mul_f32 v[22:23], v[6:7], v[22:23]
	v_pk_mul_f32 v[26:27], v[24:25], v[24:25]
	v_cvt_pk_bf16_f32 v22, v22, v23
	global_store_dword v[20:21], v22, off offset:512
	v_lshlrev_b32_e32 v20, 16, v58
	v_and_b32_e32 v21, 0xffff0000, v58
	v_pk_mul_f32 v[22:23], v[20:21], v[20:21]
	v_mov_b32_e32 v28, v26
	v_mov_b32_e32 v29, v22
	v_mov_b32_e32 v22, v27
	v_pk_add_f32 v[22:23], v[28:29], v[22:23]
	v_mov_b32_e32 v27, v23
	v_mov_b32_e32 v26, v22
	s_nop 0
	v_permlane32_swap_b32_e32 v27, v23
	v_permlane32_swap_b32_e32 v26, v22
	s_waitcnt lgkmcnt(0)
	v_pk_add_f32 v[22:23], v[22:23], v[26:27]
	v_mov_b32_e32 v27, v23
	v_mov_b32_e32 v26, v22
	s_nop 0
	v_permlane16_swap_b32_e32 v27, v23
	v_permlane16_swap_b32_e32 v26, v22
	s_waitcnt lgkmcnt(0)
	v_pk_add_f32 v[22:23], v[22:23], v[26:27]
	s_nop 1
	v_add_f32_dpp v23, v23, v23 row_ror:8 row_mask:0xf bank_mask:0xf
	v_add_f32_dpp v22, v22, v22 row_ror:8 row_mask:0xf bank_mask:0xf
	s_waitcnt lgkmcnt(0)
	s_nop 1
	v_add_f32_dpp v23, v23, v23 row_ror:4 row_mask:0xf bank_mask:0xf
	v_add_f32_dpp v22, v22, v22 row_ror:4 row_mask:0xf bank_mask:0xf
	s_waitcnt lgkmcnt(0)
	s_nop 1
	v_add_f32_dpp v23, v23, v23 quad_perm:[2,3,0,1] row_mask:0xf bank_mask:0xf
	v_add_f32_dpp v22, v22, v22 quad_perm:[2,3,0,1] row_mask:0xf bank_mask:0xf
	s_waitcnt lgkmcnt(0)
	s_nop 1
	v_add_f32_dpp v23, v23, v23 quad_perm:[1,0,3,2] row_mask:0xf bank_mask:0xf
	v_add_f32_dpp v22, v22, v22 quad_perm:[1,0,3,2] row_mask:0xf bank_mask:0xf
	s_waitcnt lgkmcnt(0)
	s_nop 0
	v_pk_fma_f32 v[22:23], v[22:23], s[96:97], v[18:19] op_sel_hi:[1,0,0]
	s_nop 0
	v_cmp_gt_f32_e64 s[0:1], s77, v23
	v_cmp_gt_f32_e32 vcc, s77, v22
	s_nop 0
	v_rsq_f32_e32 v13, v23
	s_nop 0
	v_mul_f32_e32 v26, 0x3e0293ee, v13
	v_pk_mul_f32 v[20:21], v[26:27], v[20:21] op_sel_hi:[0,1]
	v_pk_mul_f32 v[20:21], v[8:9], v[20:21]
	s_waitcnt vmcnt(36)
	v_and_b32_e32 v23, 0xffff0000, v55
	v_cvt_pk_bf16_f32 v13, v20, v21
	global_store_dword v[16:17], v13, off offset:2944
	v_rsq_f32_e32 v13, v22
	v_lshlrev_b32_e32 v22, 16, v55
	v_mul_f32_e32 v16, 0x3e0293ee, v13
	v_pk_mul_f32 v[16:17], v[16:17], v[24:25] op_sel_hi:[0,1]
	v_pk_mul_f32 v[16:17], v[8:9], v[16:17]
	v_pk_mul_f32 v[24:25], v[22:23], v[22:23]
	v_cvt_pk_bf16_f32 v13, v16, v17
	v_lshlrev_b32_e32 v16, 16, v56
	v_and_b32_e32 v17, 0xffff0000, v56
	v_pk_mul_f32 v[20:21], v[16:17], v[16:17]
	v_mov_b32_e32 v26, v24
	v_mov_b32_e32 v27, v20
	v_mov_b32_e32 v20, v25
	v_pk_add_f32 v[20:21], v[26:27], v[20:21]
	v_mov_b32_e32 v25, v21
	v_mov_b32_e32 v24, v20
	s_nop 0
	v_permlane32_swap_b32_e32 v25, v21
	v_permlane32_swap_b32_e32 v24, v20
	global_store_dword v[14:15], v13, off offset:256
	s_waitcnt lgkmcnt(0)
	v_pk_add_f32 v[20:21], v[20:21], v[24:25]
	v_mov_b32_e32 v25, v21
	v_mov_b32_e32 v24, v20
	s_nop 0
	v_permlane16_swap_b32_e32 v25, v21
	v_permlane16_swap_b32_e32 v24, v20
	s_waitcnt lgkmcnt(0)
	v_pk_add_f32 v[20:21], v[20:21], v[24:25]
	s_nop 1
	v_add_f32_dpp v21, v21, v21 row_ror:8 row_mask:0xf bank_mask:0xf
	v_add_f32_dpp v20, v20, v20 row_ror:8 row_mask:0xf bank_mask:0xf
	s_waitcnt lgkmcnt(0)
	s_nop 1
	v_add_f32_dpp v21, v21, v21 row_ror:4 row_mask:0xf bank_mask:0xf
	v_add_f32_dpp v20, v20, v20 row_ror:4 row_mask:0xf bank_mask:0xf
	s_waitcnt lgkmcnt(0)
	s_nop 1
	v_add_f32_dpp v21, v21, v21 quad_perm:[2,3,0,1] row_mask:0xf bank_mask:0xf
	v_add_f32_dpp v20, v20, v20 quad_perm:[2,3,0,1] row_mask:0xf bank_mask:0xf
	s_waitcnt lgkmcnt(0)
	s_nop 1
	v_add_f32_dpp v21, v21, v21 quad_perm:[1,0,3,2] row_mask:0xf bank_mask:0xf
	v_add_f32_dpp v20, v20, v20 quad_perm:[1,0,3,2] row_mask:0xf bank_mask:0xf
	s_waitcnt lgkmcnt(0)
; DI unsigned pk2(float lo, float hi) { const f32x2 v = {lo, hi}; return __builtin_bit_cast(unsigned, __builtin_convertvector(v, bf16v2_t)); }
; DI float wave_sum(float v) { for (int o = 32; o; o >>= 1) v += __shfl_xor(v, o); return v; }
; DI void run_phase(const Params& p, int ph, unsigned char* smem, const int tid, const int rep) {
;     ...
;               for (int u = 0; u < 4; ++u) { const int t = t0 + u; bf16_t* pr = proj + (size_t)t * PLD;
;                   { const u32x2 v = vq[u]; const float a0 = __uint_as_float(v[0] << 16), a1 = __uint_as_float(v[0] & 0xffff0000u), a2 = __uint_as_float(v[1] << 16), a3 = __uint_as_float(v[1] & 0xffff0000u);
;                     const float rs = rsqrtf(wave_sum(a0 * a0 + a1 * a1 + a2 * a2 + a3 * a3) * (1.f / 256.f) + NEPS);
;                     u32x2 o; o[0] = pk2(a0 * rs * ggq[0], a1 * rs * ggq[1]); o[1] = pk2(a2 * rs * ggq[2], a3 * rs * ggq[3]); *(u32x2*)(mlaa + (size_t)t * 384 + 4 * lane) = o; }
;                   { const unsigned v = vkv[u]; const float a0 = __uint_as_float(v << 16), a1 = __uint_as_float(v & 0xffff0000u);
;                     const float rs = rsqrtf(wave_sum(a0 * a0 + a1 * a1) * (1.f / 128.f) + NEPS);
;                     *(unsigned*)(mlaa + (size_t)t * 384 + 256 + 2 * lane) = pk2(a0 * rs * gkv0, a1 * rs * gkv1); }
; #pragma unroll
;                   for (int hq = 0; hq < 8; ++hq) { const unsigned v = vf[u][hq]; const float a0 = __uint_as_float(v << 16), a1 = __uint_as_float(v & 0xffff0000u);
;                     const float rs = rsqrtf(wave_sum(a0 * a0 + a1 * a1) * (1.f / 128.f) + NEPS) * ((hq < 4) ? 0.08838834764831845f * LOG2E : 1.f);
;                     *(unsigned*)(pr + 3520 + hq * 128 + 2 * lane) = pk2(a0 * rs * ((hq < 4) ? fq0 : fk0), a1 * rs * ((hq < 4) ? fq1 : fk1)); } } } }
	s_nop 0
	v_pk_fma_f32 v[20:21], v[20:21], s[96:97], v[18:19] op_sel_hi:[1,0,0]
	s_nop 0
	v_cmp_gt_f32_e64 s[0:1], s77, v21
	v_cmp_gt_f32_e32 vcc, s77, v20
	s_nop 0
	v_rsq_f32_e32 v13, v21
	s_nop 0
	v_mul_f32_e32 v24, 0x3e0293ee, v13
	v_pk_mul_f32 v[16:17], v[24:25], v[16:17] op_sel_hi:[0,1]
	v_pk_mul_f32 v[16:17], v[8:9], v[16:17]
	s_nop 0
	v_cvt_pk_bf16_f32 v13, v16, v17
	global_store_dword v[14:15], v13, off offset:512
	v_rsq_f32_e32 v13, v20
	s_nop 0
	v_mul_f32_e32 v16, 0x3e0293ee, v13
	v_pk_mul_f32 v[16:17], v[16:17], v[22:23] op_sel_hi:[0,1]
	v_pk_mul_f32 v[16:17], v[8:9], v[16:17]
	s_waitcnt vmcnt(37)
	v_lshlrev_b32_e32 v22, 16, v53
	v_cvt_pk_bf16_f32 v13, v16, v17
	v_lshlrev_b32_e32 v16, 16, v54
	v_and_b32_e32 v17, 0xffff0000, v54
	v_and_b32_e32 v23, 0xffff0000, v53
	v_pk_mul_f32 v[20:21], v[16:17], v[16:17]
	v_pk_mul_f32 v[24:25], v[22:23], v[22:23]
	v_mov_b32_e32 v27, v20
	v_mov_b32_e32 v26, v24
	v_mov_b32_e32 v20, v25
	v_pk_add_f32 v[20:21], v[26:27], v[20:21]
	v_mov_b32_e32 v25, v21
	v_mov_b32_e32 v24, v20
	s_nop 0
	v_permlane32_swap_b32_e32 v25, v21
	v_permlane32_swap_b32_e32 v24, v20
	global_store_dword v[14:15], v13, off offset:768
	s_waitcnt lgkmcnt(0)
	v_pk_add_f32 v[20:21], v[20:21], v[24:25]
	v_mov_b32_e32 v25, v21
	v_mov_b32_e32 v24, v20
	s_nop 0
	v_permlane16_swap_b32_e32 v25, v21
	v_permlane16_swap_b32_e32 v24, v20
	s_waitcnt lgkmcnt(0)
	v_pk_add_f32 v[20:21], v[20:21], v[24:25]
	s_nop 1
	v_add_f32_dpp v21, v21, v21 row_ror:8 row_mask:0xf bank_mask:0xf
	v_add_f32_dpp v20, v20, v20 row_ror:8 row_mask:0xf bank_mask:0xf
	s_waitcnt lgkmcnt(0)
	s_nop 1
	v_add_f32_dpp v21, v21, v21 row_ror:4 row_mask:0xf bank_mask:0xf
	v_add_f32_dpp v20, v20, v20 row_ror:4 row_mask:0xf bank_mask:0xf
	s_waitcnt lgkmcnt(0)
	s_nop 1
	v_add_f32_dpp v21, v21, v21 quad_perm:[2,3,0,1] row_mask:0xf bank_mask:0xf
	v_add_f32_dpp v20, v20, v20 quad_perm:[2,3,0,1] row_mask:0xf bank_mask:0xf
	s_waitcnt lgkmcnt(0)
	s_nop 1
	v_add_f32_dpp v21, v21, v21 quad_perm:[1,0,3,2] row_mask:0xf bank_mask:0xf
	v_add_f32_dpp v20, v20, v20 quad_perm:[1,0,3,2] row_mask:0xf bank_mask:0xf
	s_waitcnt lgkmcnt(0)
	s_nop 0
	v_pk_fma_f32 v[20:21], v[20:21], s[96:97], v[18:19] op_sel_hi:[1,0,0]
	s_nop 0
	v_cmp_gt_f32_e64 s[0:1], s77, v21
	v_cmp_gt_f32_e32 vcc, s77, v20
	s_nop 0
	v_rsq_f32_e32 v13, v21
	s_nop 0
	v_mov_b32_e32 v24, v13
	v_pk_mul_f32 v[16:17], v[24:25], v[16:17] op_sel_hi:[0,1]
	v_pk_mul_f32 v[16:17], v[10:11], v[16:17]
	s_nop 0
	v_cvt_pk_bf16_f32 v13, v16, v17
	global_store_dword v[14:15], v13, off offset:1024
	v_rsq_f32_e32 v13, v20
	s_nop 0
	v_mov_b32_e32 v16, v13
	v_pk_mul_f32 v[16:17], v[16:17], v[22:23] op_sel_hi:[0,1]
	v_pk_mul_f32 v[16:17], v[10:11], v[16:17]
	s_waitcnt vmcnt(37)
	v_lshlrev_b32_e32 v22, 16, v51
	v_cvt_pk_bf16_f32 v13, v16, v17
	v_lshlrev_b32_e32 v16, 16, v52
	v_and_b32_e32 v17, 0xffff0000, v52
	v_and_b32_e32 v23, 0xffff0000, v51
	v_pk_mul_f32 v[20:21], v[16:17], v[16:17]
	v_pk_mul_f32 v[24:25], v[22:23], v[22:23]
	v_mov_b32_e32 v27, v20
	v_mov_b32_e32 v26, v24
	v_mov_b32_e32 v20, v25
	v_pk_add_f32 v[20:21], v[26:27], v[20:21]
	v_mov_b32_e32 v25, v21
	v_mov_b32_e32 v24, v20
	s_nop 0
	v_permlane32_swap_b32_e32 v25, v21
	v_permlane32_swap_b32_e32 v24, v20
	global_store_dword v[14:15], v13, off offset:1280
	s_waitcnt lgkmcnt(0)
	v_pk_add_f32 v[20:21], v[20:21], v[24:25]
	v_mov_b32_e32 v25, v21
	v_mov_b32_e32 v24, v20
	s_nop 0
	v_permlane16_swap_b32_e32 v25, v21
	v_permlane16_swap_b32_e32 v24, v20
	s_waitcnt lgkmcnt(0)
	v_pk_add_f32 v[20:21], v[20:21], v[24:25]
	s_nop 1
	v_add_f32_dpp v21, v21, v21 row_ror:8 row_mask:0xf bank_mask:0xf
	v_add_f32_dpp v20, v20, v20 row_ror:8 row_mask:0xf bank_mask:0xf
	s_waitcnt lgkmcnt(0)
	s_nop 1
	v_add_f32_dpp v21, v21, v21 row_ror:4 row_mask:0xf bank_mask:0xf
	v_add_f32_dpp v20, v20, v20 row_ror:4 row_mask:0xf bank_mask:0xf
	s_waitcnt lgkmcnt(0)
	s_nop 1
	v_add_f32_dpp v21, v21, v21 quad_perm:[2,3,0,1] row_mask:0xf bank_mask:0xf
	v_add_f32_dpp v20, v20, v20 quad_perm:[2,3,0,1] row_mask:0xf bank_mask:0xf
	s_waitcnt lgkmcnt(0)
	s_nop 1
	v_add_f32_dpp v21, v21, v21 quad_perm:[1,0,3,2] row_mask:0xf bank_mask:0xf
	v_add_f32_dpp v20, v20, v20 quad_perm:[1,0,3,2] row_mask:0xf bank_mask:0xf
	s_waitcnt lgkmcnt(0)
	s_nop 0
	v_pk_fma_f32 v[18:19], v[20:21], s[96:97], v[18:19] op_sel_hi:[1,0,0]
	s_nop 0
	v_cmp_gt_f32_e64 s[0:1], s77, v19
	v_cmp_gt_f32_e32 vcc, s77, v18
	s_nop 0
	v_rsq_f32_e32 v13, v19
	s_nop 0
	v_mov_b32_e32 v20, v13
	v_pk_mul_f32 v[16:17], v[20:21], v[16:17] op_sel_hi:[0,1]
	v_pk_mul_f32 v[16:17], v[10:11], v[16:17]
	s_nop 0
	v_cvt_pk_bf16_f32 v13, v16, v17
	global_store_dword v[14:15], v13, off offset:1536
	v_rsq_f32_e32 v13, v18
	s_nop 0
	v_mov_b32_e32 v16, v13
	v_pk_mul_f32 v[16:17], v[16:17], v[22:23] op_sel_hi:[0,1]
	v_pk_mul_f32 v[16:17], v[10:11], v[16:17]
	v_cmp_lt_i32_e32 vcc, s11, v44
	v_cvt_pk_bf16_f32 v13, v16, v17
	s_or_b64 s[40:41], vcc, s[40:41]
	global_store_dword v[14:15], v13, off offset:1792
	s_andn2_b64 exec, exec, s[40:41]
	s_cbranch_execnz .LBB0_372

; DI unsigned pk2(float lo, float hi) { const f32x2 v = {lo, hi}; return __builtin_bit_cast(unsigned, __builtin_convertvector(v, bf16v2_t)); }
; DI float wave_sum(float v) { for (int o = 32; o; o >>= 1) v += __shfl_xor(v, o); return v; }
; DI void rmsnorm_phase(const float* x, const float* g, bf16_t* h, int ntok, const int tid) {
;     ...
;     for (int t0 = (blockIdx.x * 8 + wv) * 2; t0 < ntok; t0 += gridDim.x * 16) {
;         f32x4 v[2][4];
; #pragma unroll
;         for (int u = 0; u < 2; ++u)
; #pragma unroll
;             for (int c = 0; c < 4; ++c) v[u][c] = ((const f32x4*)(x + (size_t)(t0 + u) * 1024))[lane + 64 * c];
; #pragma unroll
;         for (int u = 0; u < 2; ++u) { float ss = 0.f;
; #pragma unroll
;             for (int c = 0; c < 4; ++c) ss += v[u][c][0] * v[u][c][0] + v[u][c][1] * v[u][c][1] + v[u][c][2] * v[u][c][2] + v[u][c][3] * v[u][c][3];
;             ss = wave_sum(ss);
;             const float rs = rsqrtf(ss * (1.f / 1024.f) + NEPS);
; #pragma unroll
;             for (int c = 0; c < 4; ++c) { u32x2 o; o[0] = pk2(v[u][c][0] * rs * gg[c][0], v[u][c][1] * rs * gg[c][1]); o[1] = pk2(v[u][c][2] * rs * gg[c][2], v[u][c][3] * rs * gg[c][3]);
;                 *(u32x2*)(h + (size_t)(t0 + u) * 1024 + (lane + 64 * c) * 4) = o; } }
;     }
.LBB0_702:
	v_ashrrev_i32_e32 v51, 31, v50
	v_lshlrev_b64 v[18:19], 12, v[50:51]
	v_add_u32_e32 v56, 1, v50
	v_lshl_add_u64 v[18:19], v[52:53], 0, v[18:19]
	v_ashrrev_i32_e32 v57, 31, v56
	global_load_dwordx4 v[46:49], v[18:19], off
	global_load_dwordx4 v[42:45], v[18:19], off offset:1024
	global_load_dwordx4 v[38:41], v[18:19], off offset:2048
	global_load_dwordx4 v[34:37], v[18:19], off offset:3072
	v_lshlrev_b64 v[18:19], 12, v[56:57]
	v_lshl_add_u64 v[18:19], v[52:53], 0, v[18:19]
	global_load_dwordx4 v[30:33], v[18:19], off
	global_load_dwordx4 v[26:29], v[18:19], off offset:1024
	global_load_dwordx4 v[22:25], v[18:19], off offset:2048
	s_nop 0
	global_load_dwordx4 v[18:21], v[18:19], off offset:3072
	s_waitcnt vmcnt(7)
	v_mov_b32_e32 v66, v47
	s_waitcnt vmcnt(6)
	v_mov_b32_e32 v67, v43
	v_mov_b32_e32 v58, v46
	s_waitcnt vmcnt(3)
	v_mov_b32_e32 v72, v31
	s_waitcnt vmcnt(2)
	v_mov_b32_e32 v73, v27
	v_mov_b32_e32 v59, v42
	v_pk_mul_f32 v[66:67], v[66:67], v[66:67]
	v_mov_b32_e32 v70, v30
	v_mov_b32_e32 v71, v26
	v_pk_mul_f32 v[72:73], v[72:73], v[72:73]
	v_pk_fma_f32 v[58:59], v[58:59], v[58:59], v[66:67]
	v_mov_b32_e32 v66, v48
	v_mov_b32_e32 v67, v44
	v_pk_fma_f32 v[70:71], v[70:71], v[70:71], v[72:73]
	v_mov_b32_e32 v72, v32
	v_mov_b32_e32 v73, v28
	v_pk_fma_f32 v[58:59], v[66:67], v[66:67], v[58:59]
	v_mov_b32_e32 v66, v49
	v_mov_b32_e32 v67, v45
	v_mov_b32_e32 v68, v39
	v_mov_b32_e32 v69, v35
	v_pk_fma_f32 v[70:71], v[72:73], v[72:73], v[70:71]
	v_mov_b32_e32 v72, v33
	v_mov_b32_e32 v73, v29
	s_waitcnt vmcnt(1)
	v_mov_b32_e32 v74, v23
	s_waitcnt vmcnt(0)
	v_mov_b32_e32 v75, v19
	v_pk_fma_f32 v[66:67], v[66:67], v[66:67], v[58:59]
	v_mov_b32_e32 v58, v38
	v_mov_b32_e32 v59, v34
	v_pk_mul_f32 v[68:69], v[68:69], v[68:69]
	v_pk_fma_f32 v[70:71], v[72:73], v[72:73], v[70:71]
	v_mov_b32_e32 v72, v22
	v_mov_b32_e32 v73, v18
	v_pk_mul_f32 v[74:75], v[74:75], v[74:75]
	v_pk_fma_f32 v[58:59], v[58:59], v[58:59], v[68:69]
	v_mov_b32_e32 v68, v40
	v_mov_b32_e32 v69, v36
	v_pk_fma_f32 v[72:73], v[72:73], v[72:73], v[74:75]
	v_mov_b32_e32 v74, v24
	v_mov_b32_e32 v75, v20
	v_pk_fma_f32 v[58:59], v[68:69], v[68:69], v[58:59]
	v_mov_b32_e32 v68, v41
	v_mov_b32_e32 v69, v37
	v_pk_fma_f32 v[72:73], v[74:75], v[74:75], v[72:73]
	v_mov_b32_e32 v74, v25
	v_mov_b32_e32 v75, v21
	v_pk_fma_f32 v[68:69], v[68:69], v[68:69], v[58:59]
	v_pk_fma_f32 v[72:73], v[74:75], v[74:75], v[72:73]
	v_mov_b32_e32 v74, v70
	v_mov_b32_e32 v75, v66
	v_mov_b32_e32 v66, v71
	v_pk_add_f32 v[66:67], v[74:75], v[66:67]
	v_mov_b32_e32 v70, v72
	v_mov_b32_e32 v71, v68
	v_pk_add_f32 v[66:67], v[66:67], v[70:71]
	v_mov_b32_e32 v68, v73
	v_pk_add_f32 v[66:67], v[66:67], v[68:69]
	v_mov_b32_e32 v69, v67
	v_mov_b32_e32 v68, v66
	s_nop 0
	v_permlane32_swap_b32_e32 v69, v67
	v_permlane32_swap_b32_e32 v68, v66
	v_lshlrev_b64 v[58:59], 11, v[50:51]
	v_lshl_add_u64 v[58:59], v[54:55], 0, v[58:59]
	v_add_u32_e32 v50, s17, v50
	s_waitcnt lgkmcnt(0)
	v_pk_add_f32 v[66:67], v[66:67], v[68:69]
	v_mov_b32_e32 v69, v67
	v_mov_b32_e32 v68, v66
	s_nop 0
	v_permlane16_swap_b32_e32 v69, v67
	v_permlane16_swap_b32_e32 v68, v66
	s_waitcnt lgkmcnt(0)
	v_pk_add_f32 v[66:67], v[66:67], v[68:69]
	s_nop 1
	v_add_f32_dpp v67, v67, v67 row_ror:8 row_mask:0xf bank_mask:0xf
	v_add_f32_dpp v66, v66, v66 row_ror:8 row_mask:0xf bank_mask:0xf
	s_waitcnt lgkmcnt(0)
	s_nop 1
	v_add_f32_dpp v67, v67, v67 row_ror:4 row_mask:0xf bank_mask:0xf
	v_add_f32_dpp v66, v66, v66 row_ror:4 row_mask:0xf bank_mask:0xf
	s_waitcnt lgkmcnt(0)
	s_nop 1
	v_add_f32_dpp v67, v67, v67 quad_perm:[2,3,0,1] row_mask:0xf bank_mask:0xf
	v_add_f32_dpp v66, v66, v66 quad_perm:[2,3,0,1] row_mask:0xf bank_mask:0xf
	s_waitcnt lgkmcnt(0)
	s_nop 1
	v_add_f32_dpp v67, v67, v67 quad_perm:[1,0,3,2] row_mask:0xf bank_mask:0xf
	v_add_f32_dpp v66, v66, v66 quad_perm:[1,0,3,2] row_mask:0xf bank_mask:0xf
	s_waitcnt lgkmcnt(0)
	s_nop 0
	v_pk_fma_f32 v[66:67], v[66:67], s[4:5], v[190:191] op_sel_hi:[1,0,0]
	s_nop 0
	v_cmp_gt_f32_e64 s[0:1], s77, v67
	v_cmp_gt_f32_e32 vcc, s77, v66
	s_nop 0
	v_rsq_f32_e32 v0, v67
	s_nop 0
	v_pk_mul_f32 v[46:47], v[46:47], v[0:1] op_sel_hi:[1,0]
	v_pk_mul_f32 v[48:49], v[48:49], v[0:1] op_sel_hi:[1,0]
	v_pk_mul_f32 v[42:43], v[42:43], v[0:1] op_sel_hi:[1,0]
	v_pk_mul_f32 v[44:45], v[44:45], v[0:1] op_sel_hi:[1,0]
	v_pk_mul_f32 v[38:39], v[38:39], v[0:1] op_sel_hi:[1,0]
	v_pk_mul_f32 v[40:41], v[40:41], v[0:1] op_sel_hi:[1,0]
	v_pk_mul_f32 v[34:35], v[34:35], v[0:1] op_sel_hi:[1,0]
	v_pk_mul_f32 v[36:37], v[36:37], v[0:1] op_sel_hi:[1,0]
	v_rsq_f32_e32 v0, v66
	v_pk_mul_f32 v[34:35], v[2:3], v[34:35]
	v_pk_mul_f32 v[36:37], v[4:5], v[36:37]
	v_cvt_pk_bf16_f32 v34, v34, v35
	v_cvt_pk_bf16_f32 v35, v36, v37
	global_store_dwordx2 v[58:59], v[34:35], off offset:1536
	v_pk_mul_f32 v[30:31], v[30:31], v[0:1] op_sel_hi:[1,0]
	v_pk_mul_f32 v[32:33], v[32:33], v[0:1] op_sel_hi:[1,0]
	v_pk_mul_f32 v[26:27], v[26:27], v[0:1] op_sel_hi:[1,0]
	v_pk_mul_f32 v[28:29], v[28:29], v[0:1] op_sel_hi:[1,0]
	v_pk_mul_f32 v[22:23], v[22:23], v[0:1] op_sel_hi:[1,0]
	v_pk_mul_f32 v[24:25], v[24:25], v[0:1] op_sel_hi:[1,0]
	v_pk_mul_f32 v[18:19], v[18:19], v[0:1] op_sel_hi:[1,0]
	v_pk_mul_f32 v[20:21], v[20:21], v[0:1] op_sel_hi:[1,0]
	v_pk_mul_f32 v[46:47], v[14:15], v[46:47]
	v_pk_mul_f32 v[48:49], v[16:17], v[48:49]
	v_pk_mul_f32 v[42:43], v[10:11], v[42:43]
	v_pk_mul_f32 v[44:45], v[12:13], v[44:45]
	v_pk_mul_f32 v[38:39], v[6:7], v[38:39]
	v_pk_mul_f32 v[40:41], v[8:9], v[40:41]
	v_lshlrev_b64 v[34:35], 11, v[56:57]
	v_pk_mul_f32 v[30:31], v[14:15], v[30:31]
	v_pk_mul_f32 v[32:33], v[16:17], v[32:33]
	v_pk_mul_f32 v[26:27], v[10:11], v[26:27]
	v_pk_mul_f32 v[28:29], v[12:13], v[28:29]
	v_pk_mul_f32 v[22:23], v[6:7], v[22:23]
	v_pk_mul_f32 v[24:25], v[8:9], v[24:25]
	v_pk_mul_f32 v[18:19], v[2:3], v[18:19]
	v_pk_mul_f32 v[20:21], v[4:5], v[20:21]
	v_cmp_lt_i32_e32 vcc, s16, v50
	v_cvt_pk_bf16_f32 v46, v46, v47
	v_cvt_pk_bf16_f32 v47, v48, v49
	v_cvt_pk_bf16_f32 v42, v42, v43
	v_cvt_pk_bf16_f32 v43, v44, v45
	v_cvt_pk_bf16_f32 v38, v38, v39
	v_cvt_pk_bf16_f32 v39, v40, v41
	v_cvt_pk_bf16_f32 v30, v30, v31
	v_cvt_pk_bf16_f32 v31, v32, v33
	v_lshl_add_u64 v[32:33], v[54:55], 0, v[34:35]
	v_cvt_pk_bf16_f32 v26, v26, v27
	v_cvt_pk_bf16_f32 v27, v28, v29
	v_cvt_pk_bf16_f32 v22, v22, v23
	v_cvt_pk_bf16_f32 v23, v24, v25
	v_cvt_pk_bf16_f32 v18, v18, v19
	v_cvt_pk_bf16_f32 v19, v20, v21
	s_or_b64 s[12:13], vcc, s[12:13]
	global_store_dwordx2 v[58:59], v[46:47], off
	global_store_dwordx2 v[58:59], v[42:43], off offset:512
	global_store_dwordx2 v[58:59], v[38:39], off offset:1024
	global_store_dwordx2 v[32:33], v[30:31], off
	global_store_dwordx2 v[32:33], v[26:27], off offset:512
	global_store_dwordx2 v[32:33], v[22:23], off offset:1024
	global_store_dwordx2 v[32:33], v[18:19], off offset:1536
	s_andn2_b64 exec, exec, s[12:13]
	s_cbranch_execnz .LBB0_702
	s_getpc_b64 s[98:99]
